# v078: v077 + epilogue row reductions (xor16 + xor32 sums) via v_permlane16/32_swap instead of ds_swizzle/ds_bpermute round trips (37 sites, all k_inv epilogues)
# speedup vs baseline: 1.0069x; 1.0030x over previous
.LBB0_394:
	s_add_u32 s34, s20, s24
	s_addc_u32 s35, s21, s25
	s_add_u32 s36, s34, 0x100
	s_addc_u32 s37, s35, 0
	s_and_b64 s[30:31], s[28:29], exec
	s_cselect_b32 s39, s15, s37
	s_cselect_b32 s38, s14, s36
	s_add_u32 s24, s6, s24
	s_addc_u32 s25, s7, s25
	s_add_u32 s30, s24, 0x100
	s_addc_u32 s31, s25, 0
	s_add_u32 s24, s38, 0x80
	s_addc_u32 s25, s39, 0
	s_and_b64 s[28:29], s[28:29], exec
	s_cselect_b32 s41, s1, s31
	s_cselect_b32 s40, s13, s30
	s_add_u32 s42, s34, 0x12080
	s_addc_u32 s43, s35, 0
	s_add_i32 s78, s63, s49
	s_add_i32 m0, s50, 0xc000
	s_add_i32 s79, s50, 0xe000
	s_add_i32 s77, s78, 0x2000
	s_add_u32 s36, s40, 0x10000
	s_addc_u32 s37, s41, 0
	s_add_i32 s75, s64, s49
	s_add_i32 s73, s75, 0x2000
	s_add_i32 s72, 0, 0x18000
	s_add_u32 s34, s38, 0x12000
	ds_read_b128 v[146:149], v140
	ds_read_b128 v[150:153], v140 offset:1024
	ds_read_b128 v[154:157], v140 offset:2048
	ds_read_b128 v[158:161], v140 offset:3072
	s_addc_u32 s35, s39, 0
	s_add_i32 s70, 0, 0x1c000
	s_add_u32 s30, s40, 0x80
	s_addc_u32 s31, s41, 0
	s_add_i32 s71, s72, s49
	s_add_i32 s69, s71, 0x2000
	s_add_u32 s28, s40, 0x10080
	s_addc_u32 s29, s41, 0
	s_add_i32 s76, s70, s49
	s_add_i32 s74, s76, 0x2000
	ds_read_b128 v[162:165], v141
	ds_read_b128 v[166:169], v141 offset:1024
	ds_read_b128 v[170:173], v141 offset:2048
	ds_read_b128 v[174:177], v141 offset:3072
	ds_read_b128 v[178:181], v141 offset:4096
	ds_read_b128 v[182:185], v141 offset:5120
	ds_read_b128 v[186:189], v141 offset:6144
	ds_read_b128 v[190:193], v141 offset:7168
	s_nop 0
	global_load_lds_dwordx4 v130, s[42:43]
	s_mov_b32 m0, s79
	s_nop 0
	global_load_lds_dwordx4 v134, s[42:43]
	s_waitcnt lgkmcnt(8)
	s_barrier
	s_waitcnt lgkmcnt(0)
	s_setprio 1
	s_waitcnt lgkmcnt(0)
	v_mfma_f32_16x16x32_bf16 v[126:129], v[146:149], v[162:165], v[126:129]
	v_mfma_f32_16x16x32_bf16 v[122:125], v[154:157], v[162:165], v[122:125]
	v_mfma_f32_16x16x32_bf16 v[110:113], v[146:149], v[170:173], v[110:113]
	v_mfma_f32_16x16x32_bf16 v[106:109], v[154:157], v[170:173], v[106:109]
	v_mfma_f32_16x16x32_bf16 v[94:97], v[146:149], v[178:181], v[94:97]
	v_mfma_f32_16x16x32_bf16 v[90:93], v[154:157], v[178:181], v[90:93]
	v_mfma_f32_16x16x32_bf16 v[78:81], v[146:149], v[186:189], v[78:81]
	v_mfma_f32_16x16x32_bf16 v[74:77], v[154:157], v[186:189], v[74:77]
	v_mfma_f32_16x16x32_bf16 v[126:129], v[150:153], v[166:169], v[126:129]
	v_mfma_f32_16x16x32_bf16 v[122:125], v[158:161], v[166:169], v[122:125]
	v_mfma_f32_16x16x32_bf16 v[110:113], v[150:153], v[174:177], v[110:113]
	v_mfma_f32_16x16x32_bf16 v[106:109], v[158:161], v[174:177], v[106:109]
	v_mfma_f32_16x16x32_bf16 v[94:97], v[150:153], v[182:185], v[94:97]
	v_mfma_f32_16x16x32_bf16 v[90:93], v[158:161], v[182:185], v[90:93]
	v_mfma_f32_16x16x32_bf16 v[78:81], v[150:153], v[190:193], v[78:81]
	v_mfma_f32_16x16x32_bf16 v[74:77], v[158:161], v[190:193], v[74:77]
	s_setprio 0
	s_barrier
	s_mov_b32 m0, s78
	ds_read_b128 v[194:197], v142
	ds_read_b128 v[198:201], v142 offset:1024
	ds_read_b128 v[202:205], v142 offset:2048
	ds_read_b128 v[206:209], v142 offset:3072
	s_nop 0
	global_load_lds_dwordx4 v132, s[40:41]
	s_mov_b32 m0, s77
	s_nop 0
	global_load_lds_dwordx4 v136, s[40:41]
	s_barrier
	s_waitcnt lgkmcnt(0)
	s_setprio 1
	s_waitcnt lgkmcnt(0)
	v_mfma_f32_16x16x32_bf16 v[118:121], v[194:197], v[162:165], v[118:121]
	v_mfma_f32_16x16x32_bf16 v[114:117], v[202:205], v[162:165], v[114:117]
	v_mfma_f32_16x16x32_bf16 v[102:105], v[194:197], v[170:173], v[102:105]
	v_mfma_f32_16x16x32_bf16 v[98:101], v[202:205], v[170:173], v[98:101]
	v_mfma_f32_16x16x32_bf16 v[86:89], v[194:197], v[178:181], v[86:89]
	v_mfma_f32_16x16x32_bf16 v[82:85], v[202:205], v[178:181], v[82:85]
	v_mfma_f32_16x16x32_bf16 v[70:73], v[194:197], v[186:189], v[70:73]
	v_mfma_f32_16x16x32_bf16 v[66:69], v[202:205], v[186:189], v[66:69]
	v_mfma_f32_16x16x32_bf16 v[118:121], v[198:201], v[166:169], v[118:121]
	v_mfma_f32_16x16x32_bf16 v[114:117], v[206:209], v[166:169], v[114:117]
	v_mfma_f32_16x16x32_bf16 v[102:105], v[198:201], v[174:177], v[102:105]
	v_mfma_f32_16x16x32_bf16 v[98:101], v[206:209], v[174:177], v[98:101]
	v_mfma_f32_16x16x32_bf16 v[86:89], v[198:201], v[182:185], v[86:89]
	v_mfma_f32_16x16x32_bf16 v[82:85], v[206:209], v[182:185], v[82:85]
	v_mfma_f32_16x16x32_bf16 v[70:73], v[198:201], v[190:193], v[70:73]
	v_mfma_f32_16x16x32_bf16 v[66:69], v[206:209], v[190:193], v[66:69]
	s_setprio 0
	s_mov_b32 m0, s50
	s_barrier
	ds_read_b128 v[162:165], v141 offset:16384
	ds_read_b128 v[166:169], v141 offset:17408
	ds_read_b128 v[170:173], v141 offset:18432
	ds_read_b128 v[174:177], v141 offset:19456
	ds_read_b128 v[178:181], v141 offset:20480
	ds_read_b128 v[182:185], v141 offset:21504
	ds_read_b128 v[186:189], v141 offset:22528
	ds_read_b128 v[190:193], v141 offset:23552
	s_nop 0
	global_load_lds_dwordx4 v130, s[38:39]
	s_mov_b32 m0, s51
	s_nop 0
	global_load_lds_dwordx4 v134, s[38:39]
	s_barrier
	s_waitcnt lgkmcnt(0)
	s_setprio 1
	s_waitcnt lgkmcnt(0)
	v_mfma_f32_16x16x32_bf16 v[62:65], v[146:149], v[162:165], v[62:65]
	v_mfma_f32_16x16x32_bf16 v[58:61], v[154:157], v[162:165], v[58:61]
	v_mfma_f32_16x16x32_bf16 v[46:49], v[146:149], v[170:173], v[46:49]
	v_mfma_f32_16x16x32_bf16 v[42:45], v[154:157], v[170:173], v[42:45]
	v_mfma_f32_16x16x32_bf16 v[30:33], v[146:149], v[178:181], v[30:33]
	v_mfma_f32_16x16x32_bf16 v[26:29], v[154:157], v[178:181], v[26:29]
	v_mfma_f32_16x16x32_bf16 v[14:17], v[146:149], v[186:189], v[14:17]
	v_mfma_f32_16x16x32_bf16 v[10:13], v[154:157], v[186:189], v[10:13]
	v_mfma_f32_16x16x32_bf16 v[62:65], v[150:153], v[166:169], v[62:65]
	v_mfma_f32_16x16x32_bf16 v[58:61], v[158:161], v[166:169], v[58:61]
	v_mfma_f32_16x16x32_bf16 v[46:49], v[150:153], v[174:177], v[46:49]
	v_mfma_f32_16x16x32_bf16 v[42:45], v[158:161], v[174:177], v[42:45]
	v_mfma_f32_16x16x32_bf16 v[30:33], v[150:153], v[182:185], v[30:33]
	v_mfma_f32_16x16x32_bf16 v[26:29], v[158:161], v[182:185], v[26:29]
	v_mfma_f32_16x16x32_bf16 v[14:17], v[150:153], v[190:193], v[14:17]
	v_mfma_f32_16x16x32_bf16 v[10:13], v[158:161], v[190:193], v[10:13]
	s_setprio 0
	s_barrier
	s_mov_b32 m0, s75
	s_nop 0
	global_load_lds_dwordx4 v132, s[36:37]
	s_mov_b32 m0, s73
	s_nop 0
	global_load_lds_dwordx4 v136, s[36:37]
	s_waitcnt vmcnt(6)
	s_barrier
	s_setprio 1
	v_mfma_f32_16x16x32_bf16 v[54:57], v[194:197], v[162:165], v[54:57]
	v_mfma_f32_16x16x32_bf16 v[50:53], v[202:205], v[162:165], v[50:53]
	v_mfma_f32_16x16x32_bf16 v[38:41], v[194:197], v[170:173], v[38:41]
	v_mfma_f32_16x16x32_bf16 v[34:37], v[202:205], v[170:173], v[34:37]
	v_mfma_f32_16x16x32_bf16 v[22:25], v[194:197], v[178:181], v[22:25]
	v_mfma_f32_16x16x32_bf16 v[18:21], v[202:205], v[178:181], v[18:21]
	v_mfma_f32_16x16x32_bf16 v[6:9], v[194:197], v[186:189], v[6:9]
	v_mfma_f32_16x16x32_bf16 v[2:5], v[202:205], v[186:189], v[2:5]
	v_mfma_f32_16x16x32_bf16 v[54:57], v[198:201], v[166:169], v[54:57]
	v_mfma_f32_16x16x32_bf16 v[50:53], v[206:209], v[166:169], v[50:53]
	v_mfma_f32_16x16x32_bf16 v[38:41], v[198:201], v[174:177], v[38:41]
	v_mfma_f32_16x16x32_bf16 v[34:37], v[206:209], v[174:177], v[34:37]
	v_mfma_f32_16x16x32_bf16 v[22:25], v[198:201], v[182:185], v[22:25]
	v_mfma_f32_16x16x32_bf16 v[18:21], v[206:209], v[182:185], v[18:21]
	v_mfma_f32_16x16x32_bf16 v[6:9], v[198:201], v[190:193], v[6:9]
	v_mfma_f32_16x16x32_bf16 v[2:5], v[206:209], v[190:193], v[2:5]
	s_setprio 0
	v_add_u32_e32 v138, s72, v1
	s_barrier
	ds_read_b128 v[146:149], v138
	ds_read_b128 v[150:153], v138 offset:1024
	ds_read_b128 v[154:157], v138 offset:2048
	ds_read_b128 v[158:161], v138 offset:3072
	s_mov_b32 m0, s52
	ds_read_b128 v[162:165], v141 offset:32768
	ds_read_b128 v[166:169], v141 offset:33792
	ds_read_b128 v[170:173], v141 offset:34816
	ds_read_b128 v[174:177], v141 offset:35840
	ds_read_b128 v[178:181], v141 offset:36864
	ds_read_b128 v[182:185], v141 offset:37888
	ds_read_b128 v[186:189], v141 offset:38912
	ds_read_b128 v[190:193], v141 offset:39936
	s_nop 0
	global_load_lds_dwordx4 v130, s[34:35]
	s_mov_b32 m0, s53
	s_nop 0
	global_load_lds_dwordx4 v134, s[34:35]
	s_waitcnt lgkmcnt(8)
	s_barrier
	s_waitcnt lgkmcnt(0)
	s_setprio 1
	s_waitcnt lgkmcnt(0)
	v_mfma_f32_16x16x32_bf16 v[126:129], v[146:149], v[162:165], v[126:129]
	v_mfma_f32_16x16x32_bf16 v[122:125], v[154:157], v[162:165], v[122:125]
	v_mfma_f32_16x16x32_bf16 v[110:113], v[146:149], v[170:173], v[110:113]
	v_mfma_f32_16x16x32_bf16 v[106:109], v[154:157], v[170:173], v[106:109]
	v_mfma_f32_16x16x32_bf16 v[94:97], v[146:149], v[178:181], v[94:97]
	v_mfma_f32_16x16x32_bf16 v[90:93], v[154:157], v[178:181], v[90:93]
	v_mfma_f32_16x16x32_bf16 v[78:81], v[146:149], v[186:189], v[78:81]
	v_mfma_f32_16x16x32_bf16 v[74:77], v[154:157], v[186:189], v[74:77]
	v_mfma_f32_16x16x32_bf16 v[126:129], v[150:153], v[166:169], v[126:129]
	v_mfma_f32_16x16x32_bf16 v[122:125], v[158:161], v[166:169], v[122:125]
	v_mfma_f32_16x16x32_bf16 v[110:113], v[150:153], v[174:177], v[110:113]
	v_mfma_f32_16x16x32_bf16 v[106:109], v[158:161], v[174:177], v[106:109]
	v_mfma_f32_16x16x32_bf16 v[94:97], v[150:153], v[182:185], v[94:97]
	v_mfma_f32_16x16x32_bf16 v[90:93], v[158:161], v[182:185], v[90:93]
	v_mfma_f32_16x16x32_bf16 v[78:81], v[150:153], v[190:193], v[78:81]
	v_mfma_f32_16x16x32_bf16 v[74:77], v[158:161], v[190:193], v[74:77]
	s_setprio 0
	s_barrier
	v_add_u32_e32 v138, s70, v1
	s_mov_b32 m0, s71
	ds_read_b128 v[194:197], v138
	ds_read_b128 v[198:201], v138 offset:1024
	ds_read_b128 v[202:205], v138 offset:2048
	ds_read_b128 v[206:209], v138 offset:3072
	s_nop 0
	global_load_lds_dwordx4 v132, s[30:31]
	s_mov_b32 m0, s69
	s_nop 0
	global_load_lds_dwordx4 v136, s[30:31]
	s_barrier
	s_waitcnt lgkmcnt(0)
	s_setprio 1
	s_waitcnt lgkmcnt(0)
	v_mfma_f32_16x16x32_bf16 v[118:121], v[194:197], v[162:165], v[118:121]
	v_mfma_f32_16x16x32_bf16 v[114:117], v[202:205], v[162:165], v[114:117]
	v_mfma_f32_16x16x32_bf16 v[102:105], v[194:197], v[170:173], v[102:105]
	v_mfma_f32_16x16x32_bf16 v[98:101], v[202:205], v[170:173], v[98:101]
	v_mfma_f32_16x16x32_bf16 v[86:89], v[194:197], v[178:181], v[86:89]
	v_mfma_f32_16x16x32_bf16 v[82:85], v[202:205], v[178:181], v[82:85]
	v_mfma_f32_16x16x32_bf16 v[70:73], v[194:197], v[186:189], v[70:73]
	v_mfma_f32_16x16x32_bf16 v[66:69], v[202:205], v[186:189], v[66:69]
	v_mfma_f32_16x16x32_bf16 v[118:121], v[198:201], v[166:169], v[118:121]
	v_mfma_f32_16x16x32_bf16 v[114:117], v[206:209], v[166:169], v[114:117]
	v_mfma_f32_16x16x32_bf16 v[102:105], v[198:201], v[174:177], v[102:105]
	v_mfma_f32_16x16x32_bf16 v[98:101], v[206:209], v[174:177], v[98:101]
	v_mfma_f32_16x16x32_bf16 v[86:89], v[198:201], v[182:185], v[86:89]
	v_mfma_f32_16x16x32_bf16 v[82:85], v[206:209], v[182:185], v[82:85]
	v_mfma_f32_16x16x32_bf16 v[70:73], v[198:201], v[190:193], v[70:73]
	v_mfma_f32_16x16x32_bf16 v[66:69], v[206:209], v[190:193], v[66:69]
	s_setprio 0
	s_mov_b32 m0, s58
	s_barrier
	ds_read_b128 v[162:165], v141 offset:49152
	ds_read_b128 v[166:169], v141 offset:50176
	ds_read_b128 v[170:173], v141 offset:51200
	ds_read_b128 v[174:177], v141 offset:52224
	ds_read_b128 v[178:181], v141 offset:53248
	ds_read_b128 v[182:185], v141 offset:54272
	ds_read_b128 v[186:189], v141 offset:55296
	ds_read_b128 v[190:193], v141 offset:56320
	s_nop 0
	global_load_lds_dwordx4 v130, s[24:25]
	s_mov_b32 m0, s59
	s_nop 0
	global_load_lds_dwordx4 v134, s[24:25]
	s_barrier
	s_waitcnt lgkmcnt(0)
	s_setprio 1
	s_waitcnt lgkmcnt(0)
	v_mfma_f32_16x16x32_bf16 v[62:65], v[146:149], v[162:165], v[62:65]
	v_mfma_f32_16x16x32_bf16 v[58:61], v[154:157], v[162:165], v[58:61]
	v_mfma_f32_16x16x32_bf16 v[46:49], v[146:149], v[170:173], v[46:49]
	v_mfma_f32_16x16x32_bf16 v[42:45], v[154:157], v[170:173], v[42:45]
	v_mfma_f32_16x16x32_bf16 v[30:33], v[146:149], v[178:181], v[30:33]
	v_mfma_f32_16x16x32_bf16 v[26:29], v[154:157], v[178:181], v[26:29]
	v_mfma_f32_16x16x32_bf16 v[14:17], v[146:149], v[186:189], v[14:17]
	v_mfma_f32_16x16x32_bf16 v[10:13], v[154:157], v[186:189], v[10:13]
	v_mfma_f32_16x16x32_bf16 v[62:65], v[150:153], v[166:169], v[62:65]
	v_mfma_f32_16x16x32_bf16 v[58:61], v[158:161], v[166:169], v[58:61]
	v_mfma_f32_16x16x32_bf16 v[46:49], v[150:153], v[174:177], v[46:49]
	v_mfma_f32_16x16x32_bf16 v[42:45], v[158:161], v[174:177], v[42:45]
	v_mfma_f32_16x16x32_bf16 v[30:33], v[150:153], v[182:185], v[30:33]
	v_mfma_f32_16x16x32_bf16 v[26:29], v[158:161], v[182:185], v[26:29]
	v_mfma_f32_16x16x32_bf16 v[14:17], v[150:153], v[190:193], v[14:17]
	v_mfma_f32_16x16x32_bf16 v[10:13], v[158:161], v[190:193], v[10:13]
	s_setprio 0
	s_barrier
	s_mov_b32 m0, s76
	s_nop 0
	global_load_lds_dwordx4 v132, s[28:29]
	s_mov_b32 m0, s74
	s_nop 0
	global_load_lds_dwordx4 v136, s[28:29]
	s_waitcnt vmcnt(6)
	s_barrier
	s_setprio 1
	v_mfma_f32_16x16x32_bf16 v[54:57], v[194:197], v[162:165], v[54:57]
	v_mfma_f32_16x16x32_bf16 v[50:53], v[202:205], v[162:165], v[50:53]
	v_mfma_f32_16x16x32_bf16 v[38:41], v[194:197], v[170:173], v[38:41]
	v_mfma_f32_16x16x32_bf16 v[34:37], v[202:205], v[170:173], v[34:37]
	v_mfma_f32_16x16x32_bf16 v[22:25], v[194:197], v[178:181], v[22:25]
	v_mfma_f32_16x16x32_bf16 v[18:21], v[202:205], v[178:181], v[18:21]
	v_mfma_f32_16x16x32_bf16 v[6:9], v[194:197], v[186:189], v[6:9]
	v_mfma_f32_16x16x32_bf16 v[2:5], v[202:205], v[186:189], v[2:5]
	v_mfma_f32_16x16x32_bf16 v[54:57], v[198:201], v[166:169], v[54:57]
	v_mfma_f32_16x16x32_bf16 v[50:53], v[206:209], v[166:169], v[50:53]
	v_mfma_f32_16x16x32_bf16 v[38:41], v[198:201], v[174:177], v[38:41]
	v_mfma_f32_16x16x32_bf16 v[34:37], v[206:209], v[174:177], v[34:37]
	v_mfma_f32_16x16x32_bf16 v[22:25], v[198:201], v[182:185], v[22:25]
	v_mfma_f32_16x16x32_bf16 v[18:21], v[206:209], v[182:185], v[18:21]
	v_mfma_f32_16x16x32_bf16 v[6:9], v[198:201], v[190:193], v[6:9]
	v_mfma_f32_16x16x32_bf16 v[2:5], v[206:209], v[190:193], v[2:5]
	s_setprio 0
	s_andn2_b64 vcc, exec, s[22:23]
	s_mov_b64 s[28:29], -1
	s_mov_b64 s[22:23], 0
	s_mov_b64 s[24:25], 0x100
	s_barrier
	s_cbranch_vccz .LBB0_394
	v_mov_b32_e32 v154, v0
	s_ashr_i32 s1, s0, 31
	v_readfirstlane_b32 s6, v154
	s_bfe_u32 s13, s6, 0x20006
	s_ashr_i32 s6, s6, 2
	s_andn2_b32 s6, s6, 63
	s_ashr_i32 s7, s6, 31
	s_lshl_b64 s[20:21], s[0:1], 10
	s_add_u32 s22, s54, s20
	s_addc_u32 s23, s55, s21
	s_lshl_b64 s[20:21], s[6:7], 2
	v_and_b32_e32 v145, 15, v154
	s_add_u32 s20, s22, s20
	s_addc_u32 s21, s23, s21
	v_lshlrev_b32_e32 v138, 2, v145
	global_load_dword v153, v138, s[20:21] offset:64
	global_load_dword v152, v138, s[20:21] offset:128
	global_load_dword v151, v138, s[20:21] offset:192
	global_load_dword v150, v138, s[20:21] offset:512
	global_load_dword v149, v138, s[20:21] offset:576
	global_load_dword v148, v138, s[20:21] offset:640
	global_load_dword v147, v138, s[20:21] offset:704
	v_mul_f32_e32 v127, v127, v127
	v_mul_f32_e32 v123, v123, v123
	v_mul_f32_e32 v119, v119, v119
	v_mul_f32_e32 v115, v115, v115
	v_fmac_f32_e32 v127, v126, v126
	v_mul_f32_e32 v126, v129, v129
	v_fmac_f32_e32 v123, v122, v122
	v_mul_f32_e32 v122, v125, v125
	v_fmac_f32_e32 v119, v118, v118
	v_mul_f32_e32 v118, v121, v121
	v_fmac_f32_e32 v115, v114, v114
	v_mul_f32_e32 v114, v117, v117
	v_fmac_f32_e32 v126, v128, v128
	v_fmac_f32_e32 v122, v124, v124
	v_fmac_f32_e32 v118, v120, v120
	v_fmac_f32_e32 v114, v116, v116
	v_add_f32_e32 v126, v127, v126
	v_add_f32_e32 v122, v123, v122
	v_add_f32_e32 v118, v119, v118
	v_add_f32_e32 v114, v115, v114
	v_add_f32_e32 v122, v126, v122
	v_add_f32_e32 v114, v118, v114
	v_add_f32_e32 v115, v122, v114
	v_mov_b32_e32 v116, v115
	s_nop 1
	v_permlane16_swap_b32 v116, v115
	v_and_b32_e32 v156, 64, v143
	v_xor_b32_e32 v155, 32, v143
	v_add_u32_e32 v156, 64, v156
	v_cmp_lt_i32_e32 vcc, v155, v156
	s_lshl_b32 s22, s68, 2
	s_or_b32 s22, s13, s22
	v_cndmask_b32_e32 v114, v143, v155, vcc
	s_lshl_b64 s[0:1], s[0:1], 8
	v_lshlrev_b32_e32 v114, 2, v114
	s_waitcnt lgkmcnt(0)
	v_add_f32_e32 v115, v115, v116
	s_add_u32 s0, s0, s6
	v_mov_b32_e32 v116, v115
	s_nop 1
	v_permlane32_swap_b32 v116, v115
	s_addc_u32 s1, s1, s7
	s_ashr_i32 s23, s22, 31
	v_or_b32_e32 v146, s0, v145
	v_mov_b32_e32 v145, s1
	s_lshl_b64 s[0:1], s[22:23], 2
	v_and_b32_e32 v117, 48, v154
	s_add_u32 s0, s56, s0
	v_cmp_eq_u32_e64 s[6:7], 0, v117
	s_addc_u32 s1, s57, s1
	s_and_saveexec_b64 s[22:23], s[6:7]
	s_cbranch_execz .LBB0_397
	v_lshl_add_u64 v[118:119], s[20:21], 0, v[138:139]
	global_load_dword v118, v[118:119], off
	s_waitcnt lgkmcnt(0)
	v_add_f32_e32 v115, v115, v116
	v_mad_u64_u32 v[116:117], s[20:21], v146, 48, s[0:1]
	s_waitcnt vmcnt(0)
	v_add_f32_e32 v115, v115, v118
	v_fmamk_f32 v115, v115, 0x3c2aaaab, v144
	v_mul_f32_e32 v118, 0x4b800000, v115
	v_cmp_gt_f32_e32 vcc, s65, v115
	s_nop 1
	v_cndmask_b32_e32 v115, v115, v118, vcc
	v_rsq_f32_e32 v115, v115
	v_mov_b32_e32 v118, v117
	v_mad_u64_u32 v[118:119], s[20:21], v145, 48, v[118:119]
	v_mul_f32_e32 v117, 0x45800000, v115
	v_cndmask_b32_e32 v115, v115, v117, vcc
	v_mov_b32_e32 v117, v118
	global_store_dword v[116:117], v115, off
.LBB0_397:
	s_or_b64 exec, exec, s[22:23]
	v_mul_f32_e32 v111, v111, v111
	v_mul_f32_e32 v107, v107, v107
	v_mul_f32_e32 v103, v103, v103
	v_mul_f32_e32 v99, v99, v99
	v_fmac_f32_e32 v111, v110, v110
	v_mul_f32_e32 v110, v113, v113
	v_fmac_f32_e32 v107, v106, v106
	v_mul_f32_e32 v106, v109, v109
	v_fmac_f32_e32 v103, v102, v102
	v_mul_f32_e32 v102, v105, v105
	v_fmac_f32_e32 v99, v98, v98
	v_mul_f32_e32 v98, v101, v101
	v_fmac_f32_e32 v110, v112, v112
	v_fmac_f32_e32 v106, v108, v108
	v_fmac_f32_e32 v102, v104, v104
	v_fmac_f32_e32 v98, v100, v100
	v_add_f32_e32 v110, v111, v110
	v_add_f32_e32 v106, v107, v106
	v_add_f32_e32 v102, v103, v102
	v_add_f32_e32 v98, v99, v98
	v_add_f32_e32 v106, v110, v106
	v_add_f32_e32 v98, v102, v98
	v_add_f32_e32 v98, v106, v98
	v_mov_b32_e32 v99, v98
	s_nop 1
	v_permlane16_swap_b32 v99, v98
	s_waitcnt lgkmcnt(0)
	v_add_f32_e32 v98, v98, v99
	v_mov_b32_e32 v99, v98
	s_nop 1
	v_permlane32_swap_b32 v99, v98
	s_and_saveexec_b64 s[20:21], s[6:7]
	s_cbranch_execz .LBB0_399
	s_waitcnt lgkmcnt(0)
	v_add_f32_e32 v98, v98, v99
	s_waitcnt vmcnt(0)
	v_add_f32_e32 v98, v153, v98
	v_fmamk_f32 v98, v98, 0x3c2aaaab, v144
	v_mul_f32_e32 v99, 0x4b800000, v98
	v_cmp_gt_f32_e32 vcc, s65, v98
	s_nop 1
	v_cndmask_b32_e32 v98, v98, v99, vcc
	v_rsq_f32_e32 v100, v98
	v_mad_u64_u32 v[98:99], s[22:23], v146, 48, s[0:1]
	v_mul_f32_e32 v101, 0x45800000, v100
	v_cndmask_b32_e32 v102, v100, v101, vcc
	v_mov_b32_e32 v100, v99
	v_mad_u64_u32 v[100:101], s[22:23], v145, 48, v[100:101]
	v_mov_b32_e32 v99, v100
	global_store_dword v[98:99], v102, off offset:768
.LBB0_399:
	s_or_b64 exec, exec, s[20:21]
	v_mul_f32_e32 v95, v95, v95
	v_mul_f32_e32 v91, v91, v91
	v_mul_f32_e32 v87, v87, v87
	v_mul_f32_e32 v83, v83, v83
	v_fmac_f32_e32 v95, v94, v94
	v_mul_f32_e32 v94, v97, v97
	v_fmac_f32_e32 v91, v90, v90
	v_mul_f32_e32 v90, v93, v93
	v_fmac_f32_e32 v87, v86, v86
	v_mul_f32_e32 v86, v89, v89
	v_fmac_f32_e32 v83, v82, v82
	v_mul_f32_e32 v82, v85, v85
	v_fmac_f32_e32 v94, v96, v96
	v_fmac_f32_e32 v90, v92, v92
	v_fmac_f32_e32 v86, v88, v88
	v_fmac_f32_e32 v82, v84, v84
	v_add_f32_e32 v94, v95, v94
	v_add_f32_e32 v90, v91, v90
	v_add_f32_e32 v86, v87, v86
	v_add_f32_e32 v82, v83, v82
	v_add_f32_e32 v90, v94, v90
	v_add_f32_e32 v82, v86, v82
	v_add_f32_e32 v82, v90, v82
	v_mov_b32_e32 v83, v82
	s_nop 1
	v_permlane16_swap_b32 v83, v82
	s_waitcnt lgkmcnt(0)
	v_add_f32_e32 v82, v82, v83
	v_mov_b32_e32 v83, v82
	s_nop 1
	v_permlane32_swap_b32 v83, v82
	s_and_saveexec_b64 s[20:21], s[6:7]
	s_cbranch_execz .LBB0_401
	s_waitcnt lgkmcnt(0)
	v_add_f32_e32 v82, v82, v83
	s_waitcnt vmcnt(0)
	v_add_f32_e32 v82, v152, v82
	v_fmamk_f32 v82, v82, 0x3c2aaaab, v144
	v_mul_f32_e32 v83, 0x4b800000, v82
	v_cmp_gt_f32_e32 vcc, s65, v82
	s_nop 1
	v_cndmask_b32_e32 v82, v82, v83, vcc
	v_rsq_f32_e32 v84, v82
	v_mad_u64_u32 v[82:83], s[22:23], v146, 48, s[0:1]
	v_mul_f32_e32 v85, 0x45800000, v84
	v_cndmask_b32_e32 v86, v84, v85, vcc
	v_mov_b32_e32 v84, v83
	v_mad_u64_u32 v[84:85], s[22:23], v145, 48, v[84:85]
	v_mov_b32_e32 v83, v84
	global_store_dword v[82:83], v86, off offset:1536
.LBB0_401:
	s_or_b64 exec, exec, s[20:21]
	v_mul_f32_e32 v79, v79, v79
	v_mul_f32_e32 v75, v75, v75
	v_mul_f32_e32 v71, v71, v71
	v_mul_f32_e32 v67, v67, v67
	v_fmac_f32_e32 v79, v78, v78
	v_mul_f32_e32 v78, v81, v81
	v_fmac_f32_e32 v75, v74, v74
	v_mul_f32_e32 v74, v77, v77
	v_fmac_f32_e32 v71, v70, v70
	v_mul_f32_e32 v70, v73, v73
	v_fmac_f32_e32 v67, v66, v66
	v_mul_f32_e32 v66, v69, v69
	v_fmac_f32_e32 v78, v80, v80
	v_fmac_f32_e32 v74, v76, v76
	v_fmac_f32_e32 v70, v72, v72
	v_fmac_f32_e32 v66, v68, v68
	v_add_f32_e32 v78, v79, v78
	v_add_f32_e32 v74, v75, v74
	v_add_f32_e32 v70, v71, v70
	v_add_f32_e32 v66, v67, v66
	v_add_f32_e32 v74, v78, v74
	v_add_f32_e32 v66, v70, v66
	v_add_f32_e32 v66, v74, v66
	v_mov_b32_e32 v67, v66
	s_nop 1
	v_permlane16_swap_b32 v67, v66
	s_waitcnt lgkmcnt(0)
	v_add_f32_e32 v66, v66, v67
	v_mov_b32_e32 v67, v66
	s_nop 1
	v_permlane32_swap_b32 v67, v66
	s_and_saveexec_b64 s[20:21], s[6:7]
	s_cbranch_execz .LBB0_403
	s_waitcnt lgkmcnt(0)
	v_add_f32_e32 v66, v66, v67
	s_waitcnt vmcnt(0)
	v_add_f32_e32 v66, v151, v66
	v_fmamk_f32 v66, v66, 0x3c2aaaab, v144
	v_mul_f32_e32 v67, 0x4b800000, v66
	v_cmp_gt_f32_e32 vcc, s65, v66
	s_nop 1
	v_cndmask_b32_e32 v66, v66, v67, vcc
	v_rsq_f32_e32 v68, v66
	v_mad_u64_u32 v[66:67], s[22:23], v146, 48, s[0:1]
	v_mul_f32_e32 v69, 0x45800000, v68
	v_cndmask_b32_e32 v70, v68, v69, vcc
	v_mov_b32_e32 v68, v67
	v_mad_u64_u32 v[68:69], s[22:23], v145, 48, v[68:69]
	v_mov_b32_e32 v67, v68
	global_store_dword v[66:67], v70, off offset:2304
.LBB0_403:
	s_or_b64 exec, exec, s[20:21]
	v_mul_f32_e32 v63, v63, v63
	v_mul_f32_e32 v59, v59, v59
	v_mul_f32_e32 v55, v55, v55
	v_mul_f32_e32 v51, v51, v51
	v_fmac_f32_e32 v63, v62, v62
	v_mul_f32_e32 v62, v65, v65
	v_fmac_f32_e32 v59, v58, v58
	v_mul_f32_e32 v58, v61, v61
	v_fmac_f32_e32 v55, v54, v54
	v_mul_f32_e32 v54, v57, v57
	v_fmac_f32_e32 v51, v50, v50
	v_mul_f32_e32 v50, v53, v53
	v_fmac_f32_e32 v62, v64, v64
	v_fmac_f32_e32 v58, v60, v60
	v_fmac_f32_e32 v54, v56, v56
	v_fmac_f32_e32 v50, v52, v52
	v_add_f32_e32 v62, v63, v62
	v_add_f32_e32 v58, v59, v58
	v_add_f32_e32 v54, v55, v54
	v_add_f32_e32 v50, v51, v50
	v_add_f32_e32 v58, v62, v58
	v_add_f32_e32 v50, v54, v50
	v_add_f32_e32 v50, v58, v50
	v_mov_b32_e32 v51, v50
	s_nop 1
	v_permlane16_swap_b32 v51, v50
	s_waitcnt lgkmcnt(0)
	v_add_f32_e32 v50, v50, v51
	v_mov_b32_e32 v51, v50
	s_nop 1
	v_permlane32_swap_b32 v51, v50
	s_and_saveexec_b64 s[20:21], s[6:7]
	s_cbranch_execz .LBB0_405
	s_waitcnt lgkmcnt(0)
	v_add_f32_e32 v50, v50, v51
	s_waitcnt vmcnt(0)
	v_add_f32_e32 v50, v150, v50
	v_fmamk_f32 v50, v50, 0x3c2aaaab, v144
	v_mul_f32_e32 v51, 0x4b800000, v50
	v_cmp_gt_f32_e32 vcc, s65, v50
	s_nop 1
	v_cndmask_b32_e32 v50, v50, v51, vcc
	v_rsq_f32_e32 v52, v50
	v_mad_u64_u32 v[50:51], s[22:23], v146, 48, s[0:1]
	v_mul_f32_e32 v53, 0x45800000, v52
	v_cndmask_b32_e32 v54, v52, v53, vcc
	v_mov_b32_e32 v52, v51
	v_mad_u64_u32 v[52:53], s[22:23], v145, 48, v[52:53]
	v_add_co_u32_e32 v50, vcc, 0x1000, v50
	s_nop 1
	v_addc_co_u32_e32 v51, vcc, 0, v52, vcc
	global_store_dword v[50:51], v54, off offset:2048
.LBB0_405:
	s_or_b64 exec, exec, s[20:21]
	v_mul_f32_e32 v47, v47, v47
	v_mul_f32_e32 v43, v43, v43
	v_mul_f32_e32 v39, v39, v39
	v_mul_f32_e32 v35, v35, v35
	v_fmac_f32_e32 v47, v46, v46
	v_mul_f32_e32 v46, v49, v49
	v_fmac_f32_e32 v43, v42, v42
	v_mul_f32_e32 v42, v45, v45
	v_fmac_f32_e32 v39, v38, v38
	v_mul_f32_e32 v38, v41, v41
	v_fmac_f32_e32 v35, v34, v34
	v_mul_f32_e32 v34, v37, v37
	v_fmac_f32_e32 v46, v48, v48
	v_fmac_f32_e32 v42, v44, v44
	v_fmac_f32_e32 v38, v40, v40
	v_fmac_f32_e32 v34, v36, v36
	v_add_f32_e32 v46, v47, v46
	v_add_f32_e32 v42, v43, v42
	v_add_f32_e32 v38, v39, v38
	v_add_f32_e32 v34, v35, v34
	v_add_f32_e32 v42, v46, v42
	v_add_f32_e32 v34, v38, v34
	v_add_f32_e32 v34, v42, v34
	v_mov_b32_e32 v35, v34
	s_nop 1
	v_permlane16_swap_b32 v35, v34
	s_waitcnt lgkmcnt(0)
	v_add_f32_e32 v34, v34, v35
	v_mov_b32_e32 v35, v34
	s_nop 1
	v_permlane32_swap_b32 v35, v34
	s_and_saveexec_b64 s[20:21], s[6:7]
	s_cbranch_execz .LBB0_407
	s_waitcnt lgkmcnt(0)
	v_add_f32_e32 v34, v34, v35
	s_waitcnt vmcnt(0)
	v_add_f32_e32 v34, v149, v34
	v_fmamk_f32 v34, v34, 0x3c2aaaab, v144
	v_mul_f32_e32 v35, 0x4b800000, v34
	v_cmp_gt_f32_e32 vcc, s65, v34
	s_nop 1
	v_cndmask_b32_e32 v34, v34, v35, vcc
	v_rsq_f32_e32 v36, v34
	v_mad_u64_u32 v[34:35], s[22:23], v146, 48, s[0:1]
	v_mul_f32_e32 v37, 0x45800000, v36
	v_cndmask_b32_e32 v38, v36, v37, vcc
	v_mov_b32_e32 v36, v35
	v_mad_u64_u32 v[36:37], s[22:23], v145, 48, v[36:37]
	v_add_co_u32_e32 v34, vcc, 0x1000, v34
	s_nop 1
	v_addc_co_u32_e32 v35, vcc, 0, v36, vcc
	global_store_dword v[34:35], v38, off offset:2816
.LBB0_407:
	s_or_b64 exec, exec, s[20:21]
	v_mul_f32_e32 v31, v31, v31
	v_mul_f32_e32 v27, v27, v27
	v_mul_f32_e32 v23, v23, v23
	v_mul_f32_e32 v19, v19, v19
	v_fmac_f32_e32 v31, v30, v30
	v_mul_f32_e32 v30, v33, v33
	v_fmac_f32_e32 v27, v26, v26
	v_mul_f32_e32 v26, v29, v29
	v_fmac_f32_e32 v23, v22, v22
	v_mul_f32_e32 v22, v25, v25
	v_fmac_f32_e32 v19, v18, v18
	v_mul_f32_e32 v18, v21, v21
	v_fmac_f32_e32 v30, v32, v32
	v_fmac_f32_e32 v26, v28, v28
	v_fmac_f32_e32 v22, v24, v24
	v_fmac_f32_e32 v18, v20, v20
	v_add_f32_e32 v30, v31, v30
	v_add_f32_e32 v26, v27, v26
	v_add_f32_e32 v22, v23, v22
	v_add_f32_e32 v18, v19, v18
	v_add_f32_e32 v26, v30, v26
	v_add_f32_e32 v18, v22, v18
	v_add_f32_e32 v18, v26, v18
	v_mov_b32_e32 v19, v18
	s_nop 1
	v_permlane16_swap_b32 v19, v18
	s_waitcnt lgkmcnt(0)
	v_add_f32_e32 v18, v18, v19
	v_mov_b32_e32 v19, v18
	s_nop 1
	v_permlane32_swap_b32 v19, v18
	s_and_saveexec_b64 s[20:21], s[6:7]
	s_cbranch_execz .LBB0_409
	s_waitcnt lgkmcnt(0)
	v_add_f32_e32 v18, v18, v19
	s_waitcnt vmcnt(0)
	v_add_f32_e32 v18, v148, v18
	v_fmamk_f32 v18, v18, 0x3c2aaaab, v144
	v_mul_f32_e32 v19, 0x4b800000, v18
	v_cmp_gt_f32_e32 vcc, s65, v18
	s_nop 1
	v_cndmask_b32_e32 v18, v18, v19, vcc
	v_rsq_f32_e32 v20, v18
	v_mad_u64_u32 v[18:19], s[22:23], v146, 48, s[0:1]
	v_mul_f32_e32 v21, 0x45800000, v20
	v_cndmask_b32_e32 v22, v20, v21, vcc
	v_mov_b32_e32 v20, v19
	v_mad_u64_u32 v[20:21], s[22:23], v145, 48, v[20:21]
	v_add_co_u32_e32 v18, vcc, 0x1000, v18
	s_nop 1
	v_addc_co_u32_e32 v19, vcc, 0, v20, vcc
	global_store_dword v[18:19], v22, off offset:3584
.LBB0_409:
	s_or_b64 exec, exec, s[20:21]
	v_mul_f32_e32 v15, v15, v15
	v_mul_f32_e32 v11, v11, v11
	v_mul_f32_e32 v7, v7, v7
	v_mul_f32_e32 v3, v3, v3
	v_fmac_f32_e32 v15, v14, v14
	v_mul_f32_e32 v14, v17, v17
	v_fmac_f32_e32 v11, v10, v10
	v_mul_f32_e32 v10, v13, v13
	v_fmac_f32_e32 v7, v6, v6
	v_mul_f32_e32 v6, v9, v9
	v_fmac_f32_e32 v3, v2, v2
	v_mul_f32_e32 v2, v5, v5
	v_fmac_f32_e32 v14, v16, v16
	v_fmac_f32_e32 v10, v12, v12
	v_fmac_f32_e32 v6, v8, v8
	v_fmac_f32_e32 v2, v4, v4
	v_add_f32_e32 v14, v15, v14
	v_add_f32_e32 v10, v11, v10
	v_add_f32_e32 v6, v7, v6
	v_add_f32_e32 v2, v3, v2
	v_add_f32_e32 v10, v14, v10
	v_add_f32_e32 v2, v6, v2
	v_add_f32_e32 v2, v10, v2
	v_mov_b32_e32 v3, v2
	s_nop 1
	v_permlane16_swap_b32 v3, v2
	s_waitcnt lgkmcnt(0)
	v_add_f32_e32 v2, v2, v3
	v_mov_b32_e32 v3, v2
	s_nop 1
	v_permlane32_swap_b32 v3, v2
	s_and_saveexec_b64 s[20:21], s[6:7]
	s_cbranch_execz .LBB0_385
	s_waitcnt lgkmcnt(0)
	v_add_f32_e32 v2, v2, v3
	s_waitcnt vmcnt(0)
	v_add_f32_e32 v2, v147, v2
	v_fmamk_f32 v2, v2, 0x3c2aaaab, v144
	v_mul_f32_e32 v3, 0x4b800000, v2
	v_cmp_gt_f32_e32 vcc, s65, v2
	s_nop 1
	v_cndmask_b32_e32 v2, v2, v3, vcc
	v_rsq_f32_e32 v4, v2
	v_mad_u64_u32 v[2:3], s[0:1], v146, 48, s[0:1]
	v_mul_f32_e32 v5, 0x45800000, v4
	v_cndmask_b32_e32 v6, v4, v5, vcc
	v_mov_b32_e32 v4, v3
	v_mad_u64_u32 v[4:5], s[0:1], v145, 48, v[4:5]
	v_add_co_u32_e32 v2, vcc, 0x2000, v2
	s_nop 1
	v_addc_co_u32_e32 v3, vcc, 0, v4, vcc
	global_store_dword v[2:3], v6, off offset:256
	s_branch .LBB0_385

.LBB0_654:
	s_add_u32 s36, s14, s26
	s_addc_u32 s37, s15, s27
	s_add_u32 s38, s36, 0x100
	s_addc_u32 s39, s37, 0
	s_and_b64 s[30:31], s[28:29], exec
	s_cselect_b32 s41, s19, s39
	s_cselect_b32 s40, s18, s38
	s_add_u32 s26, s0, s26
	s_addc_u32 s27, s1, s27
	s_add_u32 s30, s26, 0x100
	s_addc_u32 s31, s27, 0
	s_add_u32 s26, s40, 0x80
	s_addc_u32 s27, s41, 0
	s_add_i32 s81, 0, 0x10000
	s_and_b64 s[28:29], s[28:29], exec
	s_cselect_b32 s43, s17, s31
	s_cselect_b32 s42, s23, s30
	s_add_u32 s44, s36, 0x12080
	s_addc_u32 s45, s37, 0
	s_add_i32 s86, s81, s51
	s_add_i32 m0, s52, 0xc000
	s_add_i32 s87, s52, 0xe000
	s_add_i32 s85, 0, 0x14000
	s_add_i32 s84, s86, 0x2000
	s_add_u32 s38, s42, 0x10000
	s_addc_u32 s39, s43, 0
	s_add_i32 s82, s85, s51
	s_add_i32 s80, s82, 0x2000
	s_add_i32 s79, 0, 0x18000
	v_add_u32_e32 v152, s81, v1
	s_add_u32 s36, s40, 0x12000
	ds_read_b128 v[140:143], v152
	ds_read_b128 v[144:147], v152 offset:1024
	ds_read_b128 v[148:151], v152 offset:2048
	ds_read_b128 v[152:155], v152 offset:3072
	s_addc_u32 s37, s41, 0
	s_add_i32 s75, 0, 0x1c000
	s_add_u32 s30, s42, 0x80
	s_addc_u32 s31, s43, 0
	s_add_i32 s78, s79, s51
	s_add_i32 s74, s78, 0x2000
	s_add_u32 s28, s42, 0x10080
	s_addc_u32 s29, s43, 0
	s_add_i32 s83, s75, s51
	s_add_i32 s81, s83, 0x2000
	ds_read_b128 v[156:159], v3
	ds_read_b128 v[160:163], v3 offset:1024
	ds_read_b128 v[164:167], v3 offset:2048
	ds_read_b128 v[168:171], v3 offset:3072
	ds_read_b128 v[172:175], v3 offset:4096
	ds_read_b128 v[176:179], v3 offset:5120
	ds_read_b128 v[180:183], v3 offset:6144
	ds_read_b128 v[184:187], v3 offset:7168
	s_nop 0
	global_load_lds_dwordx4 v132, s[44:45]
	s_mov_b32 m0, s87
	s_nop 0
	global_load_lds_dwordx4 v136, s[44:45]
	s_waitcnt lgkmcnt(8)
	s_barrier
	s_waitcnt lgkmcnt(0)
	s_setprio 1
	s_waitcnt lgkmcnt(0)
	v_mfma_f32_16x16x32_bf16 v[128:131], v[140:143], v[156:159], v[128:131]
	v_mfma_f32_16x16x32_bf16 v[124:127], v[148:151], v[156:159], v[124:127]
	v_mfma_f32_16x16x32_bf16 v[112:115], v[140:143], v[164:167], v[112:115]
	v_mfma_f32_16x16x32_bf16 v[108:111], v[148:151], v[164:167], v[108:111]
	v_mfma_f32_16x16x32_bf16 v[96:99], v[140:143], v[172:175], v[96:99]
	v_mfma_f32_16x16x32_bf16 v[92:95], v[148:151], v[172:175], v[92:95]
	v_mfma_f32_16x16x32_bf16 v[80:83], v[140:143], v[180:183], v[80:83]
	v_mfma_f32_16x16x32_bf16 v[76:79], v[148:151], v[180:183], v[76:79]
	v_mfma_f32_16x16x32_bf16 v[128:131], v[144:147], v[160:163], v[128:131]
	v_mfma_f32_16x16x32_bf16 v[124:127], v[152:155], v[160:163], v[124:127]
	v_mfma_f32_16x16x32_bf16 v[112:115], v[144:147], v[168:171], v[112:115]
	v_mfma_f32_16x16x32_bf16 v[108:111], v[152:155], v[168:171], v[108:111]
	v_mfma_f32_16x16x32_bf16 v[96:99], v[144:147], v[176:179], v[96:99]
	v_mfma_f32_16x16x32_bf16 v[92:95], v[152:155], v[176:179], v[92:95]
	v_mfma_f32_16x16x32_bf16 v[80:83], v[144:147], v[184:187], v[80:83]
	v_mfma_f32_16x16x32_bf16 v[76:79], v[152:155], v[184:187], v[76:79]
	s_setprio 0
	s_barrier
	v_add_u32_e32 v214, s85, v1
	s_mov_b32 m0, s86
	ds_read_b128 v[188:191], v214
	ds_read_b128 v[192:195], v214 offset:1024
	ds_read_b128 v[210:213], v214 offset:2048
	ds_read_b128 v[214:217], v214 offset:3072
	s_nop 0
	global_load_lds_dwordx4 v134, s[42:43]
	s_mov_b32 m0, s84
	s_nop 0
	global_load_lds_dwordx4 v138, s[42:43]
	s_barrier
	s_waitcnt lgkmcnt(0)
	s_setprio 1
	s_waitcnt lgkmcnt(0)
	v_mfma_f32_16x16x32_bf16 v[120:123], v[188:191], v[156:159], v[120:123]
	v_mfma_f32_16x16x32_bf16 v[116:119], v[210:213], v[156:159], v[116:119]
	v_mfma_f32_16x16x32_bf16 v[104:107], v[188:191], v[164:167], v[104:107]
	v_mfma_f32_16x16x32_bf16 v[100:103], v[210:213], v[164:167], v[100:103]
	v_mfma_f32_16x16x32_bf16 v[88:91], v[188:191], v[172:175], v[88:91]
	v_mfma_f32_16x16x32_bf16 v[84:87], v[210:213], v[172:175], v[84:87]
	v_mfma_f32_16x16x32_bf16 v[72:75], v[188:191], v[180:183], v[72:75]
	v_mfma_f32_16x16x32_bf16 v[68:71], v[210:213], v[180:183], v[68:71]
	v_mfma_f32_16x16x32_bf16 v[120:123], v[192:195], v[160:163], v[120:123]
	v_mfma_f32_16x16x32_bf16 v[116:119], v[214:217], v[160:163], v[116:119]
	v_mfma_f32_16x16x32_bf16 v[104:107], v[192:195], v[168:171], v[104:107]
	v_mfma_f32_16x16x32_bf16 v[100:103], v[214:217], v[168:171], v[100:103]
	v_mfma_f32_16x16x32_bf16 v[88:91], v[192:195], v[176:179], v[88:91]
	v_mfma_f32_16x16x32_bf16 v[84:87], v[214:217], v[176:179], v[84:87]
	v_mfma_f32_16x16x32_bf16 v[72:75], v[192:195], v[184:187], v[72:75]
	v_mfma_f32_16x16x32_bf16 v[68:71], v[214:217], v[184:187], v[68:71]
	s_setprio 0
	s_mov_b32 m0, s52
	s_barrier
	ds_read_b128 v[156:159], v3 offset:16384
	ds_read_b128 v[160:163], v3 offset:17408
	ds_read_b128 v[164:167], v3 offset:18432
	ds_read_b128 v[168:171], v3 offset:19456
	ds_read_b128 v[172:175], v3 offset:20480
	ds_read_b128 v[176:179], v3 offset:21504
	ds_read_b128 v[180:183], v3 offset:22528
	ds_read_b128 v[184:187], v3 offset:23552
	s_nop 0
	global_load_lds_dwordx4 v132, s[40:41]
	s_mov_b32 m0, s53
	s_nop 0
	global_load_lds_dwordx4 v136, s[40:41]
	s_barrier
	s_waitcnt lgkmcnt(0)
	s_setprio 1
	s_waitcnt lgkmcnt(0)
	v_mfma_f32_16x16x32_bf16 v[64:67], v[140:143], v[156:159], v[64:67]
	v_mfma_f32_16x16x32_bf16 v[60:63], v[148:151], v[156:159], v[60:63]
	v_mfma_f32_16x16x32_bf16 v[48:51], v[140:143], v[164:167], v[48:51]
	v_mfma_f32_16x16x32_bf16 v[44:47], v[148:151], v[164:167], v[44:47]
	v_mfma_f32_16x16x32_bf16 v[32:35], v[140:143], v[172:175], v[32:35]
	v_mfma_f32_16x16x32_bf16 v[28:31], v[148:151], v[172:175], v[28:31]
	v_mfma_f32_16x16x32_bf16 v[16:19], v[140:143], v[180:183], v[16:19]
	v_mfma_f32_16x16x32_bf16 v[12:15], v[148:151], v[180:183], v[12:15]
	v_mfma_f32_16x16x32_bf16 v[64:67], v[144:147], v[160:163], v[64:67]
	v_mfma_f32_16x16x32_bf16 v[60:63], v[152:155], v[160:163], v[60:63]
	v_mfma_f32_16x16x32_bf16 v[48:51], v[144:147], v[168:171], v[48:51]
	v_mfma_f32_16x16x32_bf16 v[44:47], v[152:155], v[168:171], v[44:47]
	v_mfma_f32_16x16x32_bf16 v[32:35], v[144:147], v[176:179], v[32:35]
	v_mfma_f32_16x16x32_bf16 v[28:31], v[152:155], v[176:179], v[28:31]
	v_mfma_f32_16x16x32_bf16 v[16:19], v[144:147], v[184:187], v[16:19]
	v_mfma_f32_16x16x32_bf16 v[12:15], v[152:155], v[184:187], v[12:15]
	s_setprio 0
	s_barrier
	s_mov_b32 m0, s82
	s_nop 0
	global_load_lds_dwordx4 v134, s[38:39]
	s_mov_b32 m0, s80
	s_nop 0
	global_load_lds_dwordx4 v138, s[38:39]
	s_waitcnt vmcnt(6)
	s_barrier
	s_setprio 1
	v_mfma_f32_16x16x32_bf16 v[56:59], v[188:191], v[156:159], v[56:59]
	v_mfma_f32_16x16x32_bf16 v[52:55], v[210:213], v[156:159], v[52:55]
	v_mfma_f32_16x16x32_bf16 v[40:43], v[188:191], v[164:167], v[40:43]
	v_mfma_f32_16x16x32_bf16 v[36:39], v[210:213], v[164:167], v[36:39]
	v_mfma_f32_16x16x32_bf16 v[24:27], v[188:191], v[172:175], v[24:27]
	v_mfma_f32_16x16x32_bf16 v[20:23], v[210:213], v[172:175], v[20:23]
	v_mfma_f32_16x16x32_bf16 v[8:11], v[188:191], v[180:183], v[8:11]
	v_mfma_f32_16x16x32_bf16 v[4:7], v[210:213], v[180:183], v[4:7]
	v_mfma_f32_16x16x32_bf16 v[56:59], v[192:195], v[160:163], v[56:59]
	v_mfma_f32_16x16x32_bf16 v[52:55], v[214:217], v[160:163], v[52:55]
	v_mfma_f32_16x16x32_bf16 v[40:43], v[192:195], v[168:171], v[40:43]
	v_mfma_f32_16x16x32_bf16 v[36:39], v[214:217], v[168:171], v[36:39]
	v_mfma_f32_16x16x32_bf16 v[24:27], v[192:195], v[176:179], v[24:27]
	v_mfma_f32_16x16x32_bf16 v[20:23], v[214:217], v[176:179], v[20:23]
	v_mfma_f32_16x16x32_bf16 v[8:11], v[192:195], v[184:187], v[8:11]
	v_mfma_f32_16x16x32_bf16 v[4:7], v[214:217], v[184:187], v[4:7]
	s_setprio 0
	v_add_u32_e32 v152, s79, v1
	s_barrier
	ds_read_b128 v[140:143], v152
	ds_read_b128 v[144:147], v152 offset:1024
	ds_read_b128 v[148:151], v152 offset:2048
	ds_read_b128 v[152:155], v152 offset:3072
	s_mov_b32 m0, s55
	ds_read_b128 v[156:159], v3 offset:32768
	ds_read_b128 v[160:163], v3 offset:33792
	ds_read_b128 v[164:167], v3 offset:34816
	ds_read_b128 v[168:171], v3 offset:35840
	ds_read_b128 v[172:175], v3 offset:36864
	ds_read_b128 v[176:179], v3 offset:37888
	ds_read_b128 v[180:183], v3 offset:38912
	ds_read_b128 v[184:187], v3 offset:39936
	s_nop 0
	global_load_lds_dwordx4 v132, s[36:37]
	s_mov_b32 m0, s56
	s_nop 0
	global_load_lds_dwordx4 v136, s[36:37]
	s_waitcnt lgkmcnt(8)
	s_barrier
	s_waitcnt lgkmcnt(0)
	s_setprio 1
	s_waitcnt lgkmcnt(0)
	v_mfma_f32_16x16x32_bf16 v[128:131], v[140:143], v[156:159], v[128:131]
	v_mfma_f32_16x16x32_bf16 v[124:127], v[148:151], v[156:159], v[124:127]
	v_mfma_f32_16x16x32_bf16 v[112:115], v[140:143], v[164:167], v[112:115]
	v_mfma_f32_16x16x32_bf16 v[108:111], v[148:151], v[164:167], v[108:111]
	v_mfma_f32_16x16x32_bf16 v[96:99], v[140:143], v[172:175], v[96:99]
	v_mfma_f32_16x16x32_bf16 v[92:95], v[148:151], v[172:175], v[92:95]
	v_mfma_f32_16x16x32_bf16 v[80:83], v[140:143], v[180:183], v[80:83]
	v_mfma_f32_16x16x32_bf16 v[76:79], v[148:151], v[180:183], v[76:79]
	v_mfma_f32_16x16x32_bf16 v[128:131], v[144:147], v[160:163], v[128:131]
	v_mfma_f32_16x16x32_bf16 v[124:127], v[152:155], v[160:163], v[124:127]
	v_mfma_f32_16x16x32_bf16 v[112:115], v[144:147], v[168:171], v[112:115]
	v_mfma_f32_16x16x32_bf16 v[108:111], v[152:155], v[168:171], v[108:111]
	v_mfma_f32_16x16x32_bf16 v[96:99], v[144:147], v[176:179], v[96:99]
	v_mfma_f32_16x16x32_bf16 v[92:95], v[152:155], v[176:179], v[92:95]
	v_mfma_f32_16x16x32_bf16 v[80:83], v[144:147], v[184:187], v[80:83]
	v_mfma_f32_16x16x32_bf16 v[76:79], v[152:155], v[184:187], v[76:79]
	s_setprio 0
	s_barrier
	v_add_u32_e32 v214, s75, v1
	s_mov_b32 m0, s78
	ds_read_b128 v[188:191], v214
	ds_read_b128 v[192:195], v214 offset:1024
	ds_read_b128 v[210:213], v214 offset:2048
	ds_read_b128 v[214:217], v214 offset:3072
	s_nop 0
	global_load_lds_dwordx4 v134, s[30:31]
	s_mov_b32 m0, s74
	s_nop 0
	global_load_lds_dwordx4 v138, s[30:31]
	s_barrier
	s_waitcnt lgkmcnt(0)
	s_setprio 1
	s_waitcnt lgkmcnt(0)
	v_mfma_f32_16x16x32_bf16 v[120:123], v[188:191], v[156:159], v[120:123]
	v_mfma_f32_16x16x32_bf16 v[116:119], v[210:213], v[156:159], v[116:119]
	v_mfma_f32_16x16x32_bf16 v[104:107], v[188:191], v[164:167], v[104:107]
	v_mfma_f32_16x16x32_bf16 v[100:103], v[210:213], v[164:167], v[100:103]
	v_mfma_f32_16x16x32_bf16 v[88:91], v[188:191], v[172:175], v[88:91]
	v_mfma_f32_16x16x32_bf16 v[84:87], v[210:213], v[172:175], v[84:87]
	v_mfma_f32_16x16x32_bf16 v[72:75], v[188:191], v[180:183], v[72:75]
	v_mfma_f32_16x16x32_bf16 v[68:71], v[210:213], v[180:183], v[68:71]
	v_mfma_f32_16x16x32_bf16 v[120:123], v[192:195], v[160:163], v[120:123]
	v_mfma_f32_16x16x32_bf16 v[116:119], v[214:217], v[160:163], v[116:119]
	v_mfma_f32_16x16x32_bf16 v[104:107], v[192:195], v[168:171], v[104:107]
	v_mfma_f32_16x16x32_bf16 v[100:103], v[214:217], v[168:171], v[100:103]
	v_mfma_f32_16x16x32_bf16 v[88:91], v[192:195], v[176:179], v[88:91]
	v_mfma_f32_16x16x32_bf16 v[84:87], v[214:217], v[176:179], v[84:87]
	v_mfma_f32_16x16x32_bf16 v[72:75], v[192:195], v[184:187], v[72:75]
	v_mfma_f32_16x16x32_bf16 v[68:71], v[214:217], v[184:187], v[68:71]
	s_setprio 0
	s_mov_b32 m0, s65
	s_barrier
	ds_read_b128 v[156:159], v3 offset:49152
	ds_read_b128 v[160:163], v3 offset:50176
	ds_read_b128 v[164:167], v3 offset:51200
	ds_read_b128 v[168:171], v3 offset:52224
	ds_read_b128 v[172:175], v3 offset:53248
	ds_read_b128 v[176:179], v3 offset:54272
	ds_read_b128 v[180:183], v3 offset:55296
	ds_read_b128 v[184:187], v3 offset:56320
	s_nop 0
	global_load_lds_dwordx4 v132, s[26:27]
	s_mov_b32 m0, s67
	s_nop 0
	global_load_lds_dwordx4 v136, s[26:27]
	s_barrier
	s_waitcnt lgkmcnt(0)
	s_setprio 1
	s_waitcnt lgkmcnt(0)
	v_mfma_f32_16x16x32_bf16 v[64:67], v[140:143], v[156:159], v[64:67]
	v_mfma_f32_16x16x32_bf16 v[60:63], v[148:151], v[156:159], v[60:63]
	v_mfma_f32_16x16x32_bf16 v[48:51], v[140:143], v[164:167], v[48:51]
	v_mfma_f32_16x16x32_bf16 v[44:47], v[148:151], v[164:167], v[44:47]
	v_mfma_f32_16x16x32_bf16 v[32:35], v[140:143], v[172:175], v[32:35]
	v_mfma_f32_16x16x32_bf16 v[28:31], v[148:151], v[172:175], v[28:31]
	v_mfma_f32_16x16x32_bf16 v[16:19], v[140:143], v[180:183], v[16:19]
	v_mfma_f32_16x16x32_bf16 v[12:15], v[148:151], v[180:183], v[12:15]
	v_mfma_f32_16x16x32_bf16 v[64:67], v[144:147], v[160:163], v[64:67]
	v_mfma_f32_16x16x32_bf16 v[60:63], v[152:155], v[160:163], v[60:63]
	v_mfma_f32_16x16x32_bf16 v[48:51], v[144:147], v[168:171], v[48:51]
	v_mfma_f32_16x16x32_bf16 v[44:47], v[152:155], v[168:171], v[44:47]
	v_mfma_f32_16x16x32_bf16 v[32:35], v[144:147], v[176:179], v[32:35]
	v_mfma_f32_16x16x32_bf16 v[28:31], v[152:155], v[176:179], v[28:31]
	v_mfma_f32_16x16x32_bf16 v[16:19], v[144:147], v[184:187], v[16:19]
	v_mfma_f32_16x16x32_bf16 v[12:15], v[152:155], v[184:187], v[12:15]
	s_setprio 0
	s_barrier
	s_mov_b32 m0, s83
	s_nop 0
	global_load_lds_dwordx4 v134, s[28:29]
	s_mov_b32 m0, s81
	s_nop 0
	global_load_lds_dwordx4 v138, s[28:29]
	s_waitcnt vmcnt(6)
	s_barrier
	s_setprio 1
	v_mfma_f32_16x16x32_bf16 v[56:59], v[188:191], v[156:159], v[56:59]
	v_mfma_f32_16x16x32_bf16 v[52:55], v[210:213], v[156:159], v[52:55]
	v_mfma_f32_16x16x32_bf16 v[40:43], v[188:191], v[164:167], v[40:43]
	v_mfma_f32_16x16x32_bf16 v[36:39], v[210:213], v[164:167], v[36:39]
	v_mfma_f32_16x16x32_bf16 v[24:27], v[188:191], v[172:175], v[24:27]
	v_mfma_f32_16x16x32_bf16 v[20:23], v[210:213], v[172:175], v[20:23]
	v_mfma_f32_16x16x32_bf16 v[8:11], v[188:191], v[180:183], v[8:11]
	v_mfma_f32_16x16x32_bf16 v[4:7], v[210:213], v[180:183], v[4:7]
	v_mfma_f32_16x16x32_bf16 v[56:59], v[192:195], v[160:163], v[56:59]
	v_mfma_f32_16x16x32_bf16 v[52:55], v[214:217], v[160:163], v[52:55]
	v_mfma_f32_16x16x32_bf16 v[40:43], v[192:195], v[168:171], v[40:43]
	v_mfma_f32_16x16x32_bf16 v[36:39], v[214:217], v[168:171], v[36:39]
	v_mfma_f32_16x16x32_bf16 v[24:27], v[192:195], v[176:179], v[24:27]
	v_mfma_f32_16x16x32_bf16 v[20:23], v[214:217], v[176:179], v[20:23]
	v_mfma_f32_16x16x32_bf16 v[8:11], v[192:195], v[184:187], v[8:11]
	v_mfma_f32_16x16x32_bf16 v[4:7], v[214:217], v[184:187], v[4:7]
	s_setprio 0
	s_andn2_b64 vcc, exec, s[24:25]
	s_mov_b64 s[28:29], -1
	s_mov_b64 s[24:25], 0
	s_mov_b64 s[26:27], 0x100
	s_barrier
	s_cbranch_vccz .LBB0_654
	v_mov_b32_e32 v141, v0
	s_ashr_i32 s23, s22, 31
	v_readfirstlane_b32 s0, v141
	s_bfe_u32 s17, s0, 0x20006
	s_ashr_i32 s0, s0, 2
	s_andn2_b32 s0, s0, 63
	s_ashr_i32 s1, s0, 31
	s_lshl_b64 s[14:15], s[22:23], 10
	s_add_u32 s24, s57, s14
	s_addc_u32 s25, s62, s15
	s_lshl_b64 s[14:15], s[0:1], 2
	v_and_b32_e32 v142, 15, v141
	s_add_u32 s24, s24, s14
	s_addc_u32 s25, s25, s15
	v_lshlrev_b32_e32 v140, 2, v142
	global_load_dword v150, v140, s[24:25] offset:64
	global_load_dword v149, v140, s[24:25] offset:128
	global_load_dword v148, v140, s[24:25] offset:192
	global_load_dword v147, v140, s[24:25] offset:512
	global_load_dword v146, v140, s[24:25] offset:576
	global_load_dword v145, v140, s[24:25] offset:640
	global_load_dword v144, v140, s[24:25] offset:704
	v_mul_f32_e32 v129, v129, v129
	v_mul_f32_e32 v125, v125, v125
	v_mul_f32_e32 v121, v121, v121
	v_mul_f32_e32 v117, v117, v117
	v_fmac_f32_e32 v129, v128, v128
	v_mul_f32_e32 v128, v131, v131
	v_fmac_f32_e32 v125, v124, v124
	v_mul_f32_e32 v124, v127, v127
	v_fmac_f32_e32 v121, v120, v120
	v_mul_f32_e32 v120, v123, v123
	v_fmac_f32_e32 v117, v116, v116
	v_mul_f32_e32 v116, v119, v119
	v_fmac_f32_e32 v128, v130, v130
	v_fmac_f32_e32 v124, v126, v126
	v_fmac_f32_e32 v120, v122, v122
	v_fmac_f32_e32 v116, v118, v118
	v_add_f32_e32 v128, v129, v128
	v_add_f32_e32 v124, v125, v124
	v_add_f32_e32 v120, v121, v120
	v_add_f32_e32 v116, v117, v116
	v_add_f32_e32 v124, v128, v124
	v_add_f32_e32 v116, v120, v116
	v_add_f32_e32 v117, v124, v116
	v_mov_b32_e32 v118, v117
	s_nop 1
	v_permlane16_swap_b32 v118, v117
	v_and_b32_e32 v152, 64, v236
	v_xor_b32_e32 v151, 32, v236
	v_add_u32_e32 v152, 64, v152
	v_cmp_lt_i32_e32 vcc, v151, v152
	s_lshl_b32 s14, s73, 2
	s_or_b32 s26, s17, s14
	v_cndmask_b32_e32 v116, v236, v151, vcc
	s_lshl_b64 s[14:15], s[22:23], 8
	v_lshlrev_b32_e32 v116, 2, v116
	s_waitcnt lgkmcnt(0)
	v_add_f32_e32 v117, v117, v118
	s_add_u32 s0, s14, s0
	v_mov_b32_e32 v118, v117
	s_nop 1
	v_permlane32_swap_b32 v118, v117
	s_addc_u32 s1, s15, s1
	s_ashr_i32 s27, s26, 31
	v_or_b32_e32 v143, s0, v142
	v_mov_b32_e32 v142, s1
	s_lshl_b64 s[0:1], s[26:27], 2
	v_and_b32_e32 v119, 48, v141
	s_add_u32 s0, s63, s0
	v_cmp_eq_u32_e64 s[14:15], 0, v119
	s_addc_u32 s1, s64, s1
	s_and_saveexec_b64 s[22:23], s[14:15]
	s_cbranch_execz .LBB0_657
	v_mov_b32_e32 v141, v2
	v_lshl_add_u64 v[120:121], s[24:25], 0, v[140:141]
	global_load_dword v119, v[120:121], off
	s_waitcnt lgkmcnt(0)
	v_add_f32_e32 v117, v117, v118
	s_waitcnt vmcnt(0)
	v_add_f32_e32 v117, v117, v119
	v_fmamk_f32 v117, v117, 0x3c2aaaab, v231
	v_cmp_gt_f32_e32 vcc, s11, v117
	v_mul_f32_e32 v118, 0x4b800000, v117
	s_nop 0
	v_cndmask_b32_e32 v117, v117, v118, vcc
	v_rsq_f32_e32 v117, v117
	s_nop 0
	v_mul_f32_e32 v118, 0x45800000, v117
	v_cndmask_b32_e32 v117, v117, v118, vcc
	v_mad_u64_u32 v[118:119], s[24:25], v143, 48, s[0:1]
	v_mov_b32_e32 v120, v119
	v_mad_u64_u32 v[120:121], s[24:25], v142, 48, v[120:121]
	v_mov_b32_e32 v119, v120
	global_store_dword v[118:119], v117, off
.LBB0_657:
	s_or_b64 exec, exec, s[22:23]
	v_mul_f32_e32 v113, v113, v113
	v_mul_f32_e32 v109, v109, v109
	v_mul_f32_e32 v105, v105, v105
	v_mul_f32_e32 v101, v101, v101
	v_fmac_f32_e32 v113, v112, v112
	v_mul_f32_e32 v112, v115, v115
	v_fmac_f32_e32 v109, v108, v108
	v_mul_f32_e32 v108, v111, v111
	v_fmac_f32_e32 v105, v104, v104
	v_mul_f32_e32 v104, v107, v107
	v_fmac_f32_e32 v101, v100, v100
	v_mul_f32_e32 v100, v103, v103
	v_fmac_f32_e32 v112, v114, v114
	v_fmac_f32_e32 v108, v110, v110
	v_fmac_f32_e32 v104, v106, v106
	v_fmac_f32_e32 v100, v102, v102
	v_add_f32_e32 v112, v113, v112
	v_add_f32_e32 v108, v109, v108
	v_add_f32_e32 v104, v105, v104
	v_add_f32_e32 v100, v101, v100
	v_add_f32_e32 v108, v112, v108
	v_add_f32_e32 v100, v104, v100
	v_add_f32_e32 v100, v108, v100
	v_mov_b32_e32 v101, v100
	s_nop 1
	v_permlane16_swap_b32 v101, v100
	s_waitcnt lgkmcnt(0)
	v_add_f32_e32 v100, v100, v101
	v_mov_b32_e32 v101, v100
	s_nop 1
	v_permlane32_swap_b32 v101, v100
	s_and_saveexec_b64 s[22:23], s[14:15]
	s_cbranch_execz .LBB0_659
	s_waitcnt lgkmcnt(0)
	v_add_f32_e32 v100, v100, v101
	s_waitcnt vmcnt(0)
	v_add_f32_e32 v100, v150, v100
	v_fmamk_f32 v100, v100, 0x3c2aaaab, v231
	v_cmp_gt_f32_e32 vcc, s11, v100
	v_mul_f32_e32 v101, 0x4b800000, v100
	s_nop 0
	v_cndmask_b32_e32 v100, v100, v101, vcc
	v_rsq_f32_e32 v100, v100
	s_nop 0
	v_mul_f32_e32 v101, 0x45800000, v100
	v_cndmask_b32_e32 v104, v100, v101, vcc
	v_mad_u64_u32 v[100:101], s[24:25], v143, 48, s[0:1]
	v_mov_b32_e32 v102, v101
	v_mad_u64_u32 v[102:103], s[24:25], v142, 48, v[102:103]
	v_mov_b32_e32 v101, v102
	global_store_dword v[100:101], v104, off offset:768
.LBB0_659:
	s_or_b64 exec, exec, s[22:23]
	v_mul_f32_e32 v97, v97, v97
	v_mul_f32_e32 v93, v93, v93
	v_mul_f32_e32 v89, v89, v89
	v_mul_f32_e32 v85, v85, v85
	v_fmac_f32_e32 v97, v96, v96
	v_mul_f32_e32 v96, v99, v99
	v_fmac_f32_e32 v93, v92, v92
	v_mul_f32_e32 v92, v95, v95
	v_fmac_f32_e32 v89, v88, v88
	v_mul_f32_e32 v88, v91, v91
	v_fmac_f32_e32 v85, v84, v84
	v_mul_f32_e32 v84, v87, v87
	v_fmac_f32_e32 v96, v98, v98
	v_fmac_f32_e32 v92, v94, v94
	v_fmac_f32_e32 v88, v90, v90
	v_fmac_f32_e32 v84, v86, v86
	v_add_f32_e32 v96, v97, v96
	v_add_f32_e32 v92, v93, v92
	v_add_f32_e32 v88, v89, v88
	v_add_f32_e32 v84, v85, v84
	v_add_f32_e32 v92, v96, v92
	v_add_f32_e32 v84, v88, v84
	v_add_f32_e32 v84, v92, v84
	v_mov_b32_e32 v85, v84
	s_nop 1
	v_permlane16_swap_b32 v85, v84
	s_waitcnt lgkmcnt(0)
	v_add_f32_e32 v84, v84, v85
	v_mov_b32_e32 v85, v84
	s_nop 1
	v_permlane32_swap_b32 v85, v84
	s_and_saveexec_b64 s[22:23], s[14:15]
	s_cbranch_execz .LBB0_661
	s_waitcnt lgkmcnt(0)
	v_add_f32_e32 v84, v84, v85
	s_waitcnt vmcnt(0)
	v_add_f32_e32 v84, v149, v84
	v_fmamk_f32 v84, v84, 0x3c2aaaab, v231
	v_cmp_gt_f32_e32 vcc, s11, v84
	v_mul_f32_e32 v85, 0x4b800000, v84
	s_nop 0
	v_cndmask_b32_e32 v84, v84, v85, vcc
	v_rsq_f32_e32 v84, v84
	s_nop 0
	v_mul_f32_e32 v85, 0x45800000, v84
	v_cndmask_b32_e32 v88, v84, v85, vcc
	v_mad_u64_u32 v[84:85], s[24:25], v143, 48, s[0:1]
	v_mov_b32_e32 v86, v85
	v_mad_u64_u32 v[86:87], s[24:25], v142, 48, v[86:87]
	v_mov_b32_e32 v85, v86
	global_store_dword v[84:85], v88, off offset:1536
.LBB0_661:
	s_or_b64 exec, exec, s[22:23]
	v_mul_f32_e32 v81, v81, v81
	v_mul_f32_e32 v77, v77, v77
	v_mul_f32_e32 v73, v73, v73
	v_mul_f32_e32 v69, v69, v69
	v_fmac_f32_e32 v81, v80, v80
	v_mul_f32_e32 v80, v83, v83
	v_fmac_f32_e32 v77, v76, v76
	v_mul_f32_e32 v76, v79, v79
	v_fmac_f32_e32 v73, v72, v72
	v_mul_f32_e32 v72, v75, v75
	v_fmac_f32_e32 v69, v68, v68
	v_mul_f32_e32 v68, v71, v71
	v_fmac_f32_e32 v80, v82, v82
	v_fmac_f32_e32 v76, v78, v78
	v_fmac_f32_e32 v72, v74, v74
	v_fmac_f32_e32 v68, v70, v70
	v_add_f32_e32 v80, v81, v80
	v_add_f32_e32 v76, v77, v76
	v_add_f32_e32 v72, v73, v72
	v_add_f32_e32 v68, v69, v68
	v_add_f32_e32 v76, v80, v76
	v_add_f32_e32 v68, v72, v68
	v_add_f32_e32 v68, v76, v68
	v_mov_b32_e32 v69, v68
	s_nop 1
	v_permlane16_swap_b32 v69, v68
	s_waitcnt lgkmcnt(0)
	v_add_f32_e32 v68, v68, v69
	v_mov_b32_e32 v69, v68
	s_nop 1
	v_permlane32_swap_b32 v69, v68
	s_and_saveexec_b64 s[22:23], s[14:15]
	s_cbranch_execz .LBB0_663
	s_waitcnt lgkmcnt(0)
	v_add_f32_e32 v68, v68, v69
	s_waitcnt vmcnt(0)
	v_add_f32_e32 v68, v148, v68
	v_fmamk_f32 v68, v68, 0x3c2aaaab, v231
	v_cmp_gt_f32_e32 vcc, s11, v68
	v_mul_f32_e32 v69, 0x4b800000, v68
	s_nop 0
	v_cndmask_b32_e32 v68, v68, v69, vcc
	v_rsq_f32_e32 v68, v68
	s_nop 0
	v_mul_f32_e32 v69, 0x45800000, v68
	v_cndmask_b32_e32 v72, v68, v69, vcc
	v_mad_u64_u32 v[68:69], s[24:25], v143, 48, s[0:1]
	v_mov_b32_e32 v70, v69
	v_mad_u64_u32 v[70:71], s[24:25], v142, 48, v[70:71]
	v_mov_b32_e32 v69, v70
	global_store_dword v[68:69], v72, off offset:2304
.LBB0_663:
	s_or_b64 exec, exec, s[22:23]
	v_mul_f32_e32 v65, v65, v65
	v_mul_f32_e32 v61, v61, v61
	v_mul_f32_e32 v57, v57, v57
	v_mul_f32_e32 v53, v53, v53
	v_fmac_f32_e32 v65, v64, v64
	v_mul_f32_e32 v64, v67, v67
	v_fmac_f32_e32 v61, v60, v60
	v_mul_f32_e32 v60, v63, v63
	v_fmac_f32_e32 v57, v56, v56
	v_mul_f32_e32 v56, v59, v59
	v_fmac_f32_e32 v53, v52, v52
	v_mul_f32_e32 v52, v55, v55
	v_fmac_f32_e32 v64, v66, v66
	v_fmac_f32_e32 v60, v62, v62
	v_fmac_f32_e32 v56, v58, v58
	v_fmac_f32_e32 v52, v54, v54
	v_add_f32_e32 v64, v65, v64
	v_add_f32_e32 v60, v61, v60
	v_add_f32_e32 v56, v57, v56
	v_add_f32_e32 v52, v53, v52
	v_add_f32_e32 v60, v64, v60
	v_add_f32_e32 v52, v56, v52
	v_add_f32_e32 v52, v60, v52
	v_mov_b32_e32 v53, v52
	s_nop 1
	v_permlane16_swap_b32 v53, v52
	s_waitcnt lgkmcnt(0)
	v_add_f32_e32 v52, v52, v53
	v_mov_b32_e32 v53, v52
	s_nop 1
	v_permlane32_swap_b32 v53, v52
	s_and_saveexec_b64 s[22:23], s[14:15]
	s_cbranch_execz .LBB0_665
	s_waitcnt lgkmcnt(0)
	v_add_f32_e32 v52, v52, v53
	s_waitcnt vmcnt(0)
	v_add_f32_e32 v52, v147, v52
	v_fmamk_f32 v52, v52, 0x3c2aaaab, v231
	v_mul_f32_e32 v53, 0x4b800000, v52
	v_cmp_gt_f32_e32 vcc, s11, v52
	s_nop 1
	v_cndmask_b32_e32 v52, v52, v53, vcc
	v_rsq_f32_e32 v54, v52
	v_mad_u64_u32 v[52:53], s[24:25], v143, 48, s[0:1]
	v_mul_f32_e32 v55, 0x45800000, v54
	v_cndmask_b32_e32 v56, v54, v55, vcc
	v_mov_b32_e32 v54, v53
	v_mad_u64_u32 v[54:55], s[24:25], v142, 48, v[54:55]
	v_add_co_u32_e32 v52, vcc, 0x1000, v52
	s_nop 1
	v_addc_co_u32_e32 v53, vcc, 0, v54, vcc
	global_store_dword v[52:53], v56, off offset:2048
.LBB0_665:
	s_or_b64 exec, exec, s[22:23]
	v_mul_f32_e32 v49, v49, v49
	v_mul_f32_e32 v45, v45, v45
	v_mul_f32_e32 v41, v41, v41
	v_mul_f32_e32 v37, v37, v37
	v_fmac_f32_e32 v49, v48, v48
	v_mul_f32_e32 v48, v51, v51
	v_fmac_f32_e32 v45, v44, v44
	v_mul_f32_e32 v44, v47, v47
	v_fmac_f32_e32 v41, v40, v40
	v_mul_f32_e32 v40, v43, v43
	v_fmac_f32_e32 v37, v36, v36
	v_mul_f32_e32 v36, v39, v39
	v_fmac_f32_e32 v48, v50, v50
	v_fmac_f32_e32 v44, v46, v46
	v_fmac_f32_e32 v40, v42, v42
	v_fmac_f32_e32 v36, v38, v38
	v_add_f32_e32 v48, v49, v48
	v_add_f32_e32 v44, v45, v44
	v_add_f32_e32 v40, v41, v40
	v_add_f32_e32 v36, v37, v36
	v_add_f32_e32 v44, v48, v44
	v_add_f32_e32 v36, v40, v36
	v_add_f32_e32 v36, v44, v36
	v_mov_b32_e32 v37, v36
	s_nop 1
	v_permlane16_swap_b32 v37, v36
	s_waitcnt lgkmcnt(0)
	v_add_f32_e32 v36, v36, v37
	v_mov_b32_e32 v37, v36
	s_nop 1
	v_permlane32_swap_b32 v37, v36
	s_and_saveexec_b64 s[22:23], s[14:15]
	s_cbranch_execz .LBB0_667
	s_waitcnt lgkmcnt(0)
	v_add_f32_e32 v36, v36, v37
	s_waitcnt vmcnt(0)
	v_add_f32_e32 v36, v146, v36
	v_fmamk_f32 v36, v36, 0x3c2aaaab, v231
	v_mul_f32_e32 v37, 0x4b800000, v36
	v_cmp_gt_f32_e32 vcc, s11, v36
	s_nop 1
	v_cndmask_b32_e32 v36, v36, v37, vcc
	v_rsq_f32_e32 v38, v36
	v_mad_u64_u32 v[36:37], s[24:25], v143, 48, s[0:1]
	v_mul_f32_e32 v39, 0x45800000, v38
	v_cndmask_b32_e32 v40, v38, v39, vcc
	v_mov_b32_e32 v38, v37
	v_mad_u64_u32 v[38:39], s[24:25], v142, 48, v[38:39]
	v_add_co_u32_e32 v36, vcc, 0x1000, v36
	s_nop 1
	v_addc_co_u32_e32 v37, vcc, 0, v38, vcc
	global_store_dword v[36:37], v40, off offset:2816
.LBB0_667:
	s_or_b64 exec, exec, s[22:23]
	v_mul_f32_e32 v33, v33, v33
	v_mul_f32_e32 v29, v29, v29
	v_mul_f32_e32 v25, v25, v25
	v_mul_f32_e32 v21, v21, v21
	v_fmac_f32_e32 v33, v32, v32
	v_mul_f32_e32 v32, v35, v35
	v_fmac_f32_e32 v29, v28, v28
	v_mul_f32_e32 v28, v31, v31
	v_fmac_f32_e32 v25, v24, v24
	v_mul_f32_e32 v24, v27, v27
	v_fmac_f32_e32 v21, v20, v20
	v_mul_f32_e32 v20, v23, v23
	v_fmac_f32_e32 v32, v34, v34
	v_fmac_f32_e32 v28, v30, v30
	v_fmac_f32_e32 v24, v26, v26
	v_fmac_f32_e32 v20, v22, v22
	v_add_f32_e32 v32, v33, v32
	v_add_f32_e32 v28, v29, v28
	v_add_f32_e32 v24, v25, v24
	v_add_f32_e32 v20, v21, v20
	v_add_f32_e32 v28, v32, v28
	v_add_f32_e32 v20, v24, v20
	v_add_f32_e32 v20, v28, v20
	v_mov_b32_e32 v21, v20
	s_nop 1
	v_permlane16_swap_b32 v21, v20
	s_waitcnt lgkmcnt(0)
	v_add_f32_e32 v20, v20, v21
	v_mov_b32_e32 v21, v20
	s_nop 1
	v_permlane32_swap_b32 v21, v20
	s_and_saveexec_b64 s[22:23], s[14:15]
	s_cbranch_execz .LBB0_669
	s_waitcnt lgkmcnt(0)
	v_add_f32_e32 v20, v20, v21
	s_waitcnt vmcnt(0)
	v_add_f32_e32 v20, v145, v20
	v_fmamk_f32 v20, v20, 0x3c2aaaab, v231
	v_mul_f32_e32 v21, 0x4b800000, v20
	v_cmp_gt_f32_e32 vcc, s11, v20
	s_nop 1
	v_cndmask_b32_e32 v20, v20, v21, vcc
	v_rsq_f32_e32 v22, v20
	v_mad_u64_u32 v[20:21], s[24:25], v143, 48, s[0:1]
	v_mul_f32_e32 v23, 0x45800000, v22
	v_cndmask_b32_e32 v24, v22, v23, vcc
	v_mov_b32_e32 v22, v21
	v_mad_u64_u32 v[22:23], s[24:25], v142, 48, v[22:23]
	v_add_co_u32_e32 v20, vcc, 0x1000, v20
	s_nop 1
	v_addc_co_u32_e32 v21, vcc, 0, v22, vcc
	global_store_dword v[20:21], v24, off offset:3584
.LBB0_669:
	s_or_b64 exec, exec, s[22:23]
	v_mul_f32_e32 v17, v17, v17
	v_mul_f32_e32 v13, v13, v13
	v_mul_f32_e32 v9, v9, v9
	v_mul_f32_e32 v5, v5, v5
	v_fmac_f32_e32 v17, v16, v16
	v_mul_f32_e32 v16, v19, v19
	v_fmac_f32_e32 v13, v12, v12
	v_mul_f32_e32 v12, v15, v15
	v_fmac_f32_e32 v9, v8, v8
	v_mul_f32_e32 v8, v11, v11
	v_fmac_f32_e32 v5, v4, v4
	v_mul_f32_e32 v4, v7, v7
	v_fmac_f32_e32 v16, v18, v18
	v_fmac_f32_e32 v12, v14, v14
	v_fmac_f32_e32 v8, v10, v10
	v_fmac_f32_e32 v4, v6, v6
	v_add_f32_e32 v16, v17, v16
	v_add_f32_e32 v12, v13, v12
	v_add_f32_e32 v8, v9, v8
	v_add_f32_e32 v4, v5, v4
	v_add_f32_e32 v12, v16, v12
	v_add_f32_e32 v4, v8, v4
	v_add_f32_e32 v4, v12, v4
	v_mov_b32_e32 v5, v4
	s_nop 1
	v_permlane16_swap_b32 v5, v4
	s_waitcnt lgkmcnt(0)
	v_add_f32_e32 v4, v4, v5
	v_mov_b32_e32 v5, v4
	s_nop 1
	v_permlane32_swap_b32 v5, v4
	s_and_saveexec_b64 s[22:23], s[14:15]
	s_cbranch_execz .LBB0_648
	s_waitcnt lgkmcnt(0)
	v_add_f32_e32 v4, v4, v5
	s_waitcnt vmcnt(0)
	v_add_f32_e32 v4, v144, v4
	v_fmamk_f32 v4, v4, 0x3c2aaaab, v231
	v_cmp_gt_f32_e32 vcc, s11, v4
	v_mul_f32_e32 v5, 0x4b800000, v4
	s_nop 0
	v_cndmask_b32_e32 v4, v4, v5, vcc
	v_rsq_f32_e32 v4, v4
	s_nop 0
	v_mul_f32_e32 v5, 0x45800000, v4
	v_cndmask_b32_e32 v8, v4, v5, vcc
	v_mad_u64_u32 v[4:5], s[0:1], v143, 48, s[0:1]
	v_mov_b32_e32 v6, v5
	v_mad_u64_u32 v[6:7], s[0:1], v142, 48, v[6:7]
	v_add_co_u32_e32 v4, vcc, 0x2000, v4
	s_nop 1
	v_addc_co_u32_e32 v5, vcc, 0, v6, vcc
	global_store_dword v[4:5], v8, off offset:256
	s_branch .LBB0_648

.LBB0_769:
	s_add_u32 s0, s8, 0x100
	s_addc_u32 s1, s9, 0
	s_cmp_eq_u32 s62, 2
	s_cselect_b32 s22, s42, s0
	s_cselect_b32 s23, s43, s1
	s_cselect_b32 s18, s44, s47
	s_cselect_b32 s19, s45, s49
	s_add_u32 s20, s22, 0x80
	s_addc_u32 s21, s23, 0
	s_add_i32 s64, 0, 0x10000
	v_add_u32_e32 v144, s64, v1
	ds_read_b128 v[132:135], v144
	ds_read_b128 v[136:139], v144 offset:1024
	ds_read_b128 v[140:143], v144 offset:2048
	ds_read_b128 v[144:147], v144 offset:3072
	s_add_u32 s8, s8, 0x18080
	s_addc_u32 s9, s9, 0
	ds_read_b128 v[152:155], v3
	ds_read_b128 v[156:159], v3 offset:1024
	ds_read_b128 v[160:163], v3 offset:2048
	ds_read_b128 v[164:167], v3 offset:3072
	ds_read_b128 v[168:171], v3 offset:4096
	ds_read_b128 v[172:175], v3 offset:5120
	ds_read_b128 v[176:179], v3 offset:6144
	ds_read_b128 v[180:183], v3 offset:7168
	s_add_i32 m0, s57, 0xc000
	s_nop 0
	global_load_lds_dwordx4 v148, s[8:9]
	s_add_i32 m0, s57, 0xe000
	s_nop 0
	global_load_lds_dwordx4 v150, s[8:9]
	s_waitcnt lgkmcnt(8)
	s_barrier
	s_waitcnt lgkmcnt(0)
	s_setprio 1
	s_waitcnt lgkmcnt(0)
	v_mfma_f32_16x16x32_bf16 v[128:131], v[132:135], v[152:155], v[128:131]
	v_mfma_f32_16x16x32_bf16 v[124:127], v[140:143], v[152:155], v[124:127]
	v_mfma_f32_16x16x32_bf16 v[112:115], v[132:135], v[160:163], v[112:115]
	v_mfma_f32_16x16x32_bf16 v[108:111], v[140:143], v[160:163], v[108:111]
	v_mfma_f32_16x16x32_bf16 v[96:99], v[132:135], v[168:171], v[96:99]
	v_mfma_f32_16x16x32_bf16 v[92:95], v[140:143], v[168:171], v[92:95]
	v_mfma_f32_16x16x32_bf16 v[80:83], v[132:135], v[176:179], v[80:83]
	v_mfma_f32_16x16x32_bf16 v[76:79], v[140:143], v[176:179], v[76:79]
	v_mfma_f32_16x16x32_bf16 v[128:131], v[136:139], v[156:159], v[128:131]
	v_mfma_f32_16x16x32_bf16 v[124:127], v[144:147], v[156:159], v[124:127]
	v_mfma_f32_16x16x32_bf16 v[112:115], v[136:139], v[164:167], v[112:115]
	v_mfma_f32_16x16x32_bf16 v[108:111], v[144:147], v[164:167], v[108:111]
	v_mfma_f32_16x16x32_bf16 v[96:99], v[136:139], v[172:175], v[96:99]
	v_mfma_f32_16x16x32_bf16 v[92:95], v[144:147], v[172:175], v[92:95]
	v_mfma_f32_16x16x32_bf16 v[80:83], v[136:139], v[180:183], v[80:83]
	v_mfma_f32_16x16x32_bf16 v[76:79], v[144:147], v[180:183], v[76:79]
	s_setprio 0
	s_barrier
	s_add_i32 s65, 0, 0x14000
	v_add_u32_e32 v210, s65, v1
	s_mov_b64 s[8:9], s[18:19]
	s_add_i32 s64, s64, s56
	ds_read_b128 v[184:187], v210
	ds_read_b128 v[188:191], v210 offset:1024
	ds_read_b128 v[192:195], v210 offset:2048
	ds_read_b128 v[210:213], v210 offset:3072
	s_mov_b32 m0, s64
	s_nop 0
	global_load_lds_dwordx4 v148, s[8:9]
	s_add_i32 m0, s64, 0x2000
	s_nop 0
	global_load_lds_dwordx4 v150, s[8:9]
	s_barrier
	s_waitcnt lgkmcnt(0)
	s_setprio 1
	s_waitcnt lgkmcnt(0)
	v_mfma_f32_16x16x32_bf16 v[120:123], v[184:187], v[152:155], v[120:123]
	v_mfma_f32_16x16x32_bf16 v[116:119], v[192:195], v[152:155], v[116:119]
	v_mfma_f32_16x16x32_bf16 v[104:107], v[184:187], v[160:163], v[104:107]
	v_mfma_f32_16x16x32_bf16 v[100:103], v[192:195], v[160:163], v[100:103]
	v_mfma_f32_16x16x32_bf16 v[88:91], v[184:187], v[168:171], v[88:91]
	v_mfma_f32_16x16x32_bf16 v[84:87], v[192:195], v[168:171], v[84:87]
	v_mfma_f32_16x16x32_bf16 v[72:75], v[184:187], v[176:179], v[72:75]
	v_mfma_f32_16x16x32_bf16 v[68:71], v[192:195], v[176:179], v[68:71]
	v_mfma_f32_16x16x32_bf16 v[120:123], v[188:191], v[156:159], v[120:123]
	v_mfma_f32_16x16x32_bf16 v[116:119], v[210:213], v[156:159], v[116:119]
	v_mfma_f32_16x16x32_bf16 v[104:107], v[188:191], v[164:167], v[104:107]
	v_mfma_f32_16x16x32_bf16 v[100:103], v[210:213], v[164:167], v[100:103]
	v_mfma_f32_16x16x32_bf16 v[88:91], v[188:191], v[172:175], v[88:91]
	v_mfma_f32_16x16x32_bf16 v[84:87], v[210:213], v[172:175], v[84:87]
	v_mfma_f32_16x16x32_bf16 v[72:75], v[188:191], v[180:183], v[72:75]
	v_mfma_f32_16x16x32_bf16 v[68:71], v[210:213], v[180:183], v[68:71]
	s_setprio 0
	s_mov_b64 s[8:9], s[22:23]
	s_mov_b32 m0, s57
	s_barrier
	ds_read_b128 v[152:155], v3 offset:16384
	ds_read_b128 v[156:159], v3 offset:17408
	ds_read_b128 v[160:163], v3 offset:18432
	ds_read_b128 v[164:167], v3 offset:19456
	ds_read_b128 v[168:171], v3 offset:20480
	ds_read_b128 v[172:175], v3 offset:21504
	ds_read_b128 v[176:179], v3 offset:22528
	ds_read_b128 v[180:183], v3 offset:23552
	s_nop 0
	global_load_lds_dwordx4 v148, s[8:9]
	s_mov_b32 m0, s63
	s_nop 0
	global_load_lds_dwordx4 v150, s[8:9]
	s_barrier
	s_waitcnt lgkmcnt(0)
	s_setprio 1
	s_waitcnt lgkmcnt(0)
	v_mfma_f32_16x16x32_bf16 v[64:67], v[132:135], v[152:155], v[64:67]
	v_mfma_f32_16x16x32_bf16 v[60:63], v[140:143], v[152:155], v[60:63]
	v_mfma_f32_16x16x32_bf16 v[48:51], v[132:135], v[160:163], v[48:51]
	v_mfma_f32_16x16x32_bf16 v[44:47], v[140:143], v[160:163], v[44:47]
	v_mfma_f32_16x16x32_bf16 v[32:35], v[132:135], v[168:171], v[32:35]
	v_mfma_f32_16x16x32_bf16 v[28:31], v[140:143], v[168:171], v[28:31]
	v_mfma_f32_16x16x32_bf16 v[16:19], v[132:135], v[176:179], v[16:19]
	v_mfma_f32_16x16x32_bf16 v[12:15], v[140:143], v[176:179], v[12:15]
	v_mfma_f32_16x16x32_bf16 v[64:67], v[136:139], v[156:159], v[64:67]
	v_mfma_f32_16x16x32_bf16 v[60:63], v[144:147], v[156:159], v[60:63]
	v_mfma_f32_16x16x32_bf16 v[48:51], v[136:139], v[164:167], v[48:51]
	v_mfma_f32_16x16x32_bf16 v[44:47], v[144:147], v[164:167], v[44:47]
	v_mfma_f32_16x16x32_bf16 v[32:35], v[136:139], v[172:175], v[32:35]
	v_mfma_f32_16x16x32_bf16 v[28:31], v[144:147], v[172:175], v[28:31]
	v_mfma_f32_16x16x32_bf16 v[16:19], v[136:139], v[180:183], v[16:19]
	v_mfma_f32_16x16x32_bf16 v[12:15], v[144:147], v[180:183], v[12:15]
	s_setprio 0
	s_barrier
	s_add_u32 s8, s18, 0x18000
	s_addc_u32 s9, s19, 0
	s_add_i32 s64, s65, s56
	s_mov_b32 m0, s64
	s_nop 0
	global_load_lds_dwordx4 v148, s[8:9]
	s_add_i32 m0, s64, 0x2000
	s_nop 0
	global_load_lds_dwordx4 v150, s[8:9]
	s_waitcnt vmcnt(6)
	s_barrier
	s_setprio 1
	v_mfma_f32_16x16x32_bf16 v[56:59], v[184:187], v[152:155], v[56:59]
	v_mfma_f32_16x16x32_bf16 v[52:55], v[192:195], v[152:155], v[52:55]
	v_mfma_f32_16x16x32_bf16 v[40:43], v[184:187], v[160:163], v[40:43]
	v_mfma_f32_16x16x32_bf16 v[36:39], v[192:195], v[160:163], v[36:39]
	v_mfma_f32_16x16x32_bf16 v[24:27], v[184:187], v[168:171], v[24:27]
	v_mfma_f32_16x16x32_bf16 v[20:23], v[192:195], v[168:171], v[20:23]
	v_mfma_f32_16x16x32_bf16 v[8:11], v[184:187], v[176:179], v[8:11]
	v_mfma_f32_16x16x32_bf16 v[4:7], v[192:195], v[176:179], v[4:7]
	v_mfma_f32_16x16x32_bf16 v[56:59], v[188:191], v[156:159], v[56:59]
	v_mfma_f32_16x16x32_bf16 v[52:55], v[210:213], v[156:159], v[52:55]
	v_mfma_f32_16x16x32_bf16 v[40:43], v[188:191], v[164:167], v[40:43]
	v_mfma_f32_16x16x32_bf16 v[36:39], v[210:213], v[164:167], v[36:39]
	v_mfma_f32_16x16x32_bf16 v[24:27], v[188:191], v[172:175], v[24:27]
	v_mfma_f32_16x16x32_bf16 v[20:23], v[210:213], v[172:175], v[20:23]
	v_mfma_f32_16x16x32_bf16 v[8:11], v[188:191], v[180:183], v[8:11]
	v_mfma_f32_16x16x32_bf16 v[4:7], v[210:213], v[180:183], v[4:7]
	s_setprio 0
	s_add_i32 s64, 0, 0x18000
	v_add_u32_e32 v144, s64, v1
	s_barrier
	ds_read_b128 v[132:135], v144
	ds_read_b128 v[136:139], v144 offset:1024
	ds_read_b128 v[140:143], v144 offset:2048
	ds_read_b128 v[144:147], v144 offset:3072
	s_add_u32 s8, s22, 0x18000
	s_addc_u32 s9, s23, 0
	s_mov_b32 m0, s72
	ds_read_b128 v[152:155], v3 offset:32768
	ds_read_b128 v[156:159], v3 offset:33792
	ds_read_b128 v[160:163], v3 offset:34816
	ds_read_b128 v[164:167], v3 offset:35840
	ds_read_b128 v[168:171], v3 offset:36864
	ds_read_b128 v[172:175], v3 offset:37888
	ds_read_b128 v[176:179], v3 offset:38912
	ds_read_b128 v[180:183], v3 offset:39936
	s_nop 0
	global_load_lds_dwordx4 v148, s[8:9]
	s_mov_b32 m0, s73
	s_nop 0
	global_load_lds_dwordx4 v150, s[8:9]
	s_waitcnt lgkmcnt(8)
	s_barrier
	s_waitcnt lgkmcnt(0)
	s_setprio 1
	s_waitcnt lgkmcnt(0)
	v_mfma_f32_16x16x32_bf16 v[128:131], v[132:135], v[152:155], v[128:131]
	v_mfma_f32_16x16x32_bf16 v[124:127], v[140:143], v[152:155], v[124:127]
	v_mfma_f32_16x16x32_bf16 v[112:115], v[132:135], v[160:163], v[112:115]
	v_mfma_f32_16x16x32_bf16 v[108:111], v[140:143], v[160:163], v[108:111]
	v_mfma_f32_16x16x32_bf16 v[96:99], v[132:135], v[168:171], v[96:99]
	v_mfma_f32_16x16x32_bf16 v[92:95], v[140:143], v[168:171], v[92:95]
	v_mfma_f32_16x16x32_bf16 v[80:83], v[132:135], v[176:179], v[80:83]
	v_mfma_f32_16x16x32_bf16 v[76:79], v[140:143], v[176:179], v[76:79]
	v_mfma_f32_16x16x32_bf16 v[128:131], v[136:139], v[156:159], v[128:131]
	v_mfma_f32_16x16x32_bf16 v[124:127], v[144:147], v[156:159], v[124:127]
	v_mfma_f32_16x16x32_bf16 v[112:115], v[136:139], v[164:167], v[112:115]
	v_mfma_f32_16x16x32_bf16 v[108:111], v[144:147], v[164:167], v[108:111]
	v_mfma_f32_16x16x32_bf16 v[96:99], v[136:139], v[172:175], v[96:99]
	v_mfma_f32_16x16x32_bf16 v[92:95], v[144:147], v[172:175], v[92:95]
	v_mfma_f32_16x16x32_bf16 v[80:83], v[136:139], v[180:183], v[80:83]
	v_mfma_f32_16x16x32_bf16 v[76:79], v[144:147], v[180:183], v[76:79]
	s_setprio 0
	s_barrier
	s_add_i32 s22, 0, 0x1c000
	s_add_u32 s8, s18, 0x80
	v_add_u32_e32 v210, s22, v1
	s_addc_u32 s9, s19, 0
	s_add_i32 s23, s64, s56
	ds_read_b128 v[184:187], v210
	ds_read_b128 v[188:191], v210 offset:1024
	ds_read_b128 v[192:195], v210 offset:2048
	ds_read_b128 v[210:213], v210 offset:3072
	s_mov_b32 m0, s23
	s_nop 0
	global_load_lds_dwordx4 v148, s[8:9]
	s_add_i32 m0, s23, 0x2000
	s_nop 0
	global_load_lds_dwordx4 v150, s[8:9]
	s_barrier
	s_waitcnt lgkmcnt(0)
	s_setprio 1
	s_waitcnt lgkmcnt(0)
	v_mfma_f32_16x16x32_bf16 v[120:123], v[184:187], v[152:155], v[120:123]
	v_mfma_f32_16x16x32_bf16 v[116:119], v[192:195], v[152:155], v[116:119]
	v_mfma_f32_16x16x32_bf16 v[104:107], v[184:187], v[160:163], v[104:107]
	v_mfma_f32_16x16x32_bf16 v[100:103], v[192:195], v[160:163], v[100:103]
	v_mfma_f32_16x16x32_bf16 v[88:91], v[184:187], v[168:171], v[88:91]
	v_mfma_f32_16x16x32_bf16 v[84:87], v[192:195], v[168:171], v[84:87]
	v_mfma_f32_16x16x32_bf16 v[72:75], v[184:187], v[176:179], v[72:75]
	v_mfma_f32_16x16x32_bf16 v[68:71], v[192:195], v[176:179], v[68:71]
	v_mfma_f32_16x16x32_bf16 v[120:123], v[188:191], v[156:159], v[120:123]
	v_mfma_f32_16x16x32_bf16 v[116:119], v[210:213], v[156:159], v[116:119]
	v_mfma_f32_16x16x32_bf16 v[104:107], v[188:191], v[164:167], v[104:107]
	v_mfma_f32_16x16x32_bf16 v[100:103], v[210:213], v[164:167], v[100:103]
	v_mfma_f32_16x16x32_bf16 v[88:91], v[188:191], v[172:175], v[88:91]
	v_mfma_f32_16x16x32_bf16 v[84:87], v[210:213], v[172:175], v[84:87]
	v_mfma_f32_16x16x32_bf16 v[72:75], v[188:191], v[180:183], v[72:75]
	v_mfma_f32_16x16x32_bf16 v[68:71], v[210:213], v[180:183], v[68:71]
	s_setprio 0
	s_mov_b32 m0, s68
	s_barrier
	ds_read_b128 v[152:155], v3 offset:49152
	ds_read_b128 v[156:159], v3 offset:50176
	ds_read_b128 v[160:163], v3 offset:51200
	ds_read_b128 v[164:167], v3 offset:52224
	ds_read_b128 v[168:171], v3 offset:53248
	ds_read_b128 v[172:175], v3 offset:54272
	ds_read_b128 v[176:179], v3 offset:55296
	ds_read_b128 v[180:183], v3 offset:56320
	s_nop 0
	global_load_lds_dwordx4 v148, s[20:21]
	s_mov_b32 m0, s74
	s_nop 0
	global_load_lds_dwordx4 v150, s[20:21]
	s_barrier
	s_waitcnt lgkmcnt(0)
	s_setprio 1
	s_waitcnt lgkmcnt(0)
	v_mfma_f32_16x16x32_bf16 v[64:67], v[132:135], v[152:155], v[64:67]
	v_mfma_f32_16x16x32_bf16 v[60:63], v[140:143], v[152:155], v[60:63]
	v_mfma_f32_16x16x32_bf16 v[48:51], v[132:135], v[160:163], v[48:51]
	v_mfma_f32_16x16x32_bf16 v[44:47], v[140:143], v[160:163], v[44:47]
	v_mfma_f32_16x16x32_bf16 v[32:35], v[132:135], v[168:171], v[32:35]
	v_mfma_f32_16x16x32_bf16 v[28:31], v[140:143], v[168:171], v[28:31]
	v_mfma_f32_16x16x32_bf16 v[16:19], v[132:135], v[176:179], v[16:19]
	v_mfma_f32_16x16x32_bf16 v[12:15], v[140:143], v[176:179], v[12:15]
	v_mfma_f32_16x16x32_bf16 v[64:67], v[136:139], v[156:159], v[64:67]
	v_mfma_f32_16x16x32_bf16 v[60:63], v[144:147], v[156:159], v[60:63]
	v_mfma_f32_16x16x32_bf16 v[48:51], v[136:139], v[164:167], v[48:51]
	v_mfma_f32_16x16x32_bf16 v[44:47], v[144:147], v[164:167], v[44:47]
	v_mfma_f32_16x16x32_bf16 v[32:35], v[136:139], v[172:175], v[32:35]
	v_mfma_f32_16x16x32_bf16 v[28:31], v[144:147], v[172:175], v[28:31]
	v_mfma_f32_16x16x32_bf16 v[16:19], v[136:139], v[180:183], v[16:19]
	v_mfma_f32_16x16x32_bf16 v[12:15], v[144:147], v[180:183], v[12:15]
	s_setprio 0
	s_barrier
	s_add_u32 s8, s18, 0x18080
	s_addc_u32 s9, s19, 0
	s_add_i32 s18, s22, s56
	s_mov_b32 m0, s18
	s_nop 0
	global_load_lds_dwordx4 v148, s[8:9]
	s_add_i32 m0, s18, 0x2000
	s_nop 0
	global_load_lds_dwordx4 v150, s[8:9]
	s_waitcnt vmcnt(6)
	s_barrier
	s_setprio 1
	v_mfma_f32_16x16x32_bf16 v[56:59], v[184:187], v[152:155], v[56:59]
	v_mfma_f32_16x16x32_bf16 v[52:55], v[192:195], v[152:155], v[52:55]
	v_mfma_f32_16x16x32_bf16 v[40:43], v[184:187], v[160:163], v[40:43]
	v_mfma_f32_16x16x32_bf16 v[36:39], v[192:195], v[160:163], v[36:39]
	v_mfma_f32_16x16x32_bf16 v[24:27], v[184:187], v[168:171], v[24:27]
	v_mfma_f32_16x16x32_bf16 v[20:23], v[192:195], v[168:171], v[20:23]
	v_mfma_f32_16x16x32_bf16 v[8:11], v[184:187], v[176:179], v[8:11]
	v_mfma_f32_16x16x32_bf16 v[4:7], v[192:195], v[176:179], v[4:7]
	v_mfma_f32_16x16x32_bf16 v[56:59], v[188:191], v[156:159], v[56:59]
	v_mfma_f32_16x16x32_bf16 v[52:55], v[210:213], v[156:159], v[52:55]
	v_mfma_f32_16x16x32_bf16 v[40:43], v[188:191], v[164:167], v[40:43]
	v_mfma_f32_16x16x32_bf16 v[36:39], v[210:213], v[164:167], v[36:39]
	v_mfma_f32_16x16x32_bf16 v[24:27], v[188:191], v[172:175], v[24:27]
	v_mfma_f32_16x16x32_bf16 v[20:23], v[210:213], v[172:175], v[20:23]
	v_mfma_f32_16x16x32_bf16 v[8:11], v[188:191], v[180:183], v[8:11]
	v_mfma_f32_16x16x32_bf16 v[4:7], v[210:213], v[180:183], v[4:7]
	s_setprio 0
	s_add_i32 s62, s62, 2
	s_add_u32 s47, s47, 0x100
	s_addc_u32 s49, s49, 0
	s_cmp_gt_u32 s62, 3
	s_mov_b64 s[8:9], s[0:1]
	s_barrier
	s_cbranch_scc0 .LBB0_769
	v_mov_b32_e32 v132, v0
	s_nop 0
	v_readfirstlane_b32 s0, v132
	s_lshr_b32 s1, s0, 6
	s_and_b32 s49, s1, 3
	s_cmp_eq_u32 s48, 4
	s_cselect_b64 s[8:9], -1, 0
	s_cmp_gt_u32 s49, 1
	s_cselect_b64 s[18:19], -1, 0
	s_and_b64 s[8:9], s[8:9], s[18:19]
	s_and_b64 vcc, exec, s[8:9]
	s_cbranch_vccnz .LBB0_757
	s_ashr_i32 s0, s0, 2
	s_lshl_b32 s1, s46, 8
	s_andn2_b32 s0, s0, 63
	s_add_i32 s0, s0, s1
	v_and_or_b32 v152, v132, 15, s0
	v_ashrrev_i32_e32 v153, 31, v152
	v_bfe_u32 v134, v132, 4, 2
	v_lshl_add_u64 v[132:133], v[152:153], 2, s[6:7]
	global_load_dword v135, v[132:133], off
	global_load_dword v178, v[132:133], off offset:64
	global_load_dword v177, v[132:133], off offset:128
	global_load_dword v176, v[132:133], off offset:192
	global_load_dword v175, v[132:133], off offset:512
	global_load_dword v174, v[132:133], off offset:576
	global_load_dword v173, v[132:133], off offset:640
	global_load_dword v172, v[132:133], off offset:704
	s_cmp_gt_i32 s48, 2
	s_cselect_b64 s[0:1], -1, 0
	v_lshlrev_b32_e32 v179, 3, v134
	s_lshl_b32 s8, s48, 3
	s_lshl_b32 s9, s49, 1
	s_or_b32 s8, s8, s9
	s_sub_i32 s46, s8, 24
	v_cmp_eq_u32_e64 s[18:19], 0, v134
	v_cmp_ne_u32_e64 s[20:21], 0, v134
	s_mov_b64 s[8:9], -1
	v_lshlrev_b32_e32 v154, 2, v179
	s_waitcnt vmcnt(0)
	v_fmamk_f32 v132, v135, 0x3b2aaaab, v231
	v_cmp_gt_f32_e32 vcc, s11, v132
	v_mul_f32_e32 v133, 0x4b800000, v132
	s_nop 0
	v_cndmask_b32_e32 v132, v132, v133, vcc
	v_rsq_f32_e32 v132, v132
	s_nop 0
	v_mul_f32_e32 v133, 0x45800000, v132
	v_cndmask_b32_e32 v158, v132, v133, vcc
	v_and_b32_e32 v132, 8, v179
	v_mov_b32_e32 v159, v158
	s_and_b64 vcc, exec, s[0:1]
	v_lshlrev_b32_e32 v156, 2, v132
	v_pk_mul_f32 v[128:129], v[128:129], v[158:159]
	v_pk_mul_f32 v[124:125], v[124:125], v[158:159]
	s_cbranch_vccz .LBB0_781
	v_and_b32_e32 v133, 64, v236
	v_xor_b32_e32 v132, 32, v236
	v_add_u32_e32 v133, 64, v133
	v_cmp_lt_i32_e32 vcc, v132, v133
	v_mov_b32_e32 v162, v158
	v_mov_b32_e32 v163, v158
	v_cndmask_b32_e32 v132, v236, v132, vcc
	v_pk_mul_f32 v[160:161], v[130:131], v[162:163]
	v_lshlrev_b32_e32 v170, 2, v132
	v_mul_f32_e32 v132, v129, v129
	v_mul_f32_e32 v133, v161, v161
	v_fmac_f32_e32 v132, v128, v128
	v_fmac_f32_e32 v133, v160, v160
	v_add_f32_e32 v155, v132, v133
	global_load_dwordx4 v[136:139], v154, s[40:41] offset:272
	global_load_dwordx4 v[144:147], v154, s[40:41] offset:256
	global_load_dwordx4 v[132:135], v156, s[26:27] offset:16
	global_load_dwordx4 v[140:143], v156, s[26:27]
	v_pk_mul_f32 v[162:163], v[126:127], v[162:163]
	v_mul_f32_e32 v157, v125, v125
	v_mul_f32_e32 v164, v163, v163
	v_fmac_f32_e32 v157, v124, v124
	v_fmac_f32_e32 v164, v162, v162
	v_add_f32_e32 v157, v157, v164
	v_add_f32_e32 v155, v155, v157
	v_mov_b32_e32 v157, v155
	s_nop 1
	v_permlane16_swap_b32 v157, v155
	s_waitcnt lgkmcnt(0)
	v_add_f32_e32 v155, v155, v157
	v_mov_b32_e32 v157, v155
	s_nop 1
	v_permlane32_swap_b32 v157, v155
	s_and_saveexec_b64 s[8:9], s[20:21]
	s_xor_b64 s[8:9], exec, s[8:9]
	s_ashr_i32 s47, s46, 31
	s_or_saveexec_b64 s[8:9], s[8:9]
	v_mov_b64_e32 v[164:165], s[46:47]
	s_xor_b64 exec, exec, s[8:9]
	s_cbranch_execz .LBB0_776
	s_ashr_i32 s47, s46, 31
	s_mul_i32 s22, s46, 0x10400
	s_mul_hi_i32 s23, s46, 0x10400
	s_add_u32 s22, s35, s22
	s_addc_u32 s23, s54, s23
	s_waitcnt lgkmcnt(0)
	v_add_f32_e32 v155, v155, v157
	v_lshl_add_u64 v[164:165], v[152:153], 2, s[22:23]
	global_atomic_add_f32 v[164:165], v155, off
	v_mov_b64_e32 v[164:165], s[46:47]
.LBB0_776:
	s_or_b64 exec, exec, s[8:9]
	s_waitcnt vmcnt(3)
	v_pk_mul_f32 v[138:139], v[162:163], v[138:139]
	v_pk_mul_f32 v[136:137], v[124:125], v[136:137]
	s_waitcnt vmcnt(1)
	v_pk_mul_f32 v[138:139], v[138:139], v[134:135]
	v_pk_mul_f32 v[134:135], v[136:137], v[132:133]
	v_mad_i64_i32 v[132:133], s[8:9], v152, 12, v[164:165]
	v_mov_b64_e32 v[136:137], s[28:29]
	v_mad_u64_u32 v[136:137], s[8:9], v132, s77, v[136:137]
	v_mov_b32_e32 v132, v137
	v_pk_mul_f32 v[146:147], v[160:161], v[146:147]
	v_pk_mul_f32 v[144:145], v[128:129], v[144:145]
	v_mad_u64_u32 v[132:133], s[8:9], v133, s77, v[132:133]
	s_waitcnt vmcnt(0)
	v_pk_mul_f32 v[142:143], v[146:147], v[142:143]
	v_pk_mul_f32 v[140:141], v[144:145], v[140:141]
	v_mov_b32_e32 v137, v132
	v_lshlrev_b32_e32 v160, 1, v179
	v_mov_b32_e32 v161, v2
	v_mov_b32_e32 v155, v2
	v_lshl_add_u64 v[136:137], v[136:137], 0, v[160:161]
	v_cvt_pk_bf16_f32 v132, v140, v141
	v_cvt_pk_bf16_f32 v133, v142, v143
	v_cvt_pk_bf16_f32 v134, v134, v135
	v_cvt_pk_bf16_f32 v135, v138, v139
	v_lshl_add_u64 v[166:167], s[40:41], 0, v[154:155]
	s_waitcnt lgkmcnt(0)
	v_mov_b32_e32 v157, v2
	global_store_dwordx4 v[136:137], v[132:135], off offset:128
	v_lshl_add_u64 v[168:169], s[26:27], 0, v[156:157]
	global_load_dwordx4 v[136:139], v[166:167], off offset:272
	global_load_dwordx4 v[144:147], v[166:167], off offset:256
	global_load_dwordx4 v[132:135], v[168:169], off offset:16
	global_load_dwordx4 v[140:143], v[168:169], off
	v_mov_b32_e32 v162, v158
	v_mov_b32_e32 v163, v158
	v_pk_mul_f32 v[166:167], v[122:123], v[162:163]
	v_pk_mul_f32 v[168:169], v[120:121], v[158:159]
	v_mul_f32_e32 v157, v167, v167
	v_mul_f32_e32 v155, v169, v169
	v_fmac_f32_e32 v155, v168, v168
	v_fmac_f32_e32 v157, v166, v166
	v_pk_mul_f32 v[164:165], v[118:119], v[162:163]
	v_pk_mul_f32 v[162:163], v[116:117], v[158:159]
	v_add_f32_e32 v155, v155, v157
	v_mul_f32_e32 v157, v163, v163
	v_mul_f32_e32 v161, v165, v165
	v_fmac_f32_e32 v157, v162, v162
	v_fmac_f32_e32 v161, v164, v164
	v_add_f32_e32 v157, v157, v161
	v_add_f32_e32 v155, v155, v157
	v_mov_b32_e32 v157, v155
	s_nop 1
	v_permlane16_swap_b32 v157, v155
	s_or_b32 s8, s46, 1
	s_waitcnt lgkmcnt(0)
	v_add_f32_e32 v155, v155, v157
	v_mov_b32_e32 v157, v155
	s_nop 1
	v_permlane32_swap_b32 v157, v155
	s_and_saveexec_b64 s[22:23], s[20:21]
	s_xor_b64 s[22:23], exec, s[22:23]
	s_ashr_i32 s9, s8, 31
	s_or_saveexec_b64 s[22:23], s[22:23]
	v_mov_b64_e32 v[170:171], s[8:9]
	s_xor_b64 exec, exec, s[22:23]
	s_cbranch_execz .LBB0_780
	s_ashr_i32 s9, s8, 31
	s_mul_i32 s62, s8, 0x10400
	s_mul_hi_i32 s47, s8, 0x10400
	s_add_u32 s64, s35, s62
	s_addc_u32 s65, s54, s47
	s_waitcnt lgkmcnt(0)
	v_add_f32_e32 v155, v155, v157
	v_lshl_add_u64 v[170:171], v[152:153], 2, s[64:65]
	global_atomic_add_f32 v[170:171], v155, off
	v_mov_b64_e32 v[170:171], s[8:9]

.LBB0_2213:
	s_add_u32 s15, s20, s24
	s_addc_u32 s30, s21, s25
	s_add_u32 s31, s15, 0x100
	s_addc_u32 s38, s30, 0
	s_and_b64 s[28:29], s[26:27], exec
	s_cselect_b32 s41, s9, s38
	s_cselect_b32 s40, s8, s31
	s_add_u32 s24, s16, s24
	s_addc_u32 s25, s17, s25
	s_add_u32 s28, s24, 0x100
	s_addc_u32 s29, s25, 0
	s_add_u32 s24, s40, 0x80
	s_addc_u32 s25, s41, 0
	s_add_i32 s79, 0, 0x10000
	s_and_b64 s[26:27], s[26:27], exec
	s_cselect_b32 s43, s1, s29
	s_cselect_b32 s42, s7, s28
	s_add_u32 s44, s15, 0x12080
	s_addc_u32 s45, s30, 0
	s_add_i32 s84, s79, s51
	s_add_i32 m0, s52, 0xc000
	s_add_i32 s85, s52, 0xe000
	s_add_i32 s83, 0, 0x14000
	s_add_i32 s82, s84, 0x2000
	s_add_u32 s38, s42, 0x10000
	s_addc_u32 s39, s43, 0
	s_add_i32 s80, s83, s51
	s_add_i32 s78, s80, 0x2000
	s_add_i32 s75, 0, 0x18000
	v_add_u32_e32 v152, s79, v1
	s_add_u32 s30, s40, 0x12000
	ds_read_b128 v[140:143], v152
	ds_read_b128 v[144:147], v152 offset:1024
	ds_read_b128 v[148:151], v152 offset:2048
	ds_read_b128 v[152:155], v152 offset:3072
	s_addc_u32 s31, s41, 0
	s_add_i32 s73, 0, 0x1c000
	s_add_u32 s28, s42, 0x80
	s_addc_u32 s29, s43, 0
	s_add_i32 s74, s75, s51
	s_add_i32 s15, s74, 0x2000
	s_add_u32 s26, s42, 0x10080
	s_addc_u32 s27, s43, 0
	s_add_i32 s81, s73, s51
	s_add_i32 s79, s81, 0x2000
	ds_read_b128 v[156:159], v3
	ds_read_b128 v[160:163], v3 offset:1024
	ds_read_b128 v[164:167], v3 offset:2048
	ds_read_b128 v[168:171], v3 offset:3072
	ds_read_b128 v[172:175], v3 offset:4096
	ds_read_b128 v[176:179], v3 offset:5120
	ds_read_b128 v[180:183], v3 offset:6144
	ds_read_b128 v[184:187], v3 offset:7168
	s_nop 0
	global_load_lds_dwordx4 v132, s[44:45]
	s_mov_b32 m0, s85
	s_nop 0
	global_load_lds_dwordx4 v136, s[44:45]
	s_waitcnt lgkmcnt(8)
	s_barrier
	s_waitcnt lgkmcnt(0)
	s_setprio 1
	s_waitcnt lgkmcnt(0)
	v_mfma_f32_16x16x32_bf16 v[128:131], v[140:143], v[156:159], v[128:131]
	v_mfma_f32_16x16x32_bf16 v[124:127], v[148:151], v[156:159], v[124:127]
	v_mfma_f32_16x16x32_bf16 v[112:115], v[140:143], v[164:167], v[112:115]
	v_mfma_f32_16x16x32_bf16 v[108:111], v[148:151], v[164:167], v[108:111]
	v_mfma_f32_16x16x32_bf16 v[96:99], v[140:143], v[172:175], v[96:99]
	v_mfma_f32_16x16x32_bf16 v[92:95], v[148:151], v[172:175], v[92:95]
	v_mfma_f32_16x16x32_bf16 v[80:83], v[140:143], v[180:183], v[80:83]
	v_mfma_f32_16x16x32_bf16 v[76:79], v[148:151], v[180:183], v[76:79]
	v_mfma_f32_16x16x32_bf16 v[128:131], v[144:147], v[160:163], v[128:131]
	v_mfma_f32_16x16x32_bf16 v[124:127], v[152:155], v[160:163], v[124:127]
	v_mfma_f32_16x16x32_bf16 v[112:115], v[144:147], v[168:171], v[112:115]
	v_mfma_f32_16x16x32_bf16 v[108:111], v[152:155], v[168:171], v[108:111]
	v_mfma_f32_16x16x32_bf16 v[96:99], v[144:147], v[176:179], v[96:99]
	v_mfma_f32_16x16x32_bf16 v[92:95], v[152:155], v[176:179], v[92:95]
	v_mfma_f32_16x16x32_bf16 v[80:83], v[144:147], v[184:187], v[80:83]
	v_mfma_f32_16x16x32_bf16 v[76:79], v[152:155], v[184:187], v[76:79]
	s_setprio 0
	s_barrier
	v_add_u32_e32 v214, s83, v1
	s_mov_b32 m0, s84
	ds_read_b128 v[188:191], v214
	ds_read_b128 v[192:195], v214 offset:1024
	ds_read_b128 v[210:213], v214 offset:2048
	ds_read_b128 v[214:217], v214 offset:3072
	s_nop 0
	global_load_lds_dwordx4 v134, s[42:43]
	s_mov_b32 m0, s82
	s_nop 0
	global_load_lds_dwordx4 v138, s[42:43]
	s_barrier
	s_waitcnt lgkmcnt(0)
	s_setprio 1
	s_waitcnt lgkmcnt(0)
	v_mfma_f32_16x16x32_bf16 v[120:123], v[188:191], v[156:159], v[120:123]
	v_mfma_f32_16x16x32_bf16 v[116:119], v[210:213], v[156:159], v[116:119]
	v_mfma_f32_16x16x32_bf16 v[104:107], v[188:191], v[164:167], v[104:107]
	v_mfma_f32_16x16x32_bf16 v[100:103], v[210:213], v[164:167], v[100:103]
	v_mfma_f32_16x16x32_bf16 v[88:91], v[188:191], v[172:175], v[88:91]
	v_mfma_f32_16x16x32_bf16 v[84:87], v[210:213], v[172:175], v[84:87]
	v_mfma_f32_16x16x32_bf16 v[72:75], v[188:191], v[180:183], v[72:75]
	v_mfma_f32_16x16x32_bf16 v[68:71], v[210:213], v[180:183], v[68:71]
	v_mfma_f32_16x16x32_bf16 v[120:123], v[192:195], v[160:163], v[120:123]
	v_mfma_f32_16x16x32_bf16 v[116:119], v[214:217], v[160:163], v[116:119]
	v_mfma_f32_16x16x32_bf16 v[104:107], v[192:195], v[168:171], v[104:107]
	v_mfma_f32_16x16x32_bf16 v[100:103], v[214:217], v[168:171], v[100:103]
	v_mfma_f32_16x16x32_bf16 v[88:91], v[192:195], v[176:179], v[88:91]
	v_mfma_f32_16x16x32_bf16 v[84:87], v[214:217], v[176:179], v[84:87]
	v_mfma_f32_16x16x32_bf16 v[72:75], v[192:195], v[184:187], v[72:75]
	v_mfma_f32_16x16x32_bf16 v[68:71], v[214:217], v[184:187], v[68:71]
	s_setprio 0
	s_mov_b32 m0, s52
	s_barrier
	ds_read_b128 v[156:159], v3 offset:16384
	ds_read_b128 v[160:163], v3 offset:17408
	ds_read_b128 v[164:167], v3 offset:18432
	ds_read_b128 v[168:171], v3 offset:19456
	ds_read_b128 v[172:175], v3 offset:20480
	ds_read_b128 v[176:179], v3 offset:21504
	ds_read_b128 v[180:183], v3 offset:22528
	ds_read_b128 v[184:187], v3 offset:23552
	s_nop 0
	global_load_lds_dwordx4 v132, s[40:41]
	s_mov_b32 m0, s53
	s_nop 0
	global_load_lds_dwordx4 v136, s[40:41]
	s_barrier
	s_waitcnt lgkmcnt(0)
	s_setprio 1
	s_waitcnt lgkmcnt(0)
	v_mfma_f32_16x16x32_bf16 v[64:67], v[140:143], v[156:159], v[64:67]
	v_mfma_f32_16x16x32_bf16 v[60:63], v[148:151], v[156:159], v[60:63]
	v_mfma_f32_16x16x32_bf16 v[48:51], v[140:143], v[164:167], v[48:51]
	v_mfma_f32_16x16x32_bf16 v[44:47], v[148:151], v[164:167], v[44:47]
	v_mfma_f32_16x16x32_bf16 v[32:35], v[140:143], v[172:175], v[32:35]
	v_mfma_f32_16x16x32_bf16 v[28:31], v[148:151], v[172:175], v[28:31]
	v_mfma_f32_16x16x32_bf16 v[16:19], v[140:143], v[180:183], v[16:19]
	v_mfma_f32_16x16x32_bf16 v[12:15], v[148:151], v[180:183], v[12:15]
	v_mfma_f32_16x16x32_bf16 v[64:67], v[144:147], v[160:163], v[64:67]
	v_mfma_f32_16x16x32_bf16 v[60:63], v[152:155], v[160:163], v[60:63]
	v_mfma_f32_16x16x32_bf16 v[48:51], v[144:147], v[168:171], v[48:51]
	v_mfma_f32_16x16x32_bf16 v[44:47], v[152:155], v[168:171], v[44:47]
	v_mfma_f32_16x16x32_bf16 v[32:35], v[144:147], v[176:179], v[32:35]
	v_mfma_f32_16x16x32_bf16 v[28:31], v[152:155], v[176:179], v[28:31]
	v_mfma_f32_16x16x32_bf16 v[16:19], v[144:147], v[184:187], v[16:19]
	v_mfma_f32_16x16x32_bf16 v[12:15], v[152:155], v[184:187], v[12:15]
	s_setprio 0
	s_barrier
	s_mov_b32 m0, s80
	s_nop 0
	global_load_lds_dwordx4 v134, s[38:39]
	s_mov_b32 m0, s78
	s_nop 0
	global_load_lds_dwordx4 v138, s[38:39]
	s_waitcnt vmcnt(6)
	s_barrier
	s_setprio 1
	v_mfma_f32_16x16x32_bf16 v[56:59], v[188:191], v[156:159], v[56:59]
	v_mfma_f32_16x16x32_bf16 v[52:55], v[210:213], v[156:159], v[52:55]
	v_mfma_f32_16x16x32_bf16 v[40:43], v[188:191], v[164:167], v[40:43]
	v_mfma_f32_16x16x32_bf16 v[36:39], v[210:213], v[164:167], v[36:39]
	v_mfma_f32_16x16x32_bf16 v[24:27], v[188:191], v[172:175], v[24:27]
	v_mfma_f32_16x16x32_bf16 v[20:23], v[210:213], v[172:175], v[20:23]
	v_mfma_f32_16x16x32_bf16 v[8:11], v[188:191], v[180:183], v[8:11]
	v_mfma_f32_16x16x32_bf16 v[4:7], v[210:213], v[180:183], v[4:7]
	v_mfma_f32_16x16x32_bf16 v[56:59], v[192:195], v[160:163], v[56:59]
	v_mfma_f32_16x16x32_bf16 v[52:55], v[214:217], v[160:163], v[52:55]
	v_mfma_f32_16x16x32_bf16 v[40:43], v[192:195], v[168:171], v[40:43]
	v_mfma_f32_16x16x32_bf16 v[36:39], v[214:217], v[168:171], v[36:39]
	v_mfma_f32_16x16x32_bf16 v[24:27], v[192:195], v[176:179], v[24:27]
	v_mfma_f32_16x16x32_bf16 v[20:23], v[214:217], v[176:179], v[20:23]
	v_mfma_f32_16x16x32_bf16 v[8:11], v[192:195], v[184:187], v[8:11]
	v_mfma_f32_16x16x32_bf16 v[4:7], v[214:217], v[184:187], v[4:7]
	s_setprio 0
	v_add_u32_e32 v152, s75, v1
	s_barrier
	ds_read_b128 v[140:143], v152
	ds_read_b128 v[144:147], v152 offset:1024
	ds_read_b128 v[148:151], v152 offset:2048
	ds_read_b128 v[152:155], v152 offset:3072
	s_mov_b32 m0, s54
	ds_read_b128 v[156:159], v3 offset:32768
	ds_read_b128 v[160:163], v3 offset:33792
	ds_read_b128 v[164:167], v3 offset:34816
	ds_read_b128 v[168:171], v3 offset:35840
	ds_read_b128 v[172:175], v3 offset:36864
	ds_read_b128 v[176:179], v3 offset:37888
	ds_read_b128 v[180:183], v3 offset:38912
	ds_read_b128 v[184:187], v3 offset:39936
	s_nop 0
	global_load_lds_dwordx4 v132, s[30:31]
	s_mov_b32 m0, s55
	s_nop 0
	global_load_lds_dwordx4 v136, s[30:31]
	s_waitcnt lgkmcnt(8)
	s_barrier
	s_waitcnt lgkmcnt(0)
	s_setprio 1
	s_waitcnt lgkmcnt(0)
	v_mfma_f32_16x16x32_bf16 v[128:131], v[140:143], v[156:159], v[128:131]
	v_mfma_f32_16x16x32_bf16 v[124:127], v[148:151], v[156:159], v[124:127]
	v_mfma_f32_16x16x32_bf16 v[112:115], v[140:143], v[164:167], v[112:115]
	v_mfma_f32_16x16x32_bf16 v[108:111], v[148:151], v[164:167], v[108:111]
	v_mfma_f32_16x16x32_bf16 v[96:99], v[140:143], v[172:175], v[96:99]
	v_mfma_f32_16x16x32_bf16 v[92:95], v[148:151], v[172:175], v[92:95]
	v_mfma_f32_16x16x32_bf16 v[80:83], v[140:143], v[180:183], v[80:83]
	v_mfma_f32_16x16x32_bf16 v[76:79], v[148:151], v[180:183], v[76:79]
	v_mfma_f32_16x16x32_bf16 v[128:131], v[144:147], v[160:163], v[128:131]
	v_mfma_f32_16x16x32_bf16 v[124:127], v[152:155], v[160:163], v[124:127]
	v_mfma_f32_16x16x32_bf16 v[112:115], v[144:147], v[168:171], v[112:115]
	v_mfma_f32_16x16x32_bf16 v[108:111], v[152:155], v[168:171], v[108:111]
	v_mfma_f32_16x16x32_bf16 v[96:99], v[144:147], v[176:179], v[96:99]
	v_mfma_f32_16x16x32_bf16 v[92:95], v[152:155], v[176:179], v[92:95]
	v_mfma_f32_16x16x32_bf16 v[80:83], v[144:147], v[184:187], v[80:83]
	v_mfma_f32_16x16x32_bf16 v[76:79], v[152:155], v[184:187], v[76:79]
	s_setprio 0
	s_barrier
	v_add_u32_e32 v214, s73, v1
	s_mov_b32 m0, s74
	ds_read_b128 v[188:191], v214
	ds_read_b128 v[192:195], v214 offset:1024
	ds_read_b128 v[210:213], v214 offset:2048
	ds_read_b128 v[214:217], v214 offset:3072
	s_nop 0
	global_load_lds_dwordx4 v134, s[28:29]
	s_mov_b32 m0, s15
	s_nop 0
	global_load_lds_dwordx4 v138, s[28:29]
	s_barrier
	s_waitcnt lgkmcnt(0)
	s_setprio 1
	s_waitcnt lgkmcnt(0)
	v_mfma_f32_16x16x32_bf16 v[120:123], v[188:191], v[156:159], v[120:123]
	v_mfma_f32_16x16x32_bf16 v[116:119], v[210:213], v[156:159], v[116:119]
	v_mfma_f32_16x16x32_bf16 v[104:107], v[188:191], v[164:167], v[104:107]
	v_mfma_f32_16x16x32_bf16 v[100:103], v[210:213], v[164:167], v[100:103]
	v_mfma_f32_16x16x32_bf16 v[88:91], v[188:191], v[172:175], v[88:91]
	v_mfma_f32_16x16x32_bf16 v[84:87], v[210:213], v[172:175], v[84:87]
	v_mfma_f32_16x16x32_bf16 v[72:75], v[188:191], v[180:183], v[72:75]
	v_mfma_f32_16x16x32_bf16 v[68:71], v[210:213], v[180:183], v[68:71]
	v_mfma_f32_16x16x32_bf16 v[120:123], v[192:195], v[160:163], v[120:123]
	v_mfma_f32_16x16x32_bf16 v[116:119], v[214:217], v[160:163], v[116:119]
	v_mfma_f32_16x16x32_bf16 v[104:107], v[192:195], v[168:171], v[104:107]
	v_mfma_f32_16x16x32_bf16 v[100:103], v[214:217], v[168:171], v[100:103]
	v_mfma_f32_16x16x32_bf16 v[88:91], v[192:195], v[176:179], v[88:91]
	v_mfma_f32_16x16x32_bf16 v[84:87], v[214:217], v[176:179], v[84:87]
	v_mfma_f32_16x16x32_bf16 v[72:75], v[192:195], v[184:187], v[72:75]
	v_mfma_f32_16x16x32_bf16 v[68:71], v[214:217], v[184:187], v[68:71]
	s_setprio 0
	s_mov_b32 m0, s64
	s_barrier
	ds_read_b128 v[156:159], v3 offset:49152
	ds_read_b128 v[160:163], v3 offset:50176
	ds_read_b128 v[164:167], v3 offset:51200
	ds_read_b128 v[168:171], v3 offset:52224
	ds_read_b128 v[172:175], v3 offset:53248
	ds_read_b128 v[176:179], v3 offset:54272
	ds_read_b128 v[180:183], v3 offset:55296
	ds_read_b128 v[184:187], v3 offset:56320
	s_nop 0
	global_load_lds_dwordx4 v132, s[24:25]
	s_mov_b32 m0, s65
	s_nop 0
	global_load_lds_dwordx4 v136, s[24:25]
	s_barrier
	s_waitcnt lgkmcnt(0)
	s_setprio 1
	s_waitcnt lgkmcnt(0)
	v_mfma_f32_16x16x32_bf16 v[64:67], v[140:143], v[156:159], v[64:67]
	v_mfma_f32_16x16x32_bf16 v[60:63], v[148:151], v[156:159], v[60:63]
	v_mfma_f32_16x16x32_bf16 v[48:51], v[140:143], v[164:167], v[48:51]
	v_mfma_f32_16x16x32_bf16 v[44:47], v[148:151], v[164:167], v[44:47]
	v_mfma_f32_16x16x32_bf16 v[32:35], v[140:143], v[172:175], v[32:35]
	v_mfma_f32_16x16x32_bf16 v[28:31], v[148:151], v[172:175], v[28:31]
	v_mfma_f32_16x16x32_bf16 v[16:19], v[140:143], v[180:183], v[16:19]
	v_mfma_f32_16x16x32_bf16 v[12:15], v[148:151], v[180:183], v[12:15]
	v_mfma_f32_16x16x32_bf16 v[64:67], v[144:147], v[160:163], v[64:67]
	v_mfma_f32_16x16x32_bf16 v[60:63], v[152:155], v[160:163], v[60:63]
	v_mfma_f32_16x16x32_bf16 v[48:51], v[144:147], v[168:171], v[48:51]
	v_mfma_f32_16x16x32_bf16 v[44:47], v[152:155], v[168:171], v[44:47]
	v_mfma_f32_16x16x32_bf16 v[32:35], v[144:147], v[176:179], v[32:35]
	v_mfma_f32_16x16x32_bf16 v[28:31], v[152:155], v[176:179], v[28:31]
	v_mfma_f32_16x16x32_bf16 v[16:19], v[144:147], v[184:187], v[16:19]
	v_mfma_f32_16x16x32_bf16 v[12:15], v[152:155], v[184:187], v[12:15]
	s_setprio 0
	s_barrier
	s_mov_b32 m0, s81
	s_nop 0
	global_load_lds_dwordx4 v134, s[26:27]
	s_mov_b32 m0, s79
	s_nop 0
	global_load_lds_dwordx4 v138, s[26:27]
	s_waitcnt vmcnt(6)
	s_barrier
	s_setprio 1
	v_mfma_f32_16x16x32_bf16 v[56:59], v[188:191], v[156:159], v[56:59]
	v_mfma_f32_16x16x32_bf16 v[52:55], v[210:213], v[156:159], v[52:55]
	v_mfma_f32_16x16x32_bf16 v[40:43], v[188:191], v[164:167], v[40:43]
	v_mfma_f32_16x16x32_bf16 v[36:39], v[210:213], v[164:167], v[36:39]
	v_mfma_f32_16x16x32_bf16 v[24:27], v[188:191], v[172:175], v[24:27]
	v_mfma_f32_16x16x32_bf16 v[20:23], v[210:213], v[172:175], v[20:23]
	v_mfma_f32_16x16x32_bf16 v[8:11], v[188:191], v[180:183], v[8:11]
	v_mfma_f32_16x16x32_bf16 v[4:7], v[210:213], v[180:183], v[4:7]
	v_mfma_f32_16x16x32_bf16 v[56:59], v[192:195], v[160:163], v[56:59]
	v_mfma_f32_16x16x32_bf16 v[52:55], v[214:217], v[160:163], v[52:55]
	v_mfma_f32_16x16x32_bf16 v[40:43], v[192:195], v[168:171], v[40:43]
	v_mfma_f32_16x16x32_bf16 v[36:39], v[214:217], v[168:171], v[36:39]
	v_mfma_f32_16x16x32_bf16 v[24:27], v[192:195], v[176:179], v[24:27]
	v_mfma_f32_16x16x32_bf16 v[20:23], v[214:217], v[176:179], v[20:23]
	v_mfma_f32_16x16x32_bf16 v[8:11], v[192:195], v[184:187], v[8:11]
	v_mfma_f32_16x16x32_bf16 v[4:7], v[214:217], v[184:187], v[4:7]
	s_setprio 0
	s_andn2_b64 vcc, exec, s[22:23]
	s_mov_b64 s[26:27], -1
	s_mov_b64 s[22:23], 0
	s_mov_b64 s[24:25], 0x100
	s_barrier
	s_cbranch_vccz .LBB0_2213
	v_mov_b32_e32 v141, v0
	s_ashr_i32 s15, s14, 31
	v_readfirstlane_b32 s1, v141
	s_bfe_u32 s7, s1, 0x20006
	s_ashr_i32 s1, s1, 2
	s_and_b32 s16, s1, 0xffffffc0
	s_ashr_i32 s17, s16, 31
	s_lshl_b64 s[20:21], s[14:15], 10
	s_add_u32 s1, s56, s20
	s_addc_u32 s22, s57, s21
	s_lshl_b64 s[20:21], s[16:17], 2
	v_and_b32_e32 v142, 15, v141
	s_add_u32 s20, s1, s20
	s_addc_u32 s21, s22, s21
	v_lshlrev_b32_e32 v140, 2, v142
	global_load_dword v150, v140, s[20:21] offset:64
	global_load_dword v149, v140, s[20:21] offset:128
	global_load_dword v148, v140, s[20:21] offset:192
	global_load_dword v147, v140, s[20:21] offset:512
	global_load_dword v146, v140, s[20:21] offset:576
	global_load_dword v145, v140, s[20:21] offset:640
	global_load_dword v144, v140, s[20:21] offset:704
	v_mul_f32_e32 v129, v129, v129
	v_mul_f32_e32 v125, v125, v125
	v_mul_f32_e32 v121, v121, v121
	v_mul_f32_e32 v117, v117, v117
	v_fmac_f32_e32 v129, v128, v128
	v_mul_f32_e32 v128, v131, v131
	v_fmac_f32_e32 v125, v124, v124
	v_mul_f32_e32 v124, v127, v127
	v_fmac_f32_e32 v121, v120, v120
	v_mul_f32_e32 v120, v123, v123
	v_fmac_f32_e32 v117, v116, v116
	v_mul_f32_e32 v116, v119, v119
	v_fmac_f32_e32 v128, v130, v130
	v_fmac_f32_e32 v124, v126, v126
	v_fmac_f32_e32 v120, v122, v122
	v_fmac_f32_e32 v116, v118, v118
	v_add_f32_e32 v128, v129, v128
	v_add_f32_e32 v124, v125, v124
	v_add_f32_e32 v120, v121, v120
	v_add_f32_e32 v116, v117, v116
	v_add_f32_e32 v124, v128, v124
	v_add_f32_e32 v116, v120, v116
	v_add_f32_e32 v117, v124, v116
	v_mov_b32_e32 v118, v117
	s_nop 1
	v_permlane16_swap_b32 v118, v117
	v_and_b32_e32 v152, 64, v236
	v_xor_b32_e32 v151, 32, v236
	v_add_u32_e32 v152, 64, v152
	v_cmp_lt_i32_e32 vcc, v151, v152
	s_lshl_b32 s0, s0, 2
	s_or_b32 s0, s7, s0
	v_cndmask_b32_e32 v116, v236, v151, vcc
	s_lshl_b64 s[14:15], s[14:15], 8
	v_lshlrev_b32_e32 v116, 2, v116
	s_waitcnt lgkmcnt(0)
	v_add_f32_e32 v117, v117, v118
	s_add_u32 s1, s14, s16
	v_mov_b32_e32 v118, v117
	s_nop 1
	v_permlane32_swap_b32 v118, v117
	s_addc_u32 s7, s15, s17
	v_or_b32_e32 v143, s1, v142
	s_ashr_i32 s1, s0, 31
	s_lshl_b64 s[0:1], s[0:1], 2
	v_and_b32_e32 v119, 48, v141
	s_add_u32 s0, s62, s0
	v_mov_b32_e32 v142, s7
	v_cmp_eq_u32_e64 s[16:17], 0, v119
	s_addc_u32 s1, s63, s1
	s_and_saveexec_b64 s[14:15], s[16:17]
	s_cbranch_execz .LBB0_2216
	v_mov_b32_e32 v141, v2
	v_lshl_add_u64 v[120:121], s[20:21], 0, v[140:141]
	global_load_dword v119, v[120:121], off
	s_waitcnt lgkmcnt(0)
	v_add_f32_e32 v117, v117, v118
	s_waitcnt vmcnt(0)
	v_add_f32_e32 v117, v117, v119
	v_fmamk_f32 v117, v117, 0x3c2aaaab, v231
	v_cmp_gt_f32_e32 vcc, s11, v117
	v_mul_f32_e32 v118, 0x4b800000, v117
	s_nop 0
	v_cndmask_b32_e32 v117, v117, v118, vcc
	v_rsq_f32_e32 v117, v117
	s_nop 0
	v_mul_f32_e32 v118, 0x45800000, v117
	v_cndmask_b32_e32 v117, v117, v118, vcc
	v_mad_u64_u32 v[118:119], s[20:21], v143, 48, s[0:1]
	v_mov_b32_e32 v120, v119
	v_mad_u64_u32 v[120:121], s[20:21], v142, 48, v[120:121]
	v_mov_b32_e32 v119, v120
	global_store_dword v[118:119], v117, off
.LBB0_2216:
	s_or_b64 exec, exec, s[14:15]
	v_mul_f32_e32 v113, v113, v113
	v_mul_f32_e32 v109, v109, v109
	v_mul_f32_e32 v105, v105, v105
	v_mul_f32_e32 v101, v101, v101
	v_fmac_f32_e32 v113, v112, v112
	v_mul_f32_e32 v112, v115, v115
	v_fmac_f32_e32 v109, v108, v108
	v_mul_f32_e32 v108, v111, v111
	v_fmac_f32_e32 v105, v104, v104
	v_mul_f32_e32 v104, v107, v107
	v_fmac_f32_e32 v101, v100, v100
	v_mul_f32_e32 v100, v103, v103
	v_fmac_f32_e32 v112, v114, v114
	v_fmac_f32_e32 v108, v110, v110
	v_fmac_f32_e32 v104, v106, v106
	v_fmac_f32_e32 v100, v102, v102
	v_add_f32_e32 v112, v113, v112
	v_add_f32_e32 v108, v109, v108
	v_add_f32_e32 v104, v105, v104
	v_add_f32_e32 v100, v101, v100
	v_add_f32_e32 v108, v112, v108
	v_add_f32_e32 v100, v104, v100
	v_add_f32_e32 v100, v108, v100
	v_mov_b32_e32 v101, v100
	s_nop 1
	v_permlane16_swap_b32 v101, v100
	s_waitcnt lgkmcnt(0)
	v_add_f32_e32 v100, v100, v101
	v_mov_b32_e32 v101, v100
	s_nop 1
	v_permlane32_swap_b32 v101, v100
	s_and_saveexec_b64 s[14:15], s[16:17]
	s_cbranch_execz .LBB0_2218
	s_waitcnt lgkmcnt(0)
	v_add_f32_e32 v100, v100, v101
	s_waitcnt vmcnt(0)
	v_add_f32_e32 v100, v150, v100
	v_fmamk_f32 v100, v100, 0x3c2aaaab, v231
	v_cmp_gt_f32_e32 vcc, s11, v100
	v_mul_f32_e32 v101, 0x4b800000, v100
	s_nop 0
	v_cndmask_b32_e32 v100, v100, v101, vcc
	v_rsq_f32_e32 v100, v100
	s_nop 0
	v_mul_f32_e32 v101, 0x45800000, v100
	v_cndmask_b32_e32 v104, v100, v101, vcc
	v_mad_u64_u32 v[100:101], s[20:21], v143, 48, s[0:1]
	v_mov_b32_e32 v102, v101
	v_mad_u64_u32 v[102:103], s[20:21], v142, 48, v[102:103]
	v_mov_b32_e32 v101, v102
	global_store_dword v[100:101], v104, off offset:768
.LBB0_2218:
	s_or_b64 exec, exec, s[14:15]
	v_mul_f32_e32 v97, v97, v97
	v_mul_f32_e32 v93, v93, v93
	v_mul_f32_e32 v89, v89, v89
	v_mul_f32_e32 v85, v85, v85
	v_fmac_f32_e32 v97, v96, v96
	v_mul_f32_e32 v96, v99, v99
	v_fmac_f32_e32 v93, v92, v92
	v_mul_f32_e32 v92, v95, v95
	v_fmac_f32_e32 v89, v88, v88
	v_mul_f32_e32 v88, v91, v91
	v_fmac_f32_e32 v85, v84, v84
	v_mul_f32_e32 v84, v87, v87
	v_fmac_f32_e32 v96, v98, v98
	v_fmac_f32_e32 v92, v94, v94
	v_fmac_f32_e32 v88, v90, v90
	v_fmac_f32_e32 v84, v86, v86
	v_add_f32_e32 v96, v97, v96
	v_add_f32_e32 v92, v93, v92
	v_add_f32_e32 v88, v89, v88
	v_add_f32_e32 v84, v85, v84
	v_add_f32_e32 v92, v96, v92
	v_add_f32_e32 v84, v88, v84
	v_add_f32_e32 v84, v92, v84
	v_mov_b32_e32 v85, v84
	s_nop 1
	v_permlane16_swap_b32 v85, v84
	s_waitcnt lgkmcnt(0)
	v_add_f32_e32 v84, v84, v85
	v_mov_b32_e32 v85, v84
	s_nop 1
	v_permlane32_swap_b32 v85, v84
	s_and_saveexec_b64 s[14:15], s[16:17]
	s_cbranch_execz .LBB0_2220
	s_waitcnt lgkmcnt(0)
	v_add_f32_e32 v84, v84, v85
	s_waitcnt vmcnt(0)
	v_add_f32_e32 v84, v149, v84
	v_fmamk_f32 v84, v84, 0x3c2aaaab, v231
	v_cmp_gt_f32_e32 vcc, s11, v84
	v_mul_f32_e32 v85, 0x4b800000, v84
	s_nop 0
	v_cndmask_b32_e32 v84, v84, v85, vcc
	v_rsq_f32_e32 v84, v84
	s_nop 0
	v_mul_f32_e32 v85, 0x45800000, v84
	v_cndmask_b32_e32 v88, v84, v85, vcc
	v_mad_u64_u32 v[84:85], s[20:21], v143, 48, s[0:1]
	v_mov_b32_e32 v86, v85
	v_mad_u64_u32 v[86:87], s[20:21], v142, 48, v[86:87]
	v_mov_b32_e32 v85, v86
	global_store_dword v[84:85], v88, off offset:1536
.LBB0_2220:
	s_or_b64 exec, exec, s[14:15]
	v_mul_f32_e32 v81, v81, v81
	v_mul_f32_e32 v77, v77, v77
	v_mul_f32_e32 v73, v73, v73
	v_mul_f32_e32 v69, v69, v69
	v_fmac_f32_e32 v81, v80, v80
	v_mul_f32_e32 v80, v83, v83
	v_fmac_f32_e32 v77, v76, v76
	v_mul_f32_e32 v76, v79, v79
	v_fmac_f32_e32 v73, v72, v72
	v_mul_f32_e32 v72, v75, v75
	v_fmac_f32_e32 v69, v68, v68
	v_mul_f32_e32 v68, v71, v71
	v_fmac_f32_e32 v80, v82, v82
	v_fmac_f32_e32 v76, v78, v78
	v_fmac_f32_e32 v72, v74, v74
	v_fmac_f32_e32 v68, v70, v70
	v_add_f32_e32 v80, v81, v80
	v_add_f32_e32 v76, v77, v76
	v_add_f32_e32 v72, v73, v72
	v_add_f32_e32 v68, v69, v68
	v_add_f32_e32 v76, v80, v76
	v_add_f32_e32 v68, v72, v68
	v_add_f32_e32 v68, v76, v68
	v_mov_b32_e32 v69, v68
	s_nop 1
	v_permlane16_swap_b32 v69, v68
	s_waitcnt lgkmcnt(0)
	v_add_f32_e32 v68, v68, v69
	v_mov_b32_e32 v69, v68
	s_nop 1
	v_permlane32_swap_b32 v69, v68
	s_and_saveexec_b64 s[14:15], s[16:17]
	s_cbranch_execz .LBB0_2222
	s_waitcnt lgkmcnt(0)
	v_add_f32_e32 v68, v68, v69
	s_waitcnt vmcnt(0)
	v_add_f32_e32 v68, v148, v68
	v_fmamk_f32 v68, v68, 0x3c2aaaab, v231
	v_cmp_gt_f32_e32 vcc, s11, v68
	v_mul_f32_e32 v69, 0x4b800000, v68
	s_nop 0
	v_cndmask_b32_e32 v68, v68, v69, vcc
	v_rsq_f32_e32 v68, v68
	s_nop 0
	v_mul_f32_e32 v69, 0x45800000, v68
	v_cndmask_b32_e32 v72, v68, v69, vcc
	v_mad_u64_u32 v[68:69], s[20:21], v143, 48, s[0:1]
	v_mov_b32_e32 v70, v69
	v_mad_u64_u32 v[70:71], s[20:21], v142, 48, v[70:71]
	v_mov_b32_e32 v69, v70
	global_store_dword v[68:69], v72, off offset:2304
.LBB0_2222:
	s_or_b64 exec, exec, s[14:15]
	v_mul_f32_e32 v65, v65, v65
	v_mul_f32_e32 v61, v61, v61
	v_mul_f32_e32 v57, v57, v57
	v_mul_f32_e32 v53, v53, v53
	v_fmac_f32_e32 v65, v64, v64
	v_mul_f32_e32 v64, v67, v67
	v_fmac_f32_e32 v61, v60, v60
	v_mul_f32_e32 v60, v63, v63
	v_fmac_f32_e32 v57, v56, v56
	v_mul_f32_e32 v56, v59, v59
	v_fmac_f32_e32 v53, v52, v52
	v_mul_f32_e32 v52, v55, v55
	v_fmac_f32_e32 v64, v66, v66
	v_fmac_f32_e32 v60, v62, v62
	v_fmac_f32_e32 v56, v58, v58
	v_fmac_f32_e32 v52, v54, v54
	v_add_f32_e32 v64, v65, v64
	v_add_f32_e32 v60, v61, v60
	v_add_f32_e32 v56, v57, v56
	v_add_f32_e32 v52, v53, v52
	v_add_f32_e32 v60, v64, v60
	v_add_f32_e32 v52, v56, v52
	v_add_f32_e32 v52, v60, v52
	v_mov_b32_e32 v53, v52
	s_nop 1
	v_permlane16_swap_b32 v53, v52
	s_waitcnt lgkmcnt(0)
	v_add_f32_e32 v52, v52, v53
	v_mov_b32_e32 v53, v52
	s_nop 1
	v_permlane32_swap_b32 v53, v52
	s_and_saveexec_b64 s[14:15], s[16:17]
	s_cbranch_execz .LBB0_2224
	s_waitcnt lgkmcnt(0)
	v_add_f32_e32 v52, v52, v53
	s_waitcnt vmcnt(0)
	v_add_f32_e32 v52, v147, v52
	v_fmamk_f32 v52, v52, 0x3c2aaaab, v231
	v_mul_f32_e32 v53, 0x4b800000, v52
	v_cmp_gt_f32_e32 vcc, s11, v52
	s_nop 1
	v_cndmask_b32_e32 v52, v52, v53, vcc
	v_rsq_f32_e32 v54, v52
	v_mad_u64_u32 v[52:53], s[20:21], v143, 48, s[0:1]
	v_mul_f32_e32 v55, 0x45800000, v54
	v_cndmask_b32_e32 v56, v54, v55, vcc
	v_mov_b32_e32 v54, v53
	v_mad_u64_u32 v[54:55], s[20:21], v142, 48, v[54:55]
	v_add_co_u32_e32 v52, vcc, 0x1000, v52
	s_nop 1
	v_addc_co_u32_e32 v53, vcc, 0, v54, vcc
	global_store_dword v[52:53], v56, off offset:2048
.LBB0_2224:
	s_or_b64 exec, exec, s[14:15]
	v_mul_f32_e32 v49, v49, v49
	v_mul_f32_e32 v45, v45, v45
	v_mul_f32_e32 v41, v41, v41
	v_mul_f32_e32 v37, v37, v37
	v_fmac_f32_e32 v49, v48, v48
	v_mul_f32_e32 v48, v51, v51
	v_fmac_f32_e32 v45, v44, v44
	v_mul_f32_e32 v44, v47, v47
	v_fmac_f32_e32 v41, v40, v40
	v_mul_f32_e32 v40, v43, v43
	v_fmac_f32_e32 v37, v36, v36
	v_mul_f32_e32 v36, v39, v39
	v_fmac_f32_e32 v48, v50, v50
	v_fmac_f32_e32 v44, v46, v46
	v_fmac_f32_e32 v40, v42, v42
	v_fmac_f32_e32 v36, v38, v38
	v_add_f32_e32 v48, v49, v48
	v_add_f32_e32 v44, v45, v44
	v_add_f32_e32 v40, v41, v40
	v_add_f32_e32 v36, v37, v36
	v_add_f32_e32 v44, v48, v44
	v_add_f32_e32 v36, v40, v36
	v_add_f32_e32 v36, v44, v36
	v_mov_b32_e32 v37, v36
	s_nop 1
	v_permlane16_swap_b32 v37, v36
	s_waitcnt lgkmcnt(0)
	v_add_f32_e32 v36, v36, v37
	v_mov_b32_e32 v37, v36
	s_nop 1
	v_permlane32_swap_b32 v37, v36
	s_and_saveexec_b64 s[14:15], s[16:17]
	s_cbranch_execz .LBB0_2226
	s_waitcnt lgkmcnt(0)
	v_add_f32_e32 v36, v36, v37
	s_waitcnt vmcnt(0)
	v_add_f32_e32 v36, v146, v36
	v_fmamk_f32 v36, v36, 0x3c2aaaab, v231
	v_mul_f32_e32 v37, 0x4b800000, v36
	v_cmp_gt_f32_e32 vcc, s11, v36
	s_nop 1
	v_cndmask_b32_e32 v36, v36, v37, vcc
	v_rsq_f32_e32 v38, v36
	v_mad_u64_u32 v[36:37], s[20:21], v143, 48, s[0:1]
	v_mul_f32_e32 v39, 0x45800000, v38
	v_cndmask_b32_e32 v40, v38, v39, vcc
	v_mov_b32_e32 v38, v37
	v_mad_u64_u32 v[38:39], s[20:21], v142, 48, v[38:39]
	v_add_co_u32_e32 v36, vcc, 0x1000, v36
	s_nop 1
	v_addc_co_u32_e32 v37, vcc, 0, v38, vcc
	global_store_dword v[36:37], v40, off offset:2816
.LBB0_2226:
	s_or_b64 exec, exec, s[14:15]
	v_mul_f32_e32 v33, v33, v33
	v_mul_f32_e32 v29, v29, v29
	v_mul_f32_e32 v25, v25, v25
	v_mul_f32_e32 v21, v21, v21
	v_fmac_f32_e32 v33, v32, v32
	v_mul_f32_e32 v32, v35, v35
	v_fmac_f32_e32 v29, v28, v28
	v_mul_f32_e32 v28, v31, v31
	v_fmac_f32_e32 v25, v24, v24
	v_mul_f32_e32 v24, v27, v27
	v_fmac_f32_e32 v21, v20, v20
	v_mul_f32_e32 v20, v23, v23
	v_fmac_f32_e32 v32, v34, v34
	v_fmac_f32_e32 v28, v30, v30
	v_fmac_f32_e32 v24, v26, v26
	v_fmac_f32_e32 v20, v22, v22
	v_add_f32_e32 v32, v33, v32
	v_add_f32_e32 v28, v29, v28
	v_add_f32_e32 v24, v25, v24
	v_add_f32_e32 v20, v21, v20
	v_add_f32_e32 v28, v32, v28
	v_add_f32_e32 v20, v24, v20
	v_add_f32_e32 v20, v28, v20
	v_mov_b32_e32 v21, v20
	s_nop 1
	v_permlane16_swap_b32 v21, v20
	s_waitcnt lgkmcnt(0)
	v_add_f32_e32 v20, v20, v21
	v_mov_b32_e32 v21, v20
	s_nop 1
	v_permlane32_swap_b32 v21, v20
	s_and_saveexec_b64 s[14:15], s[16:17]
	s_cbranch_execz .LBB0_2228
	s_waitcnt lgkmcnt(0)
	v_add_f32_e32 v20, v20, v21
	s_waitcnt vmcnt(0)
	v_add_f32_e32 v20, v145, v20
	v_fmamk_f32 v20, v20, 0x3c2aaaab, v231
	v_mul_f32_e32 v21, 0x4b800000, v20
	v_cmp_gt_f32_e32 vcc, s11, v20
	s_nop 1
	v_cndmask_b32_e32 v20, v20, v21, vcc
	v_rsq_f32_e32 v22, v20
	v_mad_u64_u32 v[20:21], s[20:21], v143, 48, s[0:1]
	v_mul_f32_e32 v23, 0x45800000, v22
	v_cndmask_b32_e32 v24, v22, v23, vcc
	v_mov_b32_e32 v22, v21
	v_mad_u64_u32 v[22:23], s[20:21], v142, 48, v[22:23]
	v_add_co_u32_e32 v20, vcc, 0x1000, v20
	s_nop 1
	v_addc_co_u32_e32 v21, vcc, 0, v22, vcc
	global_store_dword v[20:21], v24, off offset:3584
.LBB0_2228:
	s_or_b64 exec, exec, s[14:15]
	v_mul_f32_e32 v17, v17, v17
	v_mul_f32_e32 v13, v13, v13
	v_mul_f32_e32 v9, v9, v9
	v_mul_f32_e32 v5, v5, v5
	v_fmac_f32_e32 v17, v16, v16
	v_mul_f32_e32 v16, v19, v19
	v_fmac_f32_e32 v13, v12, v12
	v_mul_f32_e32 v12, v15, v15
	v_fmac_f32_e32 v9, v8, v8
	v_mul_f32_e32 v8, v11, v11
	v_fmac_f32_e32 v5, v4, v4
	v_mul_f32_e32 v4, v7, v7
	v_fmac_f32_e32 v16, v18, v18
	v_fmac_f32_e32 v12, v14, v14
	v_fmac_f32_e32 v8, v10, v10
	v_fmac_f32_e32 v4, v6, v6
	v_add_f32_e32 v16, v17, v16
	v_add_f32_e32 v12, v13, v12
	v_add_f32_e32 v8, v9, v8
	v_add_f32_e32 v4, v5, v4
	v_add_f32_e32 v12, v16, v12
	v_add_f32_e32 v4, v8, v4
	v_add_f32_e32 v4, v12, v4
	v_mov_b32_e32 v5, v4
	s_nop 1
	v_permlane16_swap_b32 v5, v4
	s_waitcnt lgkmcnt(0)
	v_add_f32_e32 v4, v4, v5
	v_mov_b32_e32 v5, v4
	s_nop 1
	v_permlane32_swap_b32 v5, v4
	s_and_saveexec_b64 s[14:15], s[16:17]
	s_cbranch_execz .LBB0_2207
	s_waitcnt lgkmcnt(0)
	v_add_f32_e32 v4, v4, v5
	s_waitcnt vmcnt(0)
	v_add_f32_e32 v4, v144, v4
	v_fmamk_f32 v4, v4, 0x3c2aaaab, v231
	v_cmp_gt_f32_e32 vcc, s11, v4
	v_mul_f32_e32 v5, 0x4b800000, v4
	s_nop 0
	v_cndmask_b32_e32 v4, v4, v5, vcc
	v_rsq_f32_e32 v4, v4
	s_nop 0
	v_mul_f32_e32 v5, 0x45800000, v4
	v_cndmask_b32_e32 v8, v4, v5, vcc
	v_mad_u64_u32 v[4:5], s[0:1], v143, 48, s[0:1]
	v_mov_b32_e32 v6, v5
	v_mad_u64_u32 v[6:7], s[0:1], v142, 48, v[6:7]
	v_add_co_u32_e32 v4, vcc, 0x2000, v4
	s_nop 1
	v_addc_co_u32_e32 v5, vcc, 0, v6, vcc
	global_store_dword v[4:5], v8, off offset:256
	s_branch .LBB0_2207

.LBB0_2679:
	s_or_b64 exec, exec, s[0:1]
	v_add_u32_e32 v68, 0x80, v194
	s_waitcnt lgkmcnt(0)
	v_ashrrev_i32_e32 v69, 31, v68
	v_lshlrev_b64 v[70:71], 12, v[68:69]
	v_lshl_add_u64 v[72:73], v[210:211], 0, v[70:71]
	v_add_u32_e32 v122, 0x90, v194
	global_load_dwordx4 v[94:97], v[72:73], off
	global_load_dwordx4 v[98:101], v[72:73], off offset:16
	global_load_dwordx4 v[102:105], v[72:73], off offset:144
	global_load_dwordx4 v[106:109], v[72:73], off offset:128
	v_ashrrev_i32_e32 v123, 31, v122
	v_lshlrev_b64 v[72:73], 12, v[122:123]
	v_lshl_add_u64 v[74:75], v[210:211], 0, v[72:73]
	global_load_dwordx4 v[110:113], v[74:75], off
	global_load_dwordx4 v[114:117], v[74:75], off offset:16
	v_add_u32_e32 v90, 0xa0, v194
	v_add_u32_e32 v86, 0xb0, v194
	v_ashrrev_i32_e32 v91, 31, v90
	v_ashrrev_i32_e32 v87, 31, v86
	v_lshlrev_b64 v[92:93], 12, v[90:91]
	v_lshlrev_b64 v[88:89], 12, v[86:87]
	v_lshlrev_b64 v[68:69], 11, v[68:69]
	v_lshl_add_u64 v[76:77], v[210:211], 0, v[92:93]
	v_lshl_add_u64 v[146:147], v[210:211], 0, v[88:89]
	v_lshl_add_u64 v[148:149], s[20:21], 0, v[70:71]
	v_lshl_add_u64 v[150:151], s[24:25], 0, v[68:69]
	v_lshl_add_u64 v[152:153], s[20:21], 0, v[72:73]
	global_load_dwordx4 v[118:121], v[74:75], off offset:144
	global_load_dwordx4 v[126:129], v[74:75], off offset:128
	global_load_dwordx4 v[130:133], v[76:77], off offset:16
	global_load_dwordx4 v[134:137], v[76:77], off
	global_load_dwordx4 v[138:141], v[76:77], off offset:144
	global_load_dwordx4 v[142:145], v[76:77], off offset:128
	s_nop 0
	global_load_dwordx4 v[76:79], v[146:147], off offset:16
	global_load_dwordx4 v[80:83], v[146:147], off
	global_load_dwordx4 v[68:71], v[146:147], off offset:144
	global_load_dwordx4 v[72:75], v[146:147], off offset:128
	v_lshl_add_u64 v[146:147], v[148:149], 0, v[192:193]
	v_lshl_add_u64 v[148:149], v[150:151], 0, v[124:125]
	v_lshl_add_u64 v[150:151], v[152:153], 0, v[192:193]
	s_waitcnt vmcnt(14)
	v_pk_add_f32 v[62:63], v[62:63], v[100:101]
	v_pk_add_f32 v[66:67], v[66:67], v[96:97]
	v_pk_add_f32 v[64:65], v[64:65], v[94:95]
	v_pk_add_f32 v[60:61], v[60:61], v[98:99]
	s_waitcnt vmcnt(12)
	v_pk_add_f32 v[50:51], v[50:51], v[108:109]
	v_pk_add_f32 v[48:49], v[48:49], v[106:107]
	v_pk_add_f32 v[46:47], v[46:47], v[104:105]
	v_pk_add_f32 v[44:45], v[44:45], v[102:103]
	global_store_dwordx4 v[146:147], v[64:67], off
	global_store_dwordx4 v[146:147], v[60:63], off offset:16
	v_mul_f32_e32 v102, v65, v65
	v_mul_f32_e32 v103, v67, v67
	v_mul_f32_e32 v104, v61, v61
	v_mul_f32_e32 v105, v63, v63
	v_cvt_pk_bf16_f32 v94, v64, v65
	v_cvt_pk_bf16_f32 v95, v66, v67
	v_cvt_pk_bf16_f32 v96, v60, v61
	v_cvt_pk_bf16_f32 v97, v62, v63
	v_mul_f32_e32 v61, v49, v49
	v_mul_f32_e32 v63, v51, v51
	v_mul_f32_e32 v65, v45, v45
	v_mul_f32_e32 v67, v47, v47
	v_fmac_f32_e32 v102, v64, v64
	v_fmac_f32_e32 v103, v66, v66
	v_fmac_f32_e32 v104, v60, v60
	v_fmac_f32_e32 v105, v62, v62
	v_fmac_f32_e32 v61, v48, v48
	v_fmac_f32_e32 v63, v50, v50
	v_fmac_f32_e32 v65, v44, v44
	v_fmac_f32_e32 v67, v46, v46
	s_waitcnt vmcnt(13)
	v_pk_add_f32 v[58:59], v[58:59], v[112:113]
	v_pk_add_f32 v[56:57], v[56:57], v[110:111]
	s_waitcnt vmcnt(12)
	v_pk_add_f32 v[54:55], v[54:55], v[116:117]
	v_pk_add_f32 v[52:53], v[52:53], v[114:115]
	v_cvt_pk_bf16_f32 v100, v44, v45
	v_cvt_pk_bf16_f32 v101, v46, v47
	global_store_dwordx4 v[148:149], v[94:97], off
	global_store_dwordx4 v[146:147], v[48:51], off offset:128
	global_store_dwordx4 v[146:147], v[44:47], off offset:144
	v_cvt_pk_bf16_f32 v98, v48, v49
	v_mul_f32_e32 v106, v57, v57
	v_add_f32_e32 v44, v102, v103
	v_add_f32_e32 v45, v104, v105
	v_add_f32_e32 v46, v61, v63
	v_add_f32_e32 v47, v65, v67
	v_mul_f32_e32 v107, v59, v59
	v_add_f32_e32 v44, v44, v45
	v_add_f32_e32 v45, v46, v47
	v_mul_f32_e32 v47, v53, v53
	v_mul_f32_e32 v48, v55, v55
	v_fmac_f32_e32 v106, v56, v56
	v_fmac_f32_e32 v107, v58, v58
	v_fmac_f32_e32 v47, v52, v52
	v_fmac_f32_e32 v48, v54, v54
	v_add_f32_e32 v46, v106, v107
	v_add_f32_e32 v47, v47, v48
	v_add_f32_e32 v60, v46, v47
	v_lshlrev_b64 v[46:47], 11, v[122:123]
	v_lshl_add_u64 v[46:47], s[24:25], 0, v[46:47]
	v_cvt_pk_bf16_f32 v99, v50, v51
	v_lshl_add_u64 v[50:51], v[46:47], 0, v[124:125]
	v_cvt_pk_bf16_f32 v46, v56, v57
	v_cvt_pk_bf16_f32 v47, v58, v59
	v_cvt_pk_bf16_f32 v48, v52, v53
	v_cvt_pk_bf16_f32 v49, v54, v55
	s_waitcnt vmcnt(13)
	v_pk_add_f32 v[42:43], v[42:43], v[128:129]
	v_pk_add_f32 v[40:41], v[40:41], v[126:127]
	global_store_dwordx4 v[148:149], v[98:101], off offset:64
	global_store_dwordx4 v[150:151], v[56:59], off
	global_store_dwordx4 v[150:151], v[52:55], off offset:16
	global_store_dwordx4 v[50:51], v[46:49], off
	v_pk_add_f32 v[38:39], v[38:39], v[120:121]
	v_pk_add_f32 v[36:37], v[36:37], v[118:119]
	v_mul_f32_e32 v46, v41, v41
	v_mul_f32_e32 v47, v43, v43
	global_store_dwordx4 v[150:151], v[40:43], off offset:128
	global_store_dwordx4 v[150:151], v[36:39], off offset:144
	v_fmac_f32_e32 v46, v40, v40
	v_fmac_f32_e32 v47, v42, v42
	v_cvt_pk_bf16_f32 v40, v40, v41
	v_cvt_pk_bf16_f32 v41, v42, v43
	v_cvt_pk_bf16_f32 v42, v36, v37
	v_cvt_pk_bf16_f32 v43, v38, v39
	s_waitcnt vmcnt(17)
	v_pk_add_f32 v[34:35], v[34:35], v[136:137]
	v_pk_add_f32 v[32:33], v[32:33], v[134:135]
	global_store_dwordx4 v[50:51], v[40:43], off offset:64
	v_pk_add_f32 v[30:31], v[30:31], v[132:133]
	v_pk_add_f32 v[28:29], v[28:29], v[130:131]
	v_mul_f32_e32 v40, v33, v33
	v_mul_f32_e32 v41, v35, v35
	v_fmac_f32_e32 v40, v32, v32
	v_fmac_f32_e32 v41, v34, v34
	v_add_f32_e32 v40, v40, v41
	v_mul_f32_e32 v41, v29, v29
	v_mul_f32_e32 v42, v31, v31
	v_fmac_f32_e32 v41, v28, v28
	v_fmac_f32_e32 v42, v30, v30
	v_mul_f32_e32 v48, v39, v39
	v_add_f32_e32 v41, v41, v42
	v_fmac_f32_e32 v48, v38, v38
	v_lshl_add_u64 v[38:39], s[20:21], 0, v[92:93]
	v_add_f32_e32 v42, v40, v41
	v_lshlrev_b64 v[40:41], 11, v[90:91]
	v_lshl_add_u64 v[38:39], v[38:39], 0, v[192:193]
	v_lshl_add_u64 v[40:41], s[24:25], 0, v[40:41]
	s_waitcnt vmcnt(16)
	v_pk_add_f32 v[26:27], v[26:27], v[144:145]
	v_pk_add_f32 v[24:25], v[24:25], v[142:143]
	global_store_dwordx4 v[38:39], v[32:35], off
	global_store_dwordx4 v[38:39], v[28:31], off offset:16
	v_lshl_add_u64 v[40:41], v[40:41], 0, v[124:125]
	v_cvt_pk_bf16_f32 v32, v32, v33
	v_cvt_pk_bf16_f32 v33, v34, v35
	v_cvt_pk_bf16_f32 v34, v28, v29
	v_cvt_pk_bf16_f32 v35, v30, v31
	v_pk_add_f32 v[22:23], v[22:23], v[140:141]
	v_pk_add_f32 v[20:21], v[20:21], v[138:139]
	v_mul_f32_e32 v28, v25, v25
	v_mul_f32_e32 v29, v27, v27
	global_store_dwordx4 v[40:41], v[32:35], off
	global_store_dwordx4 v[38:39], v[24:27], off offset:128
	global_store_dwordx4 v[38:39], v[20:23], off offset:144
	v_fmac_f32_e32 v28, v24, v24
	v_fmac_f32_e32 v29, v26, v26
	v_cvt_pk_bf16_f32 v24, v24, v25
	v_cvt_pk_bf16_f32 v25, v26, v27
	v_cvt_pk_bf16_f32 v26, v20, v21
	v_cvt_pk_bf16_f32 v27, v22, v23
	s_waitcnt vmcnt(19)
	v_pk_add_f32 v[18:19], v[18:19], v[82:83]
	v_pk_add_f32 v[16:17], v[16:17], v[80:81]
	v_mul_f32_e32 v30, v23, v23
	global_store_dwordx4 v[40:41], v[24:27], off offset:64
	v_fmac_f32_e32 v30, v22, v22
	v_lshl_add_u64 v[22:23], s[20:21], 0, v[88:89]
	v_mul_f32_e32 v24, v17, v17
	v_mul_f32_e32 v25, v19, v19
	v_pk_add_f32 v[12:13], v[12:13], v[76:77]
	v_fmac_f32_e32 v24, v16, v16
	v_fmac_f32_e32 v25, v18, v18
	v_lshl_add_u64 v[22:23], v[22:23], 0, v[192:193]
	v_pk_add_f32 v[14:15], v[14:15], v[78:79]
	v_add_f32_e32 v24, v24, v25
	v_mul_f32_e32 v25, v13, v13
	s_waitcnt vmcnt(18)
	v_pk_add_f32 v[10:11], v[10:11], v[74:75]
	v_pk_add_f32 v[8:9], v[8:9], v[72:73]
	global_store_dwordx4 v[22:23], v[16:19], off
	global_store_dwordx4 v[22:23], v[12:15], off offset:16
	v_fmac_f32_e32 v25, v12, v12
	v_mul_f32_e32 v26, v15, v15
	v_cvt_pk_bf16_f32 v16, v16, v17
	v_cvt_pk_bf16_f32 v17, v18, v19
	v_cvt_pk_bf16_f32 v18, v12, v13
	v_pk_add_f32 v[12:13], v[4:5], v[68:69]
	v_mul_f32_e32 v4, v9, v9
	v_mul_f32_e32 v5, v11, v11
	v_fmac_f32_e32 v26, v14, v14
	v_cvt_pk_bf16_f32 v19, v14, v15
	v_pk_add_f32 v[14:15], v[6:7], v[70:71]
	v_fmac_f32_e32 v4, v8, v8
	v_fmac_f32_e32 v5, v10, v10
	v_add_f32_e32 v46, v46, v47
	v_mul_f32_e32 v47, v37, v37
	v_add_f32_e32 v28, v28, v29
	v_mul_f32_e32 v29, v21, v21
	v_add_f32_e32 v4, v4, v5
	v_mul_f32_e32 v5, v13, v13
	v_mul_f32_e32 v6, v15, v15
	v_fmac_f32_e32 v47, v36, v36
	v_fmac_f32_e32 v29, v20, v20
	v_fmac_f32_e32 v5, v12, v12
	v_fmac_f32_e32 v6, v14, v14
	v_add_f32_e32 v47, v47, v48
	v_add_f32_e32 v29, v29, v30
	v_add_f32_e32 v25, v25, v26
	v_add_f32_e32 v5, v5, v6
	v_add_f32_e32 v46, v46, v47
	v_add_f32_e32 v28, v28, v29
	v_add_f32_e32 v26, v24, v25
	v_add_f32_e32 v4, v4, v5
	v_add_f32_e32 v44, v44, v45
	v_add_f32_e32 v46, v60, v46
	v_add_f32_e32 v28, v42, v28
	v_add_f32_e32 v4, v26, v4
	ds_swizzle_b32 v45, v44 offset:swizzle(SWAP,16)
	ds_swizzle_b32 v47, v46 offset:swizzle(SWAP,16)
	ds_swizzle_b32 v29, v28 offset:swizzle(SWAP,16)
	v_mov_b32_e32 v5, v4
	s_nop 1
	v_permlane16_swap_b32 v5, v4
	v_lshlrev_b64 v[24:25], 11, v[86:87]
	s_waitcnt lgkmcnt(3)
	v_add_f32_e32 v44, v44, v45
	s_waitcnt lgkmcnt(2)
	v_add_f32_e32 v36, v46, v47
	s_waitcnt lgkmcnt(1)
	v_add_f32_e32 v20, v28, v29
	s_waitcnt lgkmcnt(0)
	v_add_f32_e32 v4, v4, v5
	ds_bpermute_b32 v45, v228, v44
	ds_bpermute_b32 v37, v228, v36
	ds_bpermute_b32 v21, v228, v20
	v_mov_b32_e32 v5, v4
	s_nop 1
	v_permlane32_swap_b32 v5, v4
	v_lshl_add_u64 v[24:25], s[24:25], 0, v[24:25]
	v_lshl_add_u64 v[24:25], v[24:25], 0, v[124:125]
	global_store_dwordx4 v[24:25], v[16:19], off
	global_store_dwordx4 v[22:23], v[8:11], off offset:128
	global_store_dwordx4 v[22:23], v[12:15], off offset:144
	v_cvt_pk_bf16_f32 v6, v8, v9
	v_cvt_pk_bf16_f32 v7, v10, v11
	v_cvt_pk_bf16_f32 v8, v12, v13
	v_cvt_pk_bf16_f32 v9, v14, v15
	global_store_dwordx4 v[24:25], v[6:9], off offset:64
	s_and_saveexec_b64 s[0:1], vcc
	s_cbranch_execz .LBB0_2681
	s_waitcnt lgkmcnt(3)
	v_add_f32_e32 v7, v44, v45
	s_waitcnt lgkmcnt(0)
	v_add_f32_e32 v4, v4, v5
	v_add_f32_e32 v5, v20, v21
	v_add_f32_e32 v6, v36, v37
	global_atomic_add_f32 v[84:85], v7, off offset:512
	global_atomic_add_f32 v[84:85], v6, off offset:576
	global_atomic_add_f32 v[84:85], v5, off offset:640
	global_atomic_add_f32 v[84:85], v4, off offset:704

.LBB0_3050:
	s_add_u32 s30, s22, s24
	s_addc_u32 s31, s23, s25
	s_add_u32 s40, s30, 0x100
	s_addc_u32 s41, s31, 0
	s_and_b64 s[28:29], s[26:27], exec
	s_cselect_b32 s43, s19, s41
	s_cselect_b32 s42, s18, s40
	s_add_u32 s24, s14, s24
	s_addc_u32 s25, s15, s25
	s_add_u32 s28, s24, 0x100
	s_addc_u32 s29, s25, 0
	s_add_u32 s24, s42, 0x80
	s_addc_u32 s25, s43, 0
	s_and_b64 s[26:27], s[26:27], exec
	s_cselect_b32 s45, s1, s29
	s_cselect_b32 s44, s9, s28
	s_add_u32 s46, s30, 0x12080
	s_addc_u32 s47, s31, 0
	s_add_i32 s95, s84, s57
	s_add_i32 m0, s63, 0xc000
	s_add_i32 s97, s63, 0xe000
	s_add_i32 s94, s95, 0x2000
	s_add_u32 s40, s44, 0x10000
	s_addc_u32 s41, s45, 0
	s_add_i32 s93, s85, s57
	s_add_i32 s92, s93, 0x2000
	v_add_u32_e32 v152, s84, v1
	s_add_u32 s30, s42, 0x12000
	ds_read_b128 v[140:143], v152
	ds_read_b128 v[144:147], v152 offset:1024
	ds_read_b128 v[148:151], v152 offset:2048
	ds_read_b128 v[152:155], v152 offset:3072
	s_addc_u32 s31, s43, 0
	s_add_u32 s28, s44, 0x80
	s_addc_u32 s29, s45, 0
	s_add_i32 s91, s88, s57
	s_add_i32 s90, s91, 0x2000
	s_add_u32 s26, s44, 0x10080
	s_addc_u32 s27, s45, 0
	s_add_i32 s87, s89, s57
	s_add_i32 s86, s87, 0x2000
	ds_read_b128 v[156:159], v3
	ds_read_b128 v[160:163], v3 offset:1024
	ds_read_b128 v[164:167], v3 offset:2048
	ds_read_b128 v[168:171], v3 offset:3072
	ds_read_b128 v[172:175], v3 offset:4096
	ds_read_b128 v[176:179], v3 offset:5120
	ds_read_b128 v[180:183], v3 offset:6144
	ds_read_b128 v[184:187], v3 offset:7168
	s_nop 0
	global_load_lds_dwordx4 v132, s[46:47]
	s_mov_b32 m0, s97
	s_nop 0
	global_load_lds_dwordx4 v136, s[46:47]
	s_waitcnt lgkmcnt(8)
	s_barrier
	s_waitcnt lgkmcnt(0)
	s_setprio 1
	s_waitcnt lgkmcnt(0)
	v_mfma_f32_16x16x32_bf16 v[128:131], v[140:143], v[156:159], v[128:131]
	v_mfma_f32_16x16x32_bf16 v[124:127], v[148:151], v[156:159], v[124:127]
	v_mfma_f32_16x16x32_bf16 v[112:115], v[140:143], v[164:167], v[112:115]
	v_mfma_f32_16x16x32_bf16 v[108:111], v[148:151], v[164:167], v[108:111]
	v_mfma_f32_16x16x32_bf16 v[96:99], v[140:143], v[172:175], v[96:99]
	v_mfma_f32_16x16x32_bf16 v[92:95], v[148:151], v[172:175], v[92:95]
	v_mfma_f32_16x16x32_bf16 v[80:83], v[140:143], v[180:183], v[80:83]
	v_mfma_f32_16x16x32_bf16 v[76:79], v[148:151], v[180:183], v[76:79]
	v_mfma_f32_16x16x32_bf16 v[128:131], v[144:147], v[160:163], v[128:131]
	v_mfma_f32_16x16x32_bf16 v[124:127], v[152:155], v[160:163], v[124:127]
	v_mfma_f32_16x16x32_bf16 v[112:115], v[144:147], v[168:171], v[112:115]
	v_mfma_f32_16x16x32_bf16 v[108:111], v[152:155], v[168:171], v[108:111]
	v_mfma_f32_16x16x32_bf16 v[96:99], v[144:147], v[176:179], v[96:99]
	v_mfma_f32_16x16x32_bf16 v[92:95], v[152:155], v[176:179], v[92:95]
	v_mfma_f32_16x16x32_bf16 v[80:83], v[144:147], v[184:187], v[80:83]
	v_mfma_f32_16x16x32_bf16 v[76:79], v[152:155], v[184:187], v[76:79]
	s_setprio 0
	s_barrier
	v_add_u32_e32 v196, s85, v1
	s_mov_b32 m0, s95
	ds_read_b128 v[188:191], v196
	ds_read_b128 v[192:195], v196 offset:1024
	ds_read_b128 v[210:213], v196 offset:2048
	ds_read_b128 v[214:217], v196 offset:3072
	s_nop 0
	global_load_lds_dwordx4 v134, s[44:45]
	s_mov_b32 m0, s94
	s_nop 0
	global_load_lds_dwordx4 v138, s[44:45]
	s_barrier
	s_waitcnt lgkmcnt(0)
	s_setprio 1
	s_waitcnt lgkmcnt(0)
	v_mfma_f32_16x16x32_bf16 v[120:123], v[188:191], v[156:159], v[120:123]
	v_mfma_f32_16x16x32_bf16 v[116:119], v[210:213], v[156:159], v[116:119]
	v_mfma_f32_16x16x32_bf16 v[104:107], v[188:191], v[164:167], v[104:107]
	v_mfma_f32_16x16x32_bf16 v[100:103], v[210:213], v[164:167], v[100:103]
	v_mfma_f32_16x16x32_bf16 v[88:91], v[188:191], v[172:175], v[88:91]
	v_mfma_f32_16x16x32_bf16 v[84:87], v[210:213], v[172:175], v[84:87]
	v_mfma_f32_16x16x32_bf16 v[72:75], v[188:191], v[180:183], v[72:75]
	v_mfma_f32_16x16x32_bf16 v[68:71], v[210:213], v[180:183], v[68:71]
	v_mfma_f32_16x16x32_bf16 v[120:123], v[192:195], v[160:163], v[120:123]
	v_mfma_f32_16x16x32_bf16 v[116:119], v[214:217], v[160:163], v[116:119]
	v_mfma_f32_16x16x32_bf16 v[104:107], v[192:195], v[168:171], v[104:107]
	v_mfma_f32_16x16x32_bf16 v[100:103], v[214:217], v[168:171], v[100:103]
	v_mfma_f32_16x16x32_bf16 v[88:91], v[192:195], v[176:179], v[88:91]
	v_mfma_f32_16x16x32_bf16 v[84:87], v[214:217], v[176:179], v[84:87]
	v_mfma_f32_16x16x32_bf16 v[72:75], v[192:195], v[184:187], v[72:75]
	v_mfma_f32_16x16x32_bf16 v[68:71], v[214:217], v[184:187], v[68:71]
	s_setprio 0
	s_mov_b32 m0, s63
	s_barrier
	ds_read_b128 v[156:159], v3 offset:16384
	ds_read_b128 v[160:163], v3 offset:17408
	ds_read_b128 v[164:167], v3 offset:18432
	ds_read_b128 v[168:171], v3 offset:19456
	ds_read_b128 v[172:175], v3 offset:20480
	ds_read_b128 v[176:179], v3 offset:21504
	ds_read_b128 v[180:183], v3 offset:22528
	ds_read_b128 v[184:187], v3 offset:23552
	s_nop 0
	global_load_lds_dwordx4 v132, s[42:43]
	s_mov_b32 m0, s64
	s_nop 0
	global_load_lds_dwordx4 v136, s[42:43]
	s_barrier
	s_waitcnt lgkmcnt(0)
	s_setprio 1
	s_waitcnt lgkmcnt(0)
	v_mfma_f32_16x16x32_bf16 v[64:67], v[140:143], v[156:159], v[64:67]
	v_mfma_f32_16x16x32_bf16 v[60:63], v[148:151], v[156:159], v[60:63]
	v_mfma_f32_16x16x32_bf16 v[48:51], v[140:143], v[164:167], v[48:51]
	v_mfma_f32_16x16x32_bf16 v[44:47], v[148:151], v[164:167], v[44:47]
	v_mfma_f32_16x16x32_bf16 v[32:35], v[140:143], v[172:175], v[32:35]
	v_mfma_f32_16x16x32_bf16 v[28:31], v[148:151], v[172:175], v[28:31]
	v_mfma_f32_16x16x32_bf16 v[16:19], v[140:143], v[180:183], v[16:19]
	v_mfma_f32_16x16x32_bf16 v[12:15], v[148:151], v[180:183], v[12:15]
	v_mfma_f32_16x16x32_bf16 v[64:67], v[144:147], v[160:163], v[64:67]
	v_mfma_f32_16x16x32_bf16 v[60:63], v[152:155], v[160:163], v[60:63]
	v_mfma_f32_16x16x32_bf16 v[48:51], v[144:147], v[168:171], v[48:51]
	v_mfma_f32_16x16x32_bf16 v[44:47], v[152:155], v[168:171], v[44:47]
	v_mfma_f32_16x16x32_bf16 v[32:35], v[144:147], v[176:179], v[32:35]
	v_mfma_f32_16x16x32_bf16 v[28:31], v[152:155], v[176:179], v[28:31]
	v_mfma_f32_16x16x32_bf16 v[16:19], v[144:147], v[184:187], v[16:19]
	v_mfma_f32_16x16x32_bf16 v[12:15], v[152:155], v[184:187], v[12:15]
	s_setprio 0
	s_barrier
	s_mov_b32 m0, s93
	s_nop 0
	global_load_lds_dwordx4 v134, s[40:41]
	s_mov_b32 m0, s92
	s_nop 0
	global_load_lds_dwordx4 v138, s[40:41]
	s_waitcnt vmcnt(6)
	s_barrier
	s_setprio 1
	v_mfma_f32_16x16x32_bf16 v[56:59], v[188:191], v[156:159], v[56:59]
	v_mfma_f32_16x16x32_bf16 v[52:55], v[210:213], v[156:159], v[52:55]
	v_mfma_f32_16x16x32_bf16 v[40:43], v[188:191], v[164:167], v[40:43]
	v_mfma_f32_16x16x32_bf16 v[36:39], v[210:213], v[164:167], v[36:39]
	v_mfma_f32_16x16x32_bf16 v[24:27], v[188:191], v[172:175], v[24:27]
	v_mfma_f32_16x16x32_bf16 v[20:23], v[210:213], v[172:175], v[20:23]
	v_mfma_f32_16x16x32_bf16 v[8:11], v[188:191], v[180:183], v[8:11]
	v_mfma_f32_16x16x32_bf16 v[4:7], v[210:213], v[180:183], v[4:7]
	v_mfma_f32_16x16x32_bf16 v[56:59], v[192:195], v[160:163], v[56:59]
	v_mfma_f32_16x16x32_bf16 v[52:55], v[214:217], v[160:163], v[52:55]
	v_mfma_f32_16x16x32_bf16 v[40:43], v[192:195], v[168:171], v[40:43]
	v_mfma_f32_16x16x32_bf16 v[36:39], v[214:217], v[168:171], v[36:39]
	v_mfma_f32_16x16x32_bf16 v[24:27], v[192:195], v[176:179], v[24:27]
	v_mfma_f32_16x16x32_bf16 v[20:23], v[214:217], v[176:179], v[20:23]
	v_mfma_f32_16x16x32_bf16 v[8:11], v[192:195], v[184:187], v[8:11]
	v_mfma_f32_16x16x32_bf16 v[4:7], v[214:217], v[184:187], v[4:7]
	s_setprio 0
	v_add_u32_e32 v152, s88, v1
	s_barrier
	ds_read_b128 v[140:143], v152
	ds_read_b128 v[144:147], v152 offset:1024
	ds_read_b128 v[148:151], v152 offset:2048
	ds_read_b128 v[152:155], v152 offset:3072
	s_mov_b32 m0, s65
	ds_read_b128 v[156:159], v3 offset:32768
	ds_read_b128 v[160:163], v3 offset:33792
	ds_read_b128 v[164:167], v3 offset:34816
	ds_read_b128 v[168:171], v3 offset:35840
	ds_read_b128 v[172:175], v3 offset:36864
	ds_read_b128 v[176:179], v3 offset:37888
	ds_read_b128 v[180:183], v3 offset:38912
	ds_read_b128 v[184:187], v3 offset:39936
	s_nop 0
	global_load_lds_dwordx4 v132, s[30:31]
	s_mov_b32 m0, s67
	s_nop 0
	global_load_lds_dwordx4 v136, s[30:31]
	s_waitcnt lgkmcnt(8)
	s_barrier
	s_waitcnt lgkmcnt(0)
	s_setprio 1
	s_waitcnt lgkmcnt(0)
	v_mfma_f32_16x16x32_bf16 v[128:131], v[140:143], v[156:159], v[128:131]
	v_mfma_f32_16x16x32_bf16 v[124:127], v[148:151], v[156:159], v[124:127]
	v_mfma_f32_16x16x32_bf16 v[112:115], v[140:143], v[164:167], v[112:115]
	v_mfma_f32_16x16x32_bf16 v[108:111], v[148:151], v[164:167], v[108:111]
	v_mfma_f32_16x16x32_bf16 v[96:99], v[140:143], v[172:175], v[96:99]
	v_mfma_f32_16x16x32_bf16 v[92:95], v[148:151], v[172:175], v[92:95]
	v_mfma_f32_16x16x32_bf16 v[80:83], v[140:143], v[180:183], v[80:83]
	v_mfma_f32_16x16x32_bf16 v[76:79], v[148:151], v[180:183], v[76:79]
	v_mfma_f32_16x16x32_bf16 v[128:131], v[144:147], v[160:163], v[128:131]
	v_mfma_f32_16x16x32_bf16 v[124:127], v[152:155], v[160:163], v[124:127]
	v_mfma_f32_16x16x32_bf16 v[112:115], v[144:147], v[168:171], v[112:115]
	v_mfma_f32_16x16x32_bf16 v[108:111], v[152:155], v[168:171], v[108:111]
	v_mfma_f32_16x16x32_bf16 v[96:99], v[144:147], v[176:179], v[96:99]
	v_mfma_f32_16x16x32_bf16 v[92:95], v[152:155], v[176:179], v[92:95]
	v_mfma_f32_16x16x32_bf16 v[80:83], v[144:147], v[184:187], v[80:83]
	v_mfma_f32_16x16x32_bf16 v[76:79], v[152:155], v[184:187], v[76:79]
	s_setprio 0
	s_barrier
	v_add_u32_e32 v196, s89, v1
	s_mov_b32 m0, s91
	ds_read_b128 v[188:191], v196
	ds_read_b128 v[192:195], v196 offset:1024
	ds_read_b128 v[210:213], v196 offset:2048
	ds_read_b128 v[214:217], v196 offset:3072
	s_nop 0
	global_load_lds_dwordx4 v134, s[28:29]
	s_mov_b32 m0, s90
	s_nop 0
	global_load_lds_dwordx4 v138, s[28:29]
	s_barrier
	s_waitcnt lgkmcnt(0)
	s_setprio 1
	s_waitcnt lgkmcnt(0)
	v_mfma_f32_16x16x32_bf16 v[120:123], v[188:191], v[156:159], v[120:123]
	v_mfma_f32_16x16x32_bf16 v[116:119], v[210:213], v[156:159], v[116:119]
	v_mfma_f32_16x16x32_bf16 v[104:107], v[188:191], v[164:167], v[104:107]
	v_mfma_f32_16x16x32_bf16 v[100:103], v[210:213], v[164:167], v[100:103]
	v_mfma_f32_16x16x32_bf16 v[88:91], v[188:191], v[172:175], v[88:91]
	v_mfma_f32_16x16x32_bf16 v[84:87], v[210:213], v[172:175], v[84:87]
	v_mfma_f32_16x16x32_bf16 v[72:75], v[188:191], v[180:183], v[72:75]
	v_mfma_f32_16x16x32_bf16 v[68:71], v[210:213], v[180:183], v[68:71]
	v_mfma_f32_16x16x32_bf16 v[120:123], v[192:195], v[160:163], v[120:123]
	v_mfma_f32_16x16x32_bf16 v[116:119], v[214:217], v[160:163], v[116:119]
	v_mfma_f32_16x16x32_bf16 v[104:107], v[192:195], v[168:171], v[104:107]
	v_mfma_f32_16x16x32_bf16 v[100:103], v[214:217], v[168:171], v[100:103]
	v_mfma_f32_16x16x32_bf16 v[88:91], v[192:195], v[176:179], v[88:91]
	v_mfma_f32_16x16x32_bf16 v[84:87], v[214:217], v[176:179], v[84:87]
	v_mfma_f32_16x16x32_bf16 v[72:75], v[192:195], v[184:187], v[72:75]
	v_mfma_f32_16x16x32_bf16 v[68:71], v[214:217], v[184:187], v[68:71]
	s_setprio 0
	s_mov_b32 m0, s75
	s_barrier
	ds_read_b128 v[156:159], v3 offset:49152
	ds_read_b128 v[160:163], v3 offset:50176
	ds_read_b128 v[164:167], v3 offset:51200
	ds_read_b128 v[168:171], v3 offset:52224
	ds_read_b128 v[172:175], v3 offset:53248
	ds_read_b128 v[176:179], v3 offset:54272
	ds_read_b128 v[180:183], v3 offset:55296
	ds_read_b128 v[184:187], v3 offset:56320
	s_nop 0
	global_load_lds_dwordx4 v132, s[24:25]
	s_mov_b32 m0, s78
	s_nop 0
	global_load_lds_dwordx4 v136, s[24:25]
	s_barrier
	s_waitcnt lgkmcnt(0)
	s_setprio 1
	s_waitcnt lgkmcnt(0)
	v_mfma_f32_16x16x32_bf16 v[64:67], v[140:143], v[156:159], v[64:67]
	v_mfma_f32_16x16x32_bf16 v[60:63], v[148:151], v[156:159], v[60:63]
	v_mfma_f32_16x16x32_bf16 v[48:51], v[140:143], v[164:167], v[48:51]
	v_mfma_f32_16x16x32_bf16 v[44:47], v[148:151], v[164:167], v[44:47]
	v_mfma_f32_16x16x32_bf16 v[32:35], v[140:143], v[172:175], v[32:35]
	v_mfma_f32_16x16x32_bf16 v[28:31], v[148:151], v[172:175], v[28:31]
	v_mfma_f32_16x16x32_bf16 v[16:19], v[140:143], v[180:183], v[16:19]
	v_mfma_f32_16x16x32_bf16 v[12:15], v[148:151], v[180:183], v[12:15]
	v_mfma_f32_16x16x32_bf16 v[64:67], v[144:147], v[160:163], v[64:67]
	v_mfma_f32_16x16x32_bf16 v[60:63], v[152:155], v[160:163], v[60:63]
	v_mfma_f32_16x16x32_bf16 v[48:51], v[144:147], v[168:171], v[48:51]
	v_mfma_f32_16x16x32_bf16 v[44:47], v[152:155], v[168:171], v[44:47]
	v_mfma_f32_16x16x32_bf16 v[32:35], v[144:147], v[176:179], v[32:35]
	v_mfma_f32_16x16x32_bf16 v[28:31], v[152:155], v[176:179], v[28:31]
	v_mfma_f32_16x16x32_bf16 v[16:19], v[144:147], v[184:187], v[16:19]
	v_mfma_f32_16x16x32_bf16 v[12:15], v[152:155], v[184:187], v[12:15]
	s_setprio 0
	s_barrier
	s_mov_b32 m0, s87
	s_nop 0
	global_load_lds_dwordx4 v134, s[26:27]
	s_mov_b32 m0, s86
	s_nop 0
	global_load_lds_dwordx4 v138, s[26:27]
	s_waitcnt vmcnt(6)
	s_barrier
	s_setprio 1
	v_mfma_f32_16x16x32_bf16 v[56:59], v[188:191], v[156:159], v[56:59]
	v_mfma_f32_16x16x32_bf16 v[52:55], v[210:213], v[156:159], v[52:55]
	v_mfma_f32_16x16x32_bf16 v[40:43], v[188:191], v[164:167], v[40:43]
	v_mfma_f32_16x16x32_bf16 v[36:39], v[210:213], v[164:167], v[36:39]
	v_mfma_f32_16x16x32_bf16 v[24:27], v[188:191], v[172:175], v[24:27]
	v_mfma_f32_16x16x32_bf16 v[20:23], v[210:213], v[172:175], v[20:23]
	v_mfma_f32_16x16x32_bf16 v[8:11], v[188:191], v[180:183], v[8:11]
	v_mfma_f32_16x16x32_bf16 v[4:7], v[210:213], v[180:183], v[4:7]
	v_mfma_f32_16x16x32_bf16 v[56:59], v[192:195], v[160:163], v[56:59]
	v_mfma_f32_16x16x32_bf16 v[52:55], v[214:217], v[160:163], v[52:55]
	v_mfma_f32_16x16x32_bf16 v[40:43], v[192:195], v[168:171], v[40:43]
	v_mfma_f32_16x16x32_bf16 v[36:39], v[214:217], v[168:171], v[36:39]
	v_mfma_f32_16x16x32_bf16 v[24:27], v[192:195], v[176:179], v[24:27]
	v_mfma_f32_16x16x32_bf16 v[20:23], v[214:217], v[176:179], v[20:23]
	v_mfma_f32_16x16x32_bf16 v[8:11], v[192:195], v[184:187], v[8:11]
	v_mfma_f32_16x16x32_bf16 v[4:7], v[214:217], v[184:187], v[4:7]
	s_setprio 0
	s_andn2_b64 vcc, exec, s[16:17]
	s_mov_b64 s[26:27], -1
	s_mov_b64 s[16:17], 0
	s_mov_b64 s[24:25], 0x100
	s_barrier
	s_cbranch_vccz .LBB0_3050
	v_mov_b32_e32 v141, v0
	s_ashr_i32 s1, s0, 31
	v_readfirstlane_b32 s9, v141
	s_bfe_u32 s24, s9, 0x20006
	s_ashr_i32 s9, s9, 2
	s_and_b32 s14, s9, 0xffffffc0
	s_ashr_i32 s15, s14, 31
	s_lshl_b64 s[16:17], s[0:1], 10
	s_add_u32 s9, s68, s16
	s_addc_u32 s23, s72, s17
	s_lshl_b64 s[16:17], s[14:15], 2
	v_and_b32_e32 v142, 15, v141
	s_add_u32 s22, s9, s16
	s_addc_u32 s23, s23, s17
	v_lshlrev_b32_e32 v140, 2, v142
	global_load_dword v150, v140, s[22:23] offset:64
	global_load_dword v149, v140, s[22:23] offset:128
	global_load_dword v148, v140, s[22:23] offset:192
	global_load_dword v147, v140, s[22:23] offset:512
	global_load_dword v146, v140, s[22:23] offset:576
	global_load_dword v145, v140, s[22:23] offset:640
	global_load_dword v144, v140, s[22:23] offset:704
	v_mul_f32_e32 v129, v129, v129
	v_mul_f32_e32 v125, v125, v125
	v_mul_f32_e32 v121, v121, v121
	v_mul_f32_e32 v117, v117, v117
	v_fmac_f32_e32 v129, v128, v128
	v_mul_f32_e32 v128, v131, v131
	v_fmac_f32_e32 v125, v124, v124
	v_mul_f32_e32 v124, v127, v127
	v_fmac_f32_e32 v121, v120, v120
	v_mul_f32_e32 v120, v123, v123
	v_fmac_f32_e32 v117, v116, v116
	v_mul_f32_e32 v116, v119, v119
	v_fmac_f32_e32 v128, v130, v130
	v_fmac_f32_e32 v124, v126, v126
	v_fmac_f32_e32 v120, v122, v122
	v_fmac_f32_e32 v116, v118, v118
	v_add_f32_e32 v128, v129, v128
	v_add_f32_e32 v124, v125, v124
	v_add_f32_e32 v120, v121, v120
	v_add_f32_e32 v116, v117, v116
	v_add_f32_e32 v124, v128, v124
	v_add_f32_e32 v116, v120, v116
	v_add_f32_e32 v117, v124, v116
	v_mov_b32_e32 v118, v117
	s_nop 1
	v_permlane16_swap_b32 v118, v117
	v_and_b32_e32 v152, 64, v236
	v_xor_b32_e32 v151, 32, v236
	v_add_u32_e32 v152, 64, v152
	v_cmp_lt_i32_e32 vcc, v151, v152
	s_lshl_b32 s9, s83, 2
	s_or_b32 s24, s24, s9
	v_cndmask_b32_e32 v116, v236, v151, vcc
	s_lshl_b64 s[0:1], s[0:1], 8
	v_lshlrev_b32_e32 v116, 2, v116
	s_waitcnt lgkmcnt(0)
	v_add_f32_e32 v117, v117, v118
	s_add_u32 s0, s0, s14
	v_mov_b32_e32 v118, v117
	s_nop 1
	v_permlane32_swap_b32 v118, v117
	s_addc_u32 s1, s1, s15
	s_ashr_i32 s25, s24, 31
	v_or_b32_e32 v143, s0, v142
	v_mov_b32_e32 v142, s1
	s_lshl_b64 s[0:1], s[24:25], 2
	v_and_b32_e32 v119, 48, v141
	s_add_u32 s0, s73, s0
	v_cmp_eq_u32_e64 s[16:17], 0, v119
	s_addc_u32 s1, s74, s1
	s_and_saveexec_b64 s[14:15], s[16:17]
	s_cbranch_execz .LBB0_3053
	v_mov_b32_e32 v141, v2
	v_lshl_add_u64 v[120:121], s[22:23], 0, v[140:141]
	global_load_dword v119, v[120:121], off
	s_waitcnt lgkmcnt(0)
	v_add_f32_e32 v117, v117, v118
	s_waitcnt vmcnt(0)
	v_add_f32_e32 v117, v117, v119
	v_fmamk_f32 v117, v117, 0x3c2aaaab, v231
	v_cmp_gt_f32_e32 vcc, s11, v117
	v_mul_f32_e32 v118, 0x4b800000, v117
	s_nop 0
	v_cndmask_b32_e32 v117, v117, v118, vcc
	v_rsq_f32_e32 v117, v117
	s_nop 0
	v_mul_f32_e32 v118, 0x45800000, v117
	v_cndmask_b32_e32 v117, v117, v118, vcc
	v_mad_u64_u32 v[118:119], s[22:23], v143, 48, s[0:1]
	v_mov_b32_e32 v120, v119
	v_mad_u64_u32 v[120:121], s[22:23], v142, 48, v[120:121]
	v_mov_b32_e32 v119, v120
	global_store_dword v[118:119], v117, off
.LBB0_3053:
	s_or_b64 exec, exec, s[14:15]
	v_mul_f32_e32 v113, v113, v113
	v_mul_f32_e32 v109, v109, v109
	v_mul_f32_e32 v105, v105, v105
	v_mul_f32_e32 v101, v101, v101
	v_fmac_f32_e32 v113, v112, v112
	v_mul_f32_e32 v112, v115, v115
	v_fmac_f32_e32 v109, v108, v108
	v_mul_f32_e32 v108, v111, v111
	v_fmac_f32_e32 v105, v104, v104
	v_mul_f32_e32 v104, v107, v107
	v_fmac_f32_e32 v101, v100, v100
	v_mul_f32_e32 v100, v103, v103
	v_fmac_f32_e32 v112, v114, v114
	v_fmac_f32_e32 v108, v110, v110
	v_fmac_f32_e32 v104, v106, v106
	v_fmac_f32_e32 v100, v102, v102
	v_add_f32_e32 v112, v113, v112
	v_add_f32_e32 v108, v109, v108
	v_add_f32_e32 v104, v105, v104
	v_add_f32_e32 v100, v101, v100
	v_add_f32_e32 v108, v112, v108
	v_add_f32_e32 v100, v104, v100
	v_add_f32_e32 v100, v108, v100
	v_mov_b32_e32 v101, v100
	s_nop 1
	v_permlane16_swap_b32 v101, v100
	s_waitcnt lgkmcnt(0)
	v_add_f32_e32 v100, v100, v101
	v_mov_b32_e32 v101, v100
	s_nop 1
	v_permlane32_swap_b32 v101, v100
	s_and_saveexec_b64 s[14:15], s[16:17]
	s_cbranch_execz .LBB0_3055
	s_waitcnt lgkmcnt(0)
	v_add_f32_e32 v100, v100, v101
	s_waitcnt vmcnt(0)
	v_add_f32_e32 v100, v150, v100
	v_fmamk_f32 v100, v100, 0x3c2aaaab, v231
	v_cmp_gt_f32_e32 vcc, s11, v100
	v_mul_f32_e32 v101, 0x4b800000, v100
	s_nop 0
	v_cndmask_b32_e32 v100, v100, v101, vcc
	v_rsq_f32_e32 v100, v100
	s_nop 0
	v_mul_f32_e32 v101, 0x45800000, v100
	v_cndmask_b32_e32 v104, v100, v101, vcc
	v_mad_u64_u32 v[100:101], s[22:23], v143, 48, s[0:1]
	v_mov_b32_e32 v102, v101
	v_mad_u64_u32 v[102:103], s[22:23], v142, 48, v[102:103]
	v_mov_b32_e32 v101, v102
	global_store_dword v[100:101], v104, off offset:768
.LBB0_3055:
	s_or_b64 exec, exec, s[14:15]
	v_mul_f32_e32 v97, v97, v97
	v_mul_f32_e32 v93, v93, v93
	v_mul_f32_e32 v89, v89, v89
	v_mul_f32_e32 v85, v85, v85
	v_fmac_f32_e32 v97, v96, v96
	v_mul_f32_e32 v96, v99, v99
	v_fmac_f32_e32 v93, v92, v92
	v_mul_f32_e32 v92, v95, v95
	v_fmac_f32_e32 v89, v88, v88
	v_mul_f32_e32 v88, v91, v91
	v_fmac_f32_e32 v85, v84, v84
	v_mul_f32_e32 v84, v87, v87
	v_fmac_f32_e32 v96, v98, v98
	v_fmac_f32_e32 v92, v94, v94
	v_fmac_f32_e32 v88, v90, v90
	v_fmac_f32_e32 v84, v86, v86
	v_add_f32_e32 v96, v97, v96
	v_add_f32_e32 v92, v93, v92
	v_add_f32_e32 v88, v89, v88
	v_add_f32_e32 v84, v85, v84
	v_add_f32_e32 v92, v96, v92
	v_add_f32_e32 v84, v88, v84
	v_add_f32_e32 v84, v92, v84
	v_mov_b32_e32 v85, v84
	s_nop 1
	v_permlane16_swap_b32 v85, v84
	s_waitcnt lgkmcnt(0)
	v_add_f32_e32 v84, v84, v85
	v_mov_b32_e32 v85, v84
	s_nop 1
	v_permlane32_swap_b32 v85, v84
	s_and_saveexec_b64 s[14:15], s[16:17]
	s_cbranch_execz .LBB0_3057
	s_waitcnt lgkmcnt(0)
	v_add_f32_e32 v84, v84, v85
	s_waitcnt vmcnt(0)
	v_add_f32_e32 v84, v149, v84
	v_fmamk_f32 v84, v84, 0x3c2aaaab, v231
	v_cmp_gt_f32_e32 vcc, s11, v84
	v_mul_f32_e32 v85, 0x4b800000, v84
	s_nop 0
	v_cndmask_b32_e32 v84, v84, v85, vcc
	v_rsq_f32_e32 v84, v84
	s_nop 0
	v_mul_f32_e32 v85, 0x45800000, v84
	v_cndmask_b32_e32 v88, v84, v85, vcc
	v_mad_u64_u32 v[84:85], s[22:23], v143, 48, s[0:1]
	v_mov_b32_e32 v86, v85
	v_mad_u64_u32 v[86:87], s[22:23], v142, 48, v[86:87]
	v_mov_b32_e32 v85, v86
	global_store_dword v[84:85], v88, off offset:1536
.LBB0_3057:
	s_or_b64 exec, exec, s[14:15]
	v_mul_f32_e32 v81, v81, v81
	v_mul_f32_e32 v77, v77, v77
	v_mul_f32_e32 v73, v73, v73
	v_mul_f32_e32 v69, v69, v69
	v_fmac_f32_e32 v81, v80, v80
	v_mul_f32_e32 v80, v83, v83
	v_fmac_f32_e32 v77, v76, v76
	v_mul_f32_e32 v76, v79, v79
	v_fmac_f32_e32 v73, v72, v72
	v_mul_f32_e32 v72, v75, v75
	v_fmac_f32_e32 v69, v68, v68
	v_mul_f32_e32 v68, v71, v71
	v_fmac_f32_e32 v80, v82, v82
	v_fmac_f32_e32 v76, v78, v78
	v_fmac_f32_e32 v72, v74, v74
	v_fmac_f32_e32 v68, v70, v70
	v_add_f32_e32 v80, v81, v80
	v_add_f32_e32 v76, v77, v76
	v_add_f32_e32 v72, v73, v72
	v_add_f32_e32 v68, v69, v68
	v_add_f32_e32 v76, v80, v76
	v_add_f32_e32 v68, v72, v68
	v_add_f32_e32 v68, v76, v68
	v_mov_b32_e32 v69, v68
	s_nop 1
	v_permlane16_swap_b32 v69, v68
	s_waitcnt lgkmcnt(0)
	v_add_f32_e32 v68, v68, v69
	v_mov_b32_e32 v69, v68
	s_nop 1
	v_permlane32_swap_b32 v69, v68
	s_and_saveexec_b64 s[14:15], s[16:17]
	v_readlane_b32 s90, v253, 25
	s_movk_i32 s91, 0xc00
	s_cbranch_execz .LBB0_3059
	s_waitcnt lgkmcnt(0)
	v_add_f32_e32 v68, v68, v69
	s_waitcnt vmcnt(0)
	v_add_f32_e32 v68, v148, v68
	v_fmamk_f32 v68, v68, 0x3c2aaaab, v231
	v_cmp_gt_f32_e32 vcc, s11, v68
	v_mul_f32_e32 v69, 0x4b800000, v68
	s_nop 0
	v_cndmask_b32_e32 v68, v68, v69, vcc
	v_rsq_f32_e32 v68, v68
	s_nop 0
	v_mul_f32_e32 v69, 0x45800000, v68
	v_cndmask_b32_e32 v72, v68, v69, vcc
	v_mad_u64_u32 v[68:69], s[22:23], v143, 48, s[0:1]
	v_mov_b32_e32 v70, v69
	v_mad_u64_u32 v[70:71], s[22:23], v142, 48, v[70:71]
	v_mov_b32_e32 v69, v70
	global_store_dword v[68:69], v72, off offset:2304
.LBB0_3059:
	s_or_b64 exec, exec, s[14:15]
	v_mul_f32_e32 v65, v65, v65
	v_mul_f32_e32 v61, v61, v61
	v_mul_f32_e32 v57, v57, v57
	v_mul_f32_e32 v53, v53, v53
	v_fmac_f32_e32 v65, v64, v64
	v_mul_f32_e32 v64, v67, v67
	v_fmac_f32_e32 v61, v60, v60
	v_mul_f32_e32 v60, v63, v63
	v_fmac_f32_e32 v57, v56, v56
	v_mul_f32_e32 v56, v59, v59
	v_fmac_f32_e32 v53, v52, v52
	v_mul_f32_e32 v52, v55, v55
	v_fmac_f32_e32 v64, v66, v66
	v_fmac_f32_e32 v60, v62, v62
	v_fmac_f32_e32 v56, v58, v58
	v_fmac_f32_e32 v52, v54, v54
	v_add_f32_e32 v64, v65, v64
	v_add_f32_e32 v60, v61, v60
	v_add_f32_e32 v56, v57, v56
	v_add_f32_e32 v52, v53, v52
	v_add_f32_e32 v60, v64, v60
	v_add_f32_e32 v52, v56, v52
	v_add_f32_e32 v52, v60, v52
	v_mov_b32_e32 v53, v52
	s_nop 1
	v_permlane16_swap_b32 v53, v52
	s_waitcnt lgkmcnt(0)
	v_add_f32_e32 v52, v52, v53
	v_mov_b32_e32 v53, v52
	s_nop 1
	v_permlane32_swap_b32 v53, v52
	s_and_saveexec_b64 s[14:15], s[16:17]
	s_cbranch_execz .LBB0_3061
	s_waitcnt lgkmcnt(0)
	v_add_f32_e32 v52, v52, v53
	s_waitcnt vmcnt(0)
	v_add_f32_e32 v52, v147, v52
	v_fmamk_f32 v52, v52, 0x3c2aaaab, v231
	v_mul_f32_e32 v53, 0x4b800000, v52
	v_cmp_gt_f32_e32 vcc, s11, v52
	s_nop 1
	v_cndmask_b32_e32 v52, v52, v53, vcc
	v_rsq_f32_e32 v54, v52
	v_mad_u64_u32 v[52:53], s[22:23], v143, 48, s[0:1]
	v_mul_f32_e32 v55, 0x45800000, v54
	v_cndmask_b32_e32 v56, v54, v55, vcc
	v_mov_b32_e32 v54, v53
	v_mad_u64_u32 v[54:55], s[22:23], v142, 48, v[54:55]
	v_add_co_u32_e32 v52, vcc, 0x1000, v52
	s_nop 1
	v_addc_co_u32_e32 v53, vcc, 0, v54, vcc
	global_store_dword v[52:53], v56, off offset:2048
.LBB0_3061:
	s_or_b64 exec, exec, s[14:15]
	v_mul_f32_e32 v49, v49, v49
	v_mul_f32_e32 v45, v45, v45
	v_mul_f32_e32 v41, v41, v41
	v_mul_f32_e32 v37, v37, v37
	v_fmac_f32_e32 v49, v48, v48
	v_mul_f32_e32 v48, v51, v51
	v_fmac_f32_e32 v45, v44, v44
	v_mul_f32_e32 v44, v47, v47
	v_fmac_f32_e32 v41, v40, v40
	v_mul_f32_e32 v40, v43, v43
	v_fmac_f32_e32 v37, v36, v36
	v_mul_f32_e32 v36, v39, v39
	v_fmac_f32_e32 v48, v50, v50
	v_fmac_f32_e32 v44, v46, v46
	v_fmac_f32_e32 v40, v42, v42
	v_fmac_f32_e32 v36, v38, v38
	v_add_f32_e32 v48, v49, v48
	v_add_f32_e32 v44, v45, v44
	v_add_f32_e32 v40, v41, v40
	v_add_f32_e32 v36, v37, v36
	v_add_f32_e32 v44, v48, v44
	v_add_f32_e32 v36, v40, v36
	v_add_f32_e32 v36, v44, v36
	v_mov_b32_e32 v37, v36
	s_nop 1
	v_permlane16_swap_b32 v37, v36
	s_waitcnt lgkmcnt(0)
	v_add_f32_e32 v36, v36, v37
	v_mov_b32_e32 v37, v36
	s_nop 1
	v_permlane32_swap_b32 v37, v36
	s_and_saveexec_b64 s[14:15], s[16:17]
	s_cbranch_execz .LBB0_3063
	s_waitcnt lgkmcnt(0)
	v_add_f32_e32 v36, v36, v37
	s_waitcnt vmcnt(0)
	v_add_f32_e32 v36, v146, v36
	v_fmamk_f32 v36, v36, 0x3c2aaaab, v231
	v_mul_f32_e32 v37, 0x4b800000, v36
	v_cmp_gt_f32_e32 vcc, s11, v36
	s_nop 1
	v_cndmask_b32_e32 v36, v36, v37, vcc
	v_rsq_f32_e32 v38, v36
	v_mad_u64_u32 v[36:37], s[22:23], v143, 48, s[0:1]
	v_mul_f32_e32 v39, 0x45800000, v38
	v_cndmask_b32_e32 v40, v38, v39, vcc
	v_mov_b32_e32 v38, v37
	v_mad_u64_u32 v[38:39], s[22:23], v142, 48, v[38:39]
	v_add_co_u32_e32 v36, vcc, 0x1000, v36
	s_nop 1
	v_addc_co_u32_e32 v37, vcc, 0, v38, vcc
	global_store_dword v[36:37], v40, off offset:2816
.LBB0_3063:
	s_or_b64 exec, exec, s[14:15]
	v_mul_f32_e32 v33, v33, v33
	v_mul_f32_e32 v29, v29, v29
	v_mul_f32_e32 v25, v25, v25
	v_mul_f32_e32 v21, v21, v21
	v_fmac_f32_e32 v33, v32, v32
	v_mul_f32_e32 v32, v35, v35
	v_fmac_f32_e32 v29, v28, v28
	v_mul_f32_e32 v28, v31, v31
	v_fmac_f32_e32 v25, v24, v24
	v_mul_f32_e32 v24, v27, v27
	v_fmac_f32_e32 v21, v20, v20
	v_mul_f32_e32 v20, v23, v23
	v_fmac_f32_e32 v32, v34, v34
	v_fmac_f32_e32 v28, v30, v30
	v_fmac_f32_e32 v24, v26, v26
	v_fmac_f32_e32 v20, v22, v22
	v_add_f32_e32 v32, v33, v32
	v_add_f32_e32 v28, v29, v28
	v_add_f32_e32 v24, v25, v24
	v_add_f32_e32 v20, v21, v20
	v_add_f32_e32 v28, v32, v28
	v_add_f32_e32 v20, v24, v20
	v_add_f32_e32 v20, v28, v20
	v_mov_b32_e32 v21, v20
	s_nop 1
	v_permlane16_swap_b32 v21, v20
	s_waitcnt lgkmcnt(0)
	v_add_f32_e32 v20, v20, v21
	v_mov_b32_e32 v21, v20
	s_nop 1
	v_permlane32_swap_b32 v21, v20
	s_and_saveexec_b64 s[14:15], s[16:17]
	s_cbranch_execz .LBB0_3065
	s_waitcnt lgkmcnt(0)
	v_add_f32_e32 v20, v20, v21
	s_waitcnt vmcnt(0)
	v_add_f32_e32 v20, v145, v20
	v_fmamk_f32 v20, v20, 0x3c2aaaab, v231
	v_mul_f32_e32 v21, 0x4b800000, v20
	v_cmp_gt_f32_e32 vcc, s11, v20
	s_nop 1
	v_cndmask_b32_e32 v20, v20, v21, vcc
	v_rsq_f32_e32 v22, v20
	v_mad_u64_u32 v[20:21], s[22:23], v143, 48, s[0:1]
	v_mul_f32_e32 v23, 0x45800000, v22
	v_cndmask_b32_e32 v24, v22, v23, vcc
	v_mov_b32_e32 v22, v21
	v_mad_u64_u32 v[22:23], s[22:23], v142, 48, v[22:23]
	v_add_co_u32_e32 v20, vcc, 0x1000, v20
	s_nop 1
	v_addc_co_u32_e32 v21, vcc, 0, v22, vcc
	global_store_dword v[20:21], v24, off offset:3584

.LBB0_3218:
	v_mul_f32_e32 v81, v81, v81
	v_mul_f32_e32 v77, v77, v77
	v_mul_f32_e32 v73, v73, v73
	v_mul_f32_e32 v69, v69, v69
	v_fmac_f32_e32 v81, v80, v80
	v_mul_f32_e32 v80, v83, v83
	v_fmac_f32_e32 v77, v76, v76
	v_mul_f32_e32 v76, v79, v79
	v_fmac_f32_e32 v73, v72, v72
	v_mul_f32_e32 v72, v75, v75
	v_fmac_f32_e32 v69, v68, v68
	v_mul_f32_e32 v68, v71, v71
	v_fmac_f32_e32 v80, v82, v82
	v_fmac_f32_e32 v76, v78, v78
	v_fmac_f32_e32 v72, v74, v74
	v_fmac_f32_e32 v68, v70, v70
	v_add_f32_e32 v80, v81, v80
	v_add_f32_e32 v76, v77, v76
	v_add_f32_e32 v72, v73, v72
	v_add_f32_e32 v68, v69, v68
	v_add_f32_e32 v76, v80, v76
	v_add_f32_e32 v68, v72, v68
	v_add_f32_e32 v68, v76, v68
	v_mov_b32_e32 v69, v68
	s_nop 1
	v_permlane16_swap_b32 v69, v68
	v_cmp_eq_u32_e32 vcc, 0, v228
	s_and_b64 s[0:1], s[30:31], vcc
	v_lshl_add_u64 v[124:125], v[194:195], 2, s[24:25]
	s_waitcnt lgkmcnt(0)
	v_add_f32_e32 v68, v68, v69
	v_mov_b32_e32 v69, v68
	s_nop 1
	v_permlane32_swap_b32 v69, v68
	s_and_saveexec_b64 s[8:9], s[0:1]
	s_cbranch_execz .LBB0_3220
	v_add_f32_e32 v72, v120, v121
	v_add_f32_e32 v70, v88, v89
	v_add_f32_e32 v71, v104, v105
	s_waitcnt lgkmcnt(0)
	v_add_f32_e32 v68, v68, v69
	global_atomic_add_f32 v[124:125], v72, off
	global_atomic_add_f32 v[124:125], v71, off offset:64
	global_atomic_add_f32 v[124:125], v70, off offset:128
	global_atomic_add_f32 v[124:125], v68, off offset:192

.LBB0_3236:
	v_mul_f32_e32 v17, v17, v17
	v_mul_f32_e32 v13, v13, v13
	v_mul_f32_e32 v9, v9, v9
	v_mul_f32_e32 v5, v5, v5
	v_fmac_f32_e32 v17, v16, v16
	v_mul_f32_e32 v16, v19, v19
	v_fmac_f32_e32 v13, v12, v12
	v_mul_f32_e32 v12, v15, v15
	v_fmac_f32_e32 v9, v8, v8
	v_mul_f32_e32 v8, v11, v11
	v_fmac_f32_e32 v5, v4, v4
	v_mul_f32_e32 v4, v7, v7
	v_fmac_f32_e32 v16, v18, v18
	v_fmac_f32_e32 v12, v14, v14
	v_fmac_f32_e32 v8, v10, v10
	v_fmac_f32_e32 v4, v6, v6
	v_add_f32_e32 v16, v17, v16
	v_add_f32_e32 v12, v13, v12
	v_add_f32_e32 v8, v9, v8
	v_add_f32_e32 v4, v5, v4
	v_add_f32_e32 v12, v16, v12
	v_add_f32_e32 v4, v8, v4
	v_add_f32_e32 v4, v12, v4
	v_mov_b32_e32 v5, v4
	s_nop 1
	v_permlane16_swap_b32 v5, v4
	s_waitcnt lgkmcnt(0)
	v_add_f32_e32 v4, v4, v5
	v_mov_b32_e32 v5, v4
	s_nop 1
	v_permlane32_swap_b32 v5, v4
	s_and_saveexec_b64 s[8:9], s[0:1]
	s_cbranch_execz .LBB0_3238
	v_add_f32_e32 v8, v56, v57
	v_add_f32_e32 v6, v24, v25
	v_add_f32_e32 v7, v40, v41
	s_waitcnt lgkmcnt(0)
	v_add_f32_e32 v4, v4, v5
	global_atomic_add_f32 v[124:125], v8, off offset:512
	global_atomic_add_f32 v[124:125], v7, off offset:576
	global_atomic_add_f32 v[124:125], v6, off offset:640
	global_atomic_add_f32 v[124:125], v4, off offset:704
